# asymmetric DMA burst split: only the last LDS-DMA load of each SP2 load segment moves to the next load segment (5+3 instead of 4+4), SP2 wait vmcnt(7)
# baseline (speedup 1.0000x reference)
; #define PG8_STAGE(bufoff, gbase, voff) do { _Pragma("unroll") for (int _i = 0; _i < 2; ++_i) \
;         __builtin_amdgcn_global_load_lds((const unsigned*)((const char*)(gbase) + (voff)[_i]), (PG8_LAS unsigned*)(lds + (bufoff) + ldsw + _i * 8192), 16, 0, 0); } while (0)
; #define PG8_LDA(dst, b, h) do { _Pragma("unroll") for (int m = 0; m < 4; ++m) _Pragma("unroll") for (int k = 0; k < 2; ++k) dst[m][k] = *(const PG8_LAS bf16x8*)(lds + PG8_SA(b, h) + aoff + m * 2048 + k * 1024); } while (0)
; #define PG8_LDB(dst, b, h) do { _Pragma("unroll") for (int n = 0; n < 2; ++n) _Pragma("unroll") for (int k = 0; k < 2; ++k) dst[n][k] = *(const PG8_LAS bf16x8*)(lds + PG8_SB(b, h) + boff + n * 2048 + k * 1024); } while (0)
; #define PG8_MMA(ai, bj, At, Bt) do { __builtin_amdgcn_s_setprio(1); _Pragma("unroll") for (int m = 0; m < 4; ++m) _Pragma("unroll") for (int n = 0; n < 2; ++n) _Pragma("unroll") for (int k = 0; k < 2; ++k) \
;         acc[ai][bj][m][n] = __builtin_amdgcn_mfma_f32_16x16x32_bf16(Bt[n][k], At[m][k], acc[ai][bj][m][n], 0, 0, 0); __builtin_amdgcn_s_setprio(0); } while (0)
; #define PG8_WAIT_V(n) asm volatile("s_waitcnt vmcnt(" #n ")" ::: "memory")
; #define PG8_BAR __builtin_amdgcn_s_barrier()
; template <class Epi, class Sched, bool ALIGN_EPI = false, bool SP2 = false>
; __device__ __forceinline__ void gemm_phase(PG8_LAS unsigned char* lds, const Gemm g, const Sched& S, const Epi& E) {
;     ...
;         for (int t = 0; t < nt; t += 2) {
;             const bool last = (t == nt - 2);
;             const char* a1 = cA + (size_t)(t + 1) * kstep;
;             const char* a2 = last ? nA : cA + (size_t)(t + 2) * kstep; const char* b2 = last ? nB : cB + (size_t)(t + 2) * kstep;
;             const char* a3 = a2 + kstep; const char* b3 = b2 + kstep;
;             if (last && has_next) S.a_ready(nxt);
;             if constexpr (SP2) {
;             PG8_LDB(B0, 0, 0); PG8_LDB(B1, 0, 1); PG8_SCHED; PG8_LDA(At, 0, 0); PG8_STAGE(PG8_SA(1, 1), a1 + hstepA, voffA);
;             PG8_WAIT_V(8); PG8_WAIT_L(0); PG8_BAR; PG8_MMA(0, 0, At, B0); PG8_MMA(0, 1, At, B1); PG8_BAR; PG8_SCHED;
;             PG8_LDA(At, 0, 1); PG8_STAGE(PG8_SB(0, 0), b2, voffB); PG8_STAGE(PG8_SB(0, 1), b2 + hstepB, voffB); PG8_STAGE(PG8_SA(0, 0), a2, voffA);
;             PG8_WAIT_V(8); PG8_WAIT_L(0); PG8_BAR; PG8_MMA(1, 0, At, B0); PG8_MMA(1, 1, At, B1); PG8_BAR; PG8_SCHED;
.LBB0_210:
	ds_read_b128 v[146:149], v155
	ds_read_b128 v[158:161], v155 offset:1024
	ds_read_b128 v[162:165], v155 offset:2048
	ds_read_b128 v[166:169], v155 offset:3072
	ds_read_b128 v[170:173], v156
	ds_read_b128 v[174:177], v156 offset:1024
	ds_read_b128 v[178:181], v156 offset:2048
	ds_read_b128 v[182:185], v156 offset:3072
	s_add_u32 s26, s24, 0xfff00080
	s_addc_u32 s27, s25, -1
	s_cmp_eq_u32 s53, 60
	s_cselect_b32 s29, s17, s27
	s_cselect_b32 s28, s49, s26
	s_cselect_b32 s27, s15, s52
	s_cselect_b32 s26, s50, s51
	v_lshl_add_u64 v[214:215], s[24:25], 0, v[138:139]
	s_add_i32 m0, s23, 0xc000
	ds_read_b128 v[186:189], v157
	ds_read_b128 v[190:193], v157 offset:1024
	ds_read_b128 v[194:197], v157 offset:2048
	ds_read_b128 v[198:201], v157 offset:3072
	ds_read_b128 v[202:205], v157 offset:4096
	ds_read_b128 v[206:209], v157 offset:5120
	ds_read_b128 v[210:213], v157 offset:6144
	ds_read_b128 v[218:221], v157 offset:7168
	global_load_lds_dwordx4 v[214:215], off
	v_lshl_add_u64 v[214:215], s[24:25], 0, v[140:141]
	s_add_i32 m0, s23, 0xe000
	s_nop 0
	global_load_lds_dwordx4 v[214:215], off
	s_waitcnt vmcnt(8)
	s_waitcnt lgkmcnt(0)
	s_barrier
	s_setprio 1
	s_waitcnt lgkmcnt(0)
	v_mfma_f32_16x16x32_bf16 v[126:129], v[146:149], v[186:189], v[126:129]
	v_mfma_f32_16x16x32_bf16 v[122:125], v[162:165], v[186:189], v[122:125]
	v_mfma_f32_16x16x32_bf16 v[118:121], v[146:149], v[194:197], v[118:121]
	v_mfma_f32_16x16x32_bf16 v[114:117], v[162:165], v[194:197], v[114:117]
	v_mfma_f32_16x16x32_bf16 v[106:109], v[146:149], v[202:205], v[106:109]
	v_mfma_f32_16x16x32_bf16 v[98:101], v[162:165], v[202:205], v[98:101]
	v_mfma_f32_16x16x32_bf16 v[78:81], v[146:149], v[210:213], v[78:81]
	v_mfma_f32_16x16x32_bf16 v[74:77], v[162:165], v[210:213], v[74:77]
	v_mfma_f32_16x16x32_bf16 v[126:129], v[158:161], v[190:193], v[126:129]
	v_mfma_f32_16x16x32_bf16 v[122:125], v[166:169], v[190:193], v[122:125]
	v_mfma_f32_16x16x32_bf16 v[118:121], v[158:161], v[198:201], v[118:121]
	v_mfma_f32_16x16x32_bf16 v[114:117], v[166:169], v[198:201], v[114:117]
	v_mfma_f32_16x16x32_bf16 v[106:109], v[158:161], v[206:209], v[106:109]
	v_mfma_f32_16x16x32_bf16 v[98:101], v[166:169], v[206:209], v[98:101]
	v_mfma_f32_16x16x32_bf16 v[78:81], v[158:161], v[218:221], v[78:81]
	v_mfma_f32_16x16x32_bf16 v[74:77], v[166:169], v[218:221], v[74:77]
	s_setprio 0
	s_setprio 1
	v_mfma_f32_16x16x32_bf16 v[110:113], v[170:173], v[186:189], v[110:113]
	v_mfma_f32_16x16x32_bf16 v[102:105], v[178:181], v[186:189], v[102:105]
	v_mfma_f32_16x16x32_bf16 v[94:97], v[170:173], v[194:197], v[94:97]
	v_mfma_f32_16x16x32_bf16 v[90:93], v[178:181], v[194:197], v[90:93]
	v_mfma_f32_16x16x32_bf16 v[86:89], v[170:173], v[202:205], v[86:89]
	v_mfma_f32_16x16x32_bf16 v[82:85], v[178:181], v[202:205], v[82:85]
	v_mfma_f32_16x16x32_bf16 v[70:73], v[170:173], v[210:213], v[70:73]
	v_mfma_f32_16x16x32_bf16 v[66:69], v[178:181], v[210:213], v[66:69]
	v_mfma_f32_16x16x32_bf16 v[110:113], v[174:177], v[190:193], v[110:113]
	v_mfma_f32_16x16x32_bf16 v[102:105], v[182:185], v[190:193], v[102:105]
	v_mfma_f32_16x16x32_bf16 v[94:97], v[174:177], v[198:201], v[94:97]
	v_mfma_f32_16x16x32_bf16 v[90:93], v[182:185], v[198:201], v[90:93]
	v_mfma_f32_16x16x32_bf16 v[86:89], v[174:177], v[206:209], v[86:89]
	v_mfma_f32_16x16x32_bf16 v[82:85], v[182:185], v[206:209], v[82:85]
	v_mfma_f32_16x16x32_bf16 v[70:73], v[174:177], v[218:221], v[70:73]
	v_mfma_f32_16x16x32_bf16 v[66:69], v[182:185], v[218:221], v[66:69]
	s_setprio 0
	s_barrier
	s_add_i32 s54, s45, s35
	v_lshl_add_u64 v[214:215], s[26:27], 0, v[134:135]
	s_mov_b32 m0, s54
	ds_read_b128 v[186:189], v157 offset:16384
	ds_read_b128 v[190:193], v157 offset:17408
	ds_read_b128 v[194:197], v157 offset:18432
	ds_read_b128 v[198:201], v157 offset:19456
	ds_read_b128 v[202:205], v157 offset:20480
	ds_read_b128 v[206:209], v157 offset:21504
	ds_read_b128 v[210:213], v157 offset:22528
	ds_read_b128 v[218:221], v157 offset:23552
	global_load_lds_dwordx4 v[214:215], off
	s_add_i32 m0, s54, 0x2000
	s_add_u32 s54, s26, 0x100000
	v_lshl_add_u64 v[222:223], s[26:27], 0, v[130:131]
	s_addc_u32 s55, s27, 0
	s_add_i32 s56, s46, s35
	global_load_lds_dwordx4 v[222:223], off
	v_lshl_add_u64 v[224:225], s[54:55], 0, v[134:135]
	s_mov_b32 m0, s56
	v_lshl_add_u64 v[226:227], s[28:29], 0, v[132:133]
	global_load_lds_dwordx4 v[224:225], off
	v_lshl_add_u64 v[224:225], s[54:55], 0, v[130:131]
	s_add_i32 m0, s56, 0x2000
	s_nop 0
	global_load_lds_dwordx4 v[224:225], off
	v_lshl_add_u64 v[224:225], s[28:29], 0, v[136:137]
	s_mov_b32 m0, s23
	s_nop 0
	global_load_lds_dwordx4 v[224:225], off
	s_waitcnt vmcnt(7)
	s_waitcnt lgkmcnt(0)
	s_barrier
; #define PG8_STAGE(bufoff, gbase, voff) do { _Pragma("unroll") for (int _i = 0; _i < 2; ++_i) \
;         __builtin_amdgcn_global_load_lds((const unsigned*)((const char*)(gbase) + (voff)[_i]), (PG8_LAS unsigned*)(lds + (bufoff) + ldsw + _i * 8192), 16, 0, 0); } while (0)
; #define PG8_LDA(dst, b, h) do { _Pragma("unroll") for (int m = 0; m < 4; ++m) _Pragma("unroll") for (int k = 0; k < 2; ++k) dst[m][k] = *(const PG8_LAS bf16x8*)(lds + PG8_SA(b, h) + aoff + m * 2048 + k * 1024); } while (0)
; #define PG8_LDB(dst, b, h) do { _Pragma("unroll") for (int n = 0; n < 2; ++n) _Pragma("unroll") for (int k = 0; k < 2; ++k) dst[n][k] = *(const PG8_LAS bf16x8*)(lds + PG8_SB(b, h) + boff + n * 2048 + k * 1024); } while (0)
; #define PG8_MMA(ai, bj, At, Bt) do { __builtin_amdgcn_s_setprio(1); _Pragma("unroll") for (int m = 0; m < 4; ++m) _Pragma("unroll") for (int n = 0; n < 2; ++n) _Pragma("unroll") for (int k = 0; k < 2; ++k) \
;         acc[ai][bj][m][n] = __builtin_amdgcn_mfma_f32_16x16x32_bf16(Bt[n][k], At[m][k], acc[ai][bj][m][n], 0, 0, 0); __builtin_amdgcn_s_setprio(0); } while (0)
; #define PG8_WAIT_V(n) asm volatile("s_waitcnt vmcnt(" #n ")" ::: "memory")
; #define PG8_WAIT_L(n) asm volatile("s_waitcnt lgkmcnt(" #n ")" ::: "memory")
; #define PG8_BAR __builtin_amdgcn_s_barrier()
; #define PG8_SCHED __builtin_amdgcn_sched_barrier(0)
; template <class Epi, class Sched, bool ALIGN_EPI = false, bool SP2 = false>
; __device__ __forceinline__ void gemm_phase(PG8_LAS unsigned char* lds, const Gemm g, const Sched& S, const Epi& E) {
;     ...
;             PG8_WAIT_V(8); PG8_WAIT_L(0); PG8_BAR; PG8_MMA(0, 0, At, B0); PG8_MMA(0, 1, At, B1); PG8_BAR; PG8_SCHED;
;             PG8_LDA(At, 0, 1); PG8_STAGE(PG8_SB(0, 0), b2, voffB); PG8_STAGE(PG8_SB(0, 1), b2 + hstepB, voffB); PG8_STAGE(PG8_SA(0, 0), a2, voffA);
;             PG8_WAIT_V(8); PG8_WAIT_L(0); PG8_BAR; PG8_MMA(1, 0, At, B0); PG8_MMA(1, 1, At, B1); PG8_BAR; PG8_SCHED;
;             PG8_LDB(B0, 1, 0); PG8_LDB(B1, 1, 1); PG8_SCHED; PG8_LDA(At, 1, 0); PG8_STAGE(PG8_SA(0, 1), a2 + hstepA, voffA);
;             PG8_WAIT_V(8); PG8_WAIT_L(0); PG8_BAR; PG8_MMA(0, 0, At, B0); PG8_MMA(0, 1, At, B1); PG8_BAR; PG8_SCHED;
	s_setprio 1
	s_waitcnt lgkmcnt(0)
	v_mfma_f32_16x16x32_bf16 v[62:65], v[146:149], v[186:189], v[62:65]
	v_mfma_f32_16x16x32_bf16 v[58:61], v[162:165], v[186:189], v[58:61]
	v_mfma_f32_16x16x32_bf16 v[50:53], v[146:149], v[194:197], v[50:53]
	v_mfma_f32_16x16x32_bf16 v[42:45], v[162:165], v[194:197], v[42:45]
	v_mfma_f32_16x16x32_bf16 v[34:37], v[146:149], v[202:205], v[34:37]
	v_mfma_f32_16x16x32_bf16 v[26:29], v[162:165], v[202:205], v[26:29]
	v_mfma_f32_16x16x32_bf16 v[18:21], v[146:149], v[210:213], v[18:21]
	v_mfma_f32_16x16x32_bf16 v[10:13], v[162:165], v[210:213], v[10:13]
	v_mfma_f32_16x16x32_bf16 v[62:65], v[158:161], v[190:193], v[62:65]
	v_mfma_f32_16x16x32_bf16 v[58:61], v[166:169], v[190:193], v[58:61]
	v_mfma_f32_16x16x32_bf16 v[50:53], v[158:161], v[198:201], v[50:53]
	v_mfma_f32_16x16x32_bf16 v[42:45], v[166:169], v[198:201], v[42:45]
	v_mfma_f32_16x16x32_bf16 v[34:37], v[158:161], v[206:209], v[34:37]
	v_mfma_f32_16x16x32_bf16 v[26:29], v[166:169], v[206:209], v[26:29]
	v_mfma_f32_16x16x32_bf16 v[18:21], v[158:161], v[218:221], v[18:21]
	v_mfma_f32_16x16x32_bf16 v[10:13], v[166:169], v[218:221], v[10:13]
	s_setprio 0
	s_setprio 1
	v_mfma_f32_16x16x32_bf16 v[54:57], v[170:173], v[186:189], v[54:57]
	v_mfma_f32_16x16x32_bf16 v[46:49], v[178:181], v[186:189], v[46:49]
	v_mfma_f32_16x16x32_bf16 v[38:41], v[170:173], v[194:197], v[38:41]
	v_mfma_f32_16x16x32_bf16 v[30:33], v[178:181], v[194:197], v[30:33]
	v_mfma_f32_16x16x32_bf16 v[22:25], v[170:173], v[202:205], v[22:25]
	v_mfma_f32_16x16x32_bf16 v[14:17], v[178:181], v[202:205], v[14:17]
	v_mfma_f32_16x16x32_bf16 v[6:9], v[170:173], v[210:213], v[6:9]
	v_mfma_f32_16x16x32_bf16 v[2:5], v[178:181], v[210:213], v[2:5]
	v_mfma_f32_16x16x32_bf16 v[54:57], v[174:177], v[190:193], v[54:57]
	v_mfma_f32_16x16x32_bf16 v[46:49], v[182:185], v[190:193], v[46:49]
	v_mfma_f32_16x16x32_bf16 v[38:41], v[174:177], v[198:201], v[38:41]
	v_mfma_f32_16x16x32_bf16 v[30:33], v[182:185], v[198:201], v[30:33]
	v_mfma_f32_16x16x32_bf16 v[22:25], v[174:177], v[206:209], v[22:25]
	v_mfma_f32_16x16x32_bf16 v[14:17], v[182:185], v[206:209], v[14:17]
	v_mfma_f32_16x16x32_bf16 v[6:9], v[174:177], v[218:221], v[6:9]
	v_mfma_f32_16x16x32_bf16 v[2:5], v[182:185], v[218:221], v[2:5]
	s_setprio 0
	s_barrier
	s_mov_b32 m0, s38
	s_nop 0
	global_load_lds_dwordx4 v[226:227], off
	s_add_i32 s54, 0, 0x18000
	v_add_u32_e32 v150, s54, v151
	s_add_i32 s55, 0, 0x1c000
	ds_read_b128 v[146:149], v150
	ds_read_b128 v[158:161], v150 offset:1024
	ds_read_b128 v[162:165], v150 offset:2048
	ds_read_b128 v[166:169], v150 offset:3072
	v_add_u32_e32 v150, s55, v151
	ds_read_b128 v[170:173], v150
	ds_read_b128 v[174:177], v150 offset:1024
	ds_read_b128 v[178:181], v150 offset:2048
	ds_read_b128 v[182:185], v150 offset:3072
	s_add_u32 s28, s28, 0x100000
	s_addc_u32 s29, s29, 0
	s_mov_b32 m0, s39
	v_lshl_add_u64 v[228:229], s[28:29], 0, v[136:137]
	ds_read_b128 v[186:189], v157 offset:32768
	ds_read_b128 v[190:193], v157 offset:33792
	ds_read_b128 v[194:197], v157 offset:34816
	ds_read_b128 v[198:201], v157 offset:35840
	ds_read_b128 v[202:205], v157 offset:36864
	ds_read_b128 v[206:209], v157 offset:37888
	ds_read_b128 v[210:213], v157 offset:38912
	ds_read_b128 v[218:221], v157 offset:39936
	global_load_lds_dwordx4 v[228:229], off
	v_lshl_add_u64 v[228:229], s[28:29], 0, v[132:133]
	s_mov_b32 m0, s40
	s_nop 0
	global_load_lds_dwordx4 v[228:229], off
	s_waitcnt vmcnt(8)
	s_waitcnt lgkmcnt(0)
	s_barrier
	s_setprio 1
	s_waitcnt lgkmcnt(0)
	v_mfma_f32_16x16x32_bf16 v[126:129], v[146:149], v[186:189], v[126:129]
	v_mfma_f32_16x16x32_bf16 v[122:125], v[162:165], v[186:189], v[122:125]
	v_mfma_f32_16x16x32_bf16 v[118:121], v[146:149], v[194:197], v[118:121]
	v_mfma_f32_16x16x32_bf16 v[114:117], v[162:165], v[194:197], v[114:117]
	v_mfma_f32_16x16x32_bf16 v[106:109], v[146:149], v[202:205], v[106:109]
	v_mfma_f32_16x16x32_bf16 v[98:101], v[162:165], v[202:205], v[98:101]
	v_mfma_f32_16x16x32_bf16 v[78:81], v[146:149], v[210:213], v[78:81]
	v_mfma_f32_16x16x32_bf16 v[74:77], v[162:165], v[210:213], v[74:77]
	v_mfma_f32_16x16x32_bf16 v[126:129], v[158:161], v[190:193], v[126:129]
	v_mfma_f32_16x16x32_bf16 v[122:125], v[166:169], v[190:193], v[122:125]
	v_mfma_f32_16x16x32_bf16 v[118:121], v[158:161], v[198:201], v[118:121]
	v_mfma_f32_16x16x32_bf16 v[114:117], v[166:169], v[198:201], v[114:117]
	v_mfma_f32_16x16x32_bf16 v[106:109], v[158:161], v[206:209], v[106:109]
	v_mfma_f32_16x16x32_bf16 v[98:101], v[166:169], v[206:209], v[98:101]
	v_mfma_f32_16x16x32_bf16 v[78:81], v[158:161], v[218:221], v[78:81]
	v_mfma_f32_16x16x32_bf16 v[74:77], v[166:169], v[218:221], v[74:77]
	s_setprio 0
	s_setprio 1
	v_mfma_f32_16x16x32_bf16 v[110:113], v[170:173], v[186:189], v[110:113]
	v_mfma_f32_16x16x32_bf16 v[102:105], v[178:181], v[186:189], v[102:105]
	v_mfma_f32_16x16x32_bf16 v[94:97], v[170:173], v[194:197], v[94:97]
	v_mfma_f32_16x16x32_bf16 v[90:93], v[178:181], v[194:197], v[90:93]
	v_mfma_f32_16x16x32_bf16 v[86:89], v[170:173], v[202:205], v[86:89]
	v_mfma_f32_16x16x32_bf16 v[82:85], v[178:181], v[202:205], v[82:85]
	v_mfma_f32_16x16x32_bf16 v[70:73], v[170:173], v[210:213], v[70:73]
	v_mfma_f32_16x16x32_bf16 v[66:69], v[178:181], v[210:213], v[66:69]
	v_mfma_f32_16x16x32_bf16 v[110:113], v[174:177], v[190:193], v[110:113]
	v_mfma_f32_16x16x32_bf16 v[102:105], v[182:185], v[190:193], v[102:105]
	v_mfma_f32_16x16x32_bf16 v[94:97], v[174:177], v[198:201], v[94:97]
	v_mfma_f32_16x16x32_bf16 v[90:93], v[182:185], v[198:201], v[90:93]
	v_mfma_f32_16x16x32_bf16 v[86:89], v[174:177], v[206:209], v[86:89]
	v_mfma_f32_16x16x32_bf16 v[82:85], v[182:185], v[206:209], v[82:85]
	v_mfma_f32_16x16x32_bf16 v[70:73], v[174:177], v[218:221], v[70:73]
	v_mfma_f32_16x16x32_bf16 v[66:69], v[182:185], v[218:221], v[66:69]
	s_setprio 0
	s_barrier
; #define PG8_STAGE(bufoff, gbase, voff) do { _Pragma("unroll") for (int _i = 0; _i < 2; ++_i) \
;         __builtin_amdgcn_global_load_lds((const unsigned*)((const char*)(gbase) + (voff)[_i]), (PG8_LAS unsigned*)(lds + (bufoff) + ldsw + _i * 8192), 16, 0, 0); } while (0)
; #define PG8_LDA(dst, b, h) do { _Pragma("unroll") for (int m = 0; m < 4; ++m) _Pragma("unroll") for (int k = 0; k < 2; ++k) dst[m][k] = *(const PG8_LAS bf16x8*)(lds + PG8_SA(b, h) + aoff + m * 2048 + k * 1024); } while (0)
; #define PG8_MMA(ai, bj, At, Bt) do { __builtin_amdgcn_s_setprio(1); _Pragma("unroll") for (int m = 0; m < 4; ++m) _Pragma("unroll") for (int n = 0; n < 2; ++n) _Pragma("unroll") for (int k = 0; k < 2; ++k) \
;         acc[ai][bj][m][n] = __builtin_amdgcn_mfma_f32_16x16x32_bf16(Bt[n][k], At[m][k], acc[ai][bj][m][n], 0, 0, 0); __builtin_amdgcn_s_setprio(0); } while (0)
; #define PG8_WAIT_V(n) asm volatile("s_waitcnt vmcnt(" #n ")" ::: "memory")
; #define PG8_WAIT_L(n) asm volatile("s_waitcnt lgkmcnt(" #n ")" ::: "memory")
; #define PG8_BAR __builtin_amdgcn_s_barrier()
; #define PG8_SCHED __builtin_amdgcn_sched_barrier(0)
; template <class Epi, class Sched, bool ALIGN_EPI = false, bool SP2 = false>
; __device__ __forceinline__ void gemm_phase(PG8_LAS unsigned char* lds, const Gemm g, const Sched& S, const Epi& E) {
;     ...
;             PG8_WAIT_V(8); PG8_WAIT_L(0); PG8_BAR; PG8_MMA(0, 0, At, B0); PG8_MMA(0, 1, At, B1); PG8_BAR; PG8_SCHED;
;             PG8_LDA(At, 1, 1); PG8_STAGE(PG8_SB(1, 0), b3, voffB); PG8_STAGE(PG8_SB(1, 1), b3 + hstepB, voffB); PG8_STAGE(PG8_SA(1, 0), a3, voffA);
;             PG8_WAIT_V(8); PG8_WAIT_L(0); PG8_BAR; PG8_MMA(1, 0, At, B0); PG8_MMA(1, 1, At, B1); PG8_BAR; PG8_SCHED;
;     ...
;         }
;         if constexpr (ALIGN_EPI) { if (wr == 0) PG8_BAR; }
	s_add_i32 s28, s54, s35
	v_lshl_add_u64 v[214:215], v[214:215], 0, s[10:11]
	s_mov_b32 m0, s28
	ds_read_b128 v[186:189], v157 offset:49152
	ds_read_b128 v[190:193], v157 offset:50176
	ds_read_b128 v[194:197], v157 offset:51200
	ds_read_b128 v[198:201], v157 offset:52224
	ds_read_b128 v[202:205], v157 offset:53248
	ds_read_b128 v[206:209], v157 offset:54272
	ds_read_b128 v[210:213], v157 offset:55296
	ds_read_b128 v[218:221], v157 offset:56320
	global_load_lds_dwordx4 v[214:215], off
	s_add_i32 m0, s28, 0x2000
	s_add_u32 s26, s26, 0x100080
	v_lshl_add_u64 v[214:215], v[222:223], 0, s[10:11]
	s_addc_u32 s27, s27, 0
	s_add_i32 s28, s55, s35
	global_load_lds_dwordx4 v[214:215], off
	v_lshl_add_u64 v[214:215], s[26:27], 0, v[134:135]
	s_mov_b32 m0, s28
	s_nop 0
	global_load_lds_dwordx4 v[214:215], off
	v_lshl_add_u64 v[214:215], s[26:27], 0, v[130:131]
	s_add_i32 m0, s28, 0x2000
	s_nop 0
	global_load_lds_dwordx4 v[214:215], off
	v_lshl_add_u64 v[214:215], v[224:225], 0, s[10:11]
	s_mov_b32 m0, s42
	s_nop 0
	global_load_lds_dwordx4 v[214:215], off
	s_waitcnt vmcnt(7)
	s_waitcnt lgkmcnt(0)
	s_barrier
	s_setprio 1
	s_waitcnt lgkmcnt(0)
	v_mfma_f32_16x16x32_bf16 v[62:65], v[146:149], v[186:189], v[62:65]
	v_mfma_f32_16x16x32_bf16 v[58:61], v[162:165], v[186:189], v[58:61]
	v_mfma_f32_16x16x32_bf16 v[50:53], v[146:149], v[194:197], v[50:53]
	v_mfma_f32_16x16x32_bf16 v[42:45], v[162:165], v[194:197], v[42:45]
	v_mfma_f32_16x16x32_bf16 v[34:37], v[146:149], v[202:205], v[34:37]
	v_mfma_f32_16x16x32_bf16 v[26:29], v[162:165], v[202:205], v[26:29]
	v_mfma_f32_16x16x32_bf16 v[18:21], v[146:149], v[210:213], v[18:21]
	v_mfma_f32_16x16x32_bf16 v[10:13], v[162:165], v[210:213], v[10:13]
	v_mfma_f32_16x16x32_bf16 v[62:65], v[158:161], v[190:193], v[62:65]
	v_mfma_f32_16x16x32_bf16 v[58:61], v[166:169], v[190:193], v[58:61]
	v_mfma_f32_16x16x32_bf16 v[50:53], v[158:161], v[198:201], v[50:53]
	v_mfma_f32_16x16x32_bf16 v[42:45], v[166:169], v[198:201], v[42:45]
	v_mfma_f32_16x16x32_bf16 v[34:37], v[158:161], v[206:209], v[34:37]
	v_mfma_f32_16x16x32_bf16 v[26:29], v[166:169], v[206:209], v[26:29]
	v_mfma_f32_16x16x32_bf16 v[18:21], v[158:161], v[218:221], v[18:21]
	v_mfma_f32_16x16x32_bf16 v[10:13], v[166:169], v[218:221], v[10:13]
	s_setprio 0
	s_setprio 1
	v_mfma_f32_16x16x32_bf16 v[54:57], v[170:173], v[186:189], v[54:57]
	v_mfma_f32_16x16x32_bf16 v[46:49], v[178:181], v[186:189], v[46:49]
	v_mfma_f32_16x16x32_bf16 v[38:41], v[170:173], v[194:197], v[38:41]
	v_mfma_f32_16x16x32_bf16 v[30:33], v[178:181], v[194:197], v[30:33]
	v_mfma_f32_16x16x32_bf16 v[22:25], v[170:173], v[202:205], v[22:25]
	v_mfma_f32_16x16x32_bf16 v[14:17], v[178:181], v[202:205], v[14:17]
	v_mfma_f32_16x16x32_bf16 v[6:9], v[170:173], v[210:213], v[6:9]
	v_mfma_f32_16x16x32_bf16 v[2:5], v[178:181], v[210:213], v[2:5]
	v_mfma_f32_16x16x32_bf16 v[54:57], v[174:177], v[190:193], v[54:57]
	v_mfma_f32_16x16x32_bf16 v[46:49], v[182:185], v[190:193], v[46:49]
	v_mfma_f32_16x16x32_bf16 v[38:41], v[174:177], v[198:201], v[38:41]
	v_mfma_f32_16x16x32_bf16 v[30:33], v[182:185], v[198:201], v[30:33]
	v_mfma_f32_16x16x32_bf16 v[22:25], v[174:177], v[206:209], v[22:25]
	v_mfma_f32_16x16x32_bf16 v[14:17], v[182:185], v[206:209], v[14:17]
	v_mfma_f32_16x16x32_bf16 v[6:9], v[174:177], v[218:221], v[6:9]
	v_mfma_f32_16x16x32_bf16 v[2:5], v[182:185], v[218:221], v[2:5]
	s_setprio 0
	s_barrier
	v_lshl_add_u64 v[214:215], v[226:227], 0, s[10:11]
	s_mov_b32 m0, s43
	s_nop 0
	global_load_lds_dwordx4 v[214:215], off
	s_add_i32 s53, s53, 2
	s_add_u32 s24, s24, 0x100
	s_addc_u32 s25, s25, 0
	s_add_u32 s51, s51, 0x100
	s_addc_u32 s52, s52, 0
	s_cmp_gt_u32 s53, 61
	s_cbranch_scc0 .LBB0_210
	s_and_b64 vcc, exec, s[12:13]
	s_cbranch_vccz .LBB0_213
	s_barrier

; #define PG8_STAGE(bufoff, gbase, voff) do { _Pragma("unroll") for (int _i = 0; _i < 2; ++_i) \
;         __builtin_amdgcn_global_load_lds((const unsigned*)((const char*)(gbase) + (voff)[_i]), (PG8_LAS unsigned*)(lds + (bufoff) + ldsw + _i * 8192), 16, 0, 0); } while (0)
; #define PG8_LDA(dst, b, h) do { _Pragma("unroll") for (int m = 0; m < 4; ++m) _Pragma("unroll") for (int k = 0; k < 2; ++k) dst[m][k] = *(const PG8_LAS bf16x8*)(lds + PG8_SA(b, h) + aoff + m * 2048 + k * 1024); } while (0)
; #define PG8_LDB(dst, b, h) do { _Pragma("unroll") for (int n = 0; n < 2; ++n) _Pragma("unroll") for (int k = 0; k < 2; ++k) dst[n][k] = *(const PG8_LAS bf16x8*)(lds + PG8_SB(b, h) + boff + n * 2048 + k * 1024); } while (0)
; #define PG8_MMA(ai, bj, At, Bt) do { __builtin_amdgcn_s_setprio(1); _Pragma("unroll") for (int m = 0; m < 4; ++m) _Pragma("unroll") for (int n = 0; n < 2; ++n) _Pragma("unroll") for (int k = 0; k < 2; ++k) \
;         acc[ai][bj][m][n] = __builtin_amdgcn_mfma_f32_16x16x32_bf16(Bt[n][k], At[m][k], acc[ai][bj][m][n], 0, 0, 0); __builtin_amdgcn_s_setprio(0); } while (0)
; #define PG8_WAIT_V(n) asm volatile("s_waitcnt vmcnt(" #n ")" ::: "memory")
; #define PG8_BAR __builtin_amdgcn_s_barrier()
; template <class Epi, class Sched, bool ALIGN_EPI = false, bool SP2 = false>
; __device__ __forceinline__ void gemm_phase(PG8_LAS unsigned char* lds, const Gemm g, const Sched& S, const Epi& E) {
;     ...
;         for (int t = 0; t < nt; t += 2) {
;             const bool last = (t == nt - 2);
;             const char* a1 = cA + (size_t)(t + 1) * kstep;
;             const char* a2 = last ? nA : cA + (size_t)(t + 2) * kstep; const char* b2 = last ? nB : cB + (size_t)(t + 2) * kstep;
;             const char* a3 = a2 + kstep; const char* b3 = b2 + kstep;
;             if (last && has_next) S.a_ready(nxt);
;             if constexpr (SP2) {
;             PG8_LDB(B0, 0, 0); PG8_LDB(B1, 0, 1); PG8_SCHED; PG8_LDA(At, 0, 0); PG8_STAGE(PG8_SA(1, 1), a1 + hstepA, voffA);
;             PG8_WAIT_V(8); PG8_WAIT_L(0); PG8_BAR; PG8_MMA(0, 0, At, B0); PG8_MMA(0, 1, At, B1); PG8_BAR; PG8_SCHED;
;             PG8_LDA(At, 0, 1); PG8_STAGE(PG8_SB(0, 0), b2, voffB); PG8_STAGE(PG8_SB(0, 1), b2 + hstepB, voffB); PG8_STAGE(PG8_SA(0, 0), a2, voffA);
;             PG8_WAIT_V(8); PG8_WAIT_L(0); PG8_BAR; PG8_MMA(1, 0, At, B0); PG8_MMA(1, 1, At, B1); PG8_BAR; PG8_SCHED;
.LBB0_241:
	s_lshl_b32 s26, s54, 7
	s_add_u32 s27, s16, s26
	s_addc_u32 s28, s17, 0
	v_add_u32_e32 v170, s46, v1
	s_add_u32 s29, s27, 0x100
	ds_read_b128 v[178:181], v170
	ds_read_b128 v[182:185], v170 offset:1024
	ds_read_b128 v[186:189], v170 offset:2048
	ds_read_b128 v[190:193], v170 offset:3072
	v_add_u32_e32 v170, s47, v1
	s_addc_u32 s55, s28, 0
	ds_read_b128 v[194:197], v170
	ds_read_b128 v[198:201], v170 offset:1024
	ds_read_b128 v[202:205], v170 offset:2048
	ds_read_b128 v[206:209], v170 offset:3072
	s_and_b64 s[24:25], s[22:23], exec
	s_cselect_b32 s25, s50, s55
	s_cselect_b32 s24, s51, s29
	s_add_u32 s26, s18, s26
	s_addc_u32 s29, s19, 0
	s_add_u32 s26, s26, 0x100
	s_addc_u32 s29, s29, 0
	s_and_b64 s[22:23], s[22:23], exec
	s_cselect_b32 s23, s52, s29
	s_cselect_b32 s22, s53, s26
	s_add_u32 s26, s27, 0x100080
	s_addc_u32 s27, s28, 0
	v_lshl_add_u64 v[214:215], s[26:27], 0, v[132:133]
	s_add_i32 m0, s1, 0xc000
	ds_read_b128 v[210:213], v175
	ds_read_b128 v[218:221], v175 offset:1024
	ds_read_b128 v[222:225], v175 offset:2048
	ds_read_b128 v[226:229], v175 offset:3072
	ds_read_b128 v[230:233], v175 offset:4096
	ds_read_b128 v[234:237], v175 offset:5120
	ds_read_b128 v[238:241], v175 offset:6144
	ds_read_b128 v[242:245], v175 offset:7168
	global_load_lds_dwordx4 v[214:215], off
	v_lshl_add_u64 v[214:215], s[26:27], 0, v[134:135]
	s_add_i32 m0, s1, 0xe000
	s_nop 0
	global_load_lds_dwordx4 v[214:215], off
	s_waitcnt vmcnt(8)
	s_waitcnt lgkmcnt(0)
	s_barrier
	s_setprio 1
	s_waitcnt lgkmcnt(0)
	v_mfma_f32_16x16x32_bf16 v[126:129], v[178:181], v[210:213], v[126:129]
	v_mfma_f32_16x16x32_bf16 v[122:125], v[186:189], v[210:213], v[122:125]
	v_mfma_f32_16x16x32_bf16 v[118:121], v[178:181], v[222:225], v[118:121]
	v_mfma_f32_16x16x32_bf16 v[114:117], v[186:189], v[222:225], v[114:117]
	v_mfma_f32_16x16x32_bf16 v[110:113], v[178:181], v[230:233], v[110:113]
	v_mfma_f32_16x16x32_bf16 v[102:105], v[186:189], v[230:233], v[102:105]
	v_mfma_f32_16x16x32_bf16 v[94:97], v[178:181], v[238:241], v[94:97]
	v_mfma_f32_16x16x32_bf16 v[86:89], v[186:189], v[238:241], v[86:89]
	v_mfma_f32_16x16x32_bf16 v[126:129], v[182:185], v[218:221], v[126:129]
	v_mfma_f32_16x16x32_bf16 v[122:125], v[190:193], v[218:221], v[122:125]
	v_mfma_f32_16x16x32_bf16 v[118:121], v[182:185], v[226:229], v[118:121]
	v_mfma_f32_16x16x32_bf16 v[114:117], v[190:193], v[226:229], v[114:117]
	v_mfma_f32_16x16x32_bf16 v[110:113], v[182:185], v[234:237], v[110:113]
	v_mfma_f32_16x16x32_bf16 v[102:105], v[190:193], v[234:237], v[102:105]
	v_mfma_f32_16x16x32_bf16 v[94:97], v[182:185], v[242:245], v[94:97]
	v_mfma_f32_16x16x32_bf16 v[86:89], v[190:193], v[242:245], v[86:89]
	s_setprio 0
	s_setprio 1
	v_mfma_f32_16x16x32_bf16 v[106:109], v[194:197], v[210:213], v[106:109]
	v_mfma_f32_16x16x32_bf16 v[98:101], v[202:205], v[210:213], v[98:101]
	v_mfma_f32_16x16x32_bf16 v[90:93], v[194:197], v[222:225], v[90:93]
	v_mfma_f32_16x16x32_bf16 v[82:85], v[202:205], v[222:225], v[82:85]
	v_mfma_f32_16x16x32_bf16 v[78:81], v[194:197], v[230:233], v[78:81]
	v_mfma_f32_16x16x32_bf16 v[74:77], v[202:205], v[230:233], v[74:77]
	v_mfma_f32_16x16x32_bf16 v[70:73], v[194:197], v[238:241], v[70:73]
	v_mfma_f32_16x16x32_bf16 v[66:69], v[202:205], v[238:241], v[66:69]
	v_mfma_f32_16x16x32_bf16 v[106:109], v[198:201], v[218:221], v[106:109]
	v_mfma_f32_16x16x32_bf16 v[98:101], v[206:209], v[218:221], v[98:101]
	v_mfma_f32_16x16x32_bf16 v[90:93], v[198:201], v[226:229], v[90:93]
	v_mfma_f32_16x16x32_bf16 v[82:85], v[206:209], v[226:229], v[82:85]
	v_mfma_f32_16x16x32_bf16 v[78:81], v[198:201], v[234:237], v[78:81]
	v_mfma_f32_16x16x32_bf16 v[74:77], v[206:209], v[234:237], v[74:77]
	v_mfma_f32_16x16x32_bf16 v[70:73], v[198:201], v[242:245], v[70:73]
	v_mfma_f32_16x16x32_bf16 v[66:69], v[206:209], v[242:245], v[66:69]
	s_setprio 0
	s_barrier
	s_add_i32 s26, s46, s39
	v_lshl_add_u64 v[214:215], s[22:23], 0, v[130:131]
	s_mov_b32 m0, s26
	ds_read_b128 v[210:213], v175 offset:16384
	ds_read_b128 v[218:221], v175 offset:17408
	ds_read_b128 v[222:225], v175 offset:18432
	ds_read_b128 v[226:229], v175 offset:19456
	ds_read_b128 v[230:233], v175 offset:20480
	ds_read_b128 v[234:237], v175 offset:21504
	ds_read_b128 v[238:241], v175 offset:22528
	ds_read_b128 v[242:245], v175 offset:23552
	global_load_lds_dwordx4 v[214:215], off
	s_add_i32 m0, s26, 0x2000
	s_add_u32 s26, s22, 0x100000
	v_lshl_add_u64 v[246:247], s[22:23], 0, v[136:137]
	s_addc_u32 s27, s23, 0
	s_add_i32 s28, s47, s39
	global_load_lds_dwordx4 v[246:247], off
	v_lshl_add_u64 v[248:249], s[26:27], 0, v[130:131]
	s_mov_b32 m0, s28
	v_lshl_add_u64 v[250:251], s[24:25], 0, v[134:135]
	global_load_lds_dwordx4 v[248:249], off
	v_lshl_add_u64 v[248:249], s[26:27], 0, v[136:137]
	s_add_i32 m0, s28, 0x2000
	s_nop 0
	global_load_lds_dwordx4 v[248:249], off
	v_lshl_add_u64 v[248:249], s[24:25], 0, v[132:133]
	s_mov_b32 m0, s1
	s_nop 0
	global_load_lds_dwordx4 v[248:249], off
	s_waitcnt vmcnt(7)
	s_waitcnt lgkmcnt(0)
	s_barrier
; #define PG8_STAGE(bufoff, gbase, voff) do { _Pragma("unroll") for (int _i = 0; _i < 2; ++_i) \
;         __builtin_amdgcn_global_load_lds((const unsigned*)((const char*)(gbase) + (voff)[_i]), (PG8_LAS unsigned*)(lds + (bufoff) + ldsw + _i * 8192), 16, 0, 0); } while (0)
; #define PG8_LDA(dst, b, h) do { _Pragma("unroll") for (int m = 0; m < 4; ++m) _Pragma("unroll") for (int k = 0; k < 2; ++k) dst[m][k] = *(const PG8_LAS bf16x8*)(lds + PG8_SA(b, h) + aoff + m * 2048 + k * 1024); } while (0)
; #define PG8_LDB(dst, b, h) do { _Pragma("unroll") for (int n = 0; n < 2; ++n) _Pragma("unroll") for (int k = 0; k < 2; ++k) dst[n][k] = *(const PG8_LAS bf16x8*)(lds + PG8_SB(b, h) + boff + n * 2048 + k * 1024); } while (0)
; #define PG8_MMA(ai, bj, At, Bt) do { __builtin_amdgcn_s_setprio(1); _Pragma("unroll") for (int m = 0; m < 4; ++m) _Pragma("unroll") for (int n = 0; n < 2; ++n) _Pragma("unroll") for (int k = 0; k < 2; ++k) \
;         acc[ai][bj][m][n] = __builtin_amdgcn_mfma_f32_16x16x32_bf16(Bt[n][k], At[m][k], acc[ai][bj][m][n], 0, 0, 0); __builtin_amdgcn_s_setprio(0); } while (0)
; #define PG8_WAIT_V(n) asm volatile("s_waitcnt vmcnt(" #n ")" ::: "memory")
; #define PG8_WAIT_L(n) asm volatile("s_waitcnt lgkmcnt(" #n ")" ::: "memory")
; #define PG8_BAR __builtin_amdgcn_s_barrier()
; #define PG8_SCHED __builtin_amdgcn_sched_barrier(0)
; template <class Epi, class Sched, bool ALIGN_EPI = false, bool SP2 = false>
; __device__ __forceinline__ void gemm_phase(PG8_LAS unsigned char* lds, const Gemm g, const Sched& S, const Epi& E) {
;     ...
;             PG8_WAIT_V(8); PG8_WAIT_L(0); PG8_BAR; PG8_MMA(0, 0, At, B0); PG8_MMA(0, 1, At, B1); PG8_BAR; PG8_SCHED;
;             PG8_LDA(At, 0, 1); PG8_STAGE(PG8_SB(0, 0), b2, voffB); PG8_STAGE(PG8_SB(0, 1), b2 + hstepB, voffB); PG8_STAGE(PG8_SA(0, 0), a2, voffA);
;             PG8_WAIT_V(8); PG8_WAIT_L(0); PG8_BAR; PG8_MMA(1, 0, At, B0); PG8_MMA(1, 1, At, B1); PG8_BAR; PG8_SCHED;
;             PG8_LDB(B0, 1, 0); PG8_LDB(B1, 1, 1); PG8_SCHED; PG8_LDA(At, 1, 0); PG8_STAGE(PG8_SA(0, 1), a2 + hstepA, voffA);
;             PG8_WAIT_V(8); PG8_WAIT_L(0); PG8_BAR; PG8_MMA(0, 0, At, B0); PG8_MMA(0, 1, At, B1); PG8_BAR; PG8_SCHED;
	s_setprio 1
	s_waitcnt lgkmcnt(0)
	v_mfma_f32_16x16x32_bf16 v[62:65], v[178:181], v[210:213], v[62:65]
	v_mfma_f32_16x16x32_bf16 v[58:61], v[186:189], v[210:213], v[58:61]
	v_mfma_f32_16x16x32_bf16 v[50:53], v[178:181], v[222:225], v[50:53]
	v_mfma_f32_16x16x32_bf16 v[42:45], v[186:189], v[222:225], v[42:45]
	v_mfma_f32_16x16x32_bf16 v[34:37], v[178:181], v[230:233], v[34:37]
	v_mfma_f32_16x16x32_bf16 v[26:29], v[186:189], v[230:233], v[26:29]
	v_mfma_f32_16x16x32_bf16 v[18:21], v[178:181], v[238:241], v[18:21]
	v_mfma_f32_16x16x32_bf16 v[10:13], v[186:189], v[238:241], v[10:13]
	v_mfma_f32_16x16x32_bf16 v[62:65], v[182:185], v[218:221], v[62:65]
	v_mfma_f32_16x16x32_bf16 v[58:61], v[190:193], v[218:221], v[58:61]
	v_mfma_f32_16x16x32_bf16 v[50:53], v[182:185], v[226:229], v[50:53]
	v_mfma_f32_16x16x32_bf16 v[42:45], v[190:193], v[226:229], v[42:45]
	v_mfma_f32_16x16x32_bf16 v[34:37], v[182:185], v[234:237], v[34:37]
	v_mfma_f32_16x16x32_bf16 v[26:29], v[190:193], v[234:237], v[26:29]
	v_mfma_f32_16x16x32_bf16 v[18:21], v[182:185], v[242:245], v[18:21]
	v_mfma_f32_16x16x32_bf16 v[10:13], v[190:193], v[242:245], v[10:13]
	s_setprio 0
	s_setprio 1
	v_mfma_f32_16x16x32_bf16 v[54:57], v[194:197], v[210:213], v[54:57]
	v_mfma_f32_16x16x32_bf16 v[46:49], v[202:205], v[210:213], v[46:49]
	v_mfma_f32_16x16x32_bf16 v[38:41], v[194:197], v[222:225], v[38:41]
	v_mfma_f32_16x16x32_bf16 v[30:33], v[202:205], v[222:225], v[30:33]
	v_mfma_f32_16x16x32_bf16 v[22:25], v[194:197], v[230:233], v[22:25]
	v_mfma_f32_16x16x32_bf16 v[14:17], v[202:205], v[230:233], v[14:17]
	v_mfma_f32_16x16x32_bf16 v[6:9], v[194:197], v[238:241], v[6:9]
	v_mfma_f32_16x16x32_bf16 v[2:5], v[202:205], v[238:241], v[2:5]
	v_mfma_f32_16x16x32_bf16 v[54:57], v[198:201], v[218:221], v[54:57]
	v_mfma_f32_16x16x32_bf16 v[46:49], v[206:209], v[218:221], v[46:49]
	v_mfma_f32_16x16x32_bf16 v[38:41], v[198:201], v[226:229], v[38:41]
	v_mfma_f32_16x16x32_bf16 v[30:33], v[206:209], v[226:229], v[30:33]
	v_mfma_f32_16x16x32_bf16 v[22:25], v[198:201], v[234:237], v[22:25]
	v_mfma_f32_16x16x32_bf16 v[14:17], v[206:209], v[234:237], v[14:17]
	v_mfma_f32_16x16x32_bf16 v[6:9], v[198:201], v[242:245], v[6:9]
	v_mfma_f32_16x16x32_bf16 v[2:5], v[206:209], v[242:245], v[2:5]
	s_setprio 0
	s_barrier
	s_mov_b32 m0, s40
	s_nop 0
	global_load_lds_dwordx4 v[250:251], off
	s_add_i32 s26, 0, 0x18000
	v_add_u32_e32 v170, s26, v1
	s_add_i32 s27, 0, 0x1c000
	ds_read_b128 v[178:181], v170
	ds_read_b128 v[182:185], v170 offset:1024
	ds_read_b128 v[186:189], v170 offset:2048
	ds_read_b128 v[190:193], v170 offset:3072
	v_add_u32_e32 v170, s27, v1
	ds_read_b128 v[194:197], v170
	ds_read_b128 v[198:201], v170 offset:1024
	ds_read_b128 v[202:205], v170 offset:2048
	ds_read_b128 v[206:209], v170 offset:3072
	s_add_u32 s24, s24, 0x100000
	s_addc_u32 s25, s25, 0
	s_mov_b32 m0, s41
	v_lshl_add_u64 v[252:253], s[24:25], 0, v[132:133]
	ds_read_b128 v[210:213], v175 offset:32768
	ds_read_b128 v[218:221], v175 offset:33792
	ds_read_b128 v[222:225], v175 offset:34816
	ds_read_b128 v[226:229], v175 offset:35840
	ds_read_b128 v[230:233], v175 offset:36864
	ds_read_b128 v[234:237], v175 offset:37888
	ds_read_b128 v[238:241], v175 offset:38912
	ds_read_b128 v[242:245], v175 offset:39936
	global_load_lds_dwordx4 v[252:253], off
	v_lshl_add_u64 v[252:253], s[24:25], 0, v[134:135]
	s_mov_b32 m0, s42
	s_nop 0
	global_load_lds_dwordx4 v[252:253], off
	s_waitcnt vmcnt(8)
	s_waitcnt lgkmcnt(0)
	s_barrier
	s_setprio 1
	s_waitcnt lgkmcnt(0)
	v_mfma_f32_16x16x32_bf16 v[126:129], v[178:181], v[210:213], v[126:129]
	v_mfma_f32_16x16x32_bf16 v[122:125], v[186:189], v[210:213], v[122:125]
	v_mfma_f32_16x16x32_bf16 v[118:121], v[178:181], v[222:225], v[118:121]
	v_mfma_f32_16x16x32_bf16 v[114:117], v[186:189], v[222:225], v[114:117]
	v_mfma_f32_16x16x32_bf16 v[110:113], v[178:181], v[230:233], v[110:113]
	v_mfma_f32_16x16x32_bf16 v[102:105], v[186:189], v[230:233], v[102:105]
	v_mfma_f32_16x16x32_bf16 v[94:97], v[178:181], v[238:241], v[94:97]
	v_mfma_f32_16x16x32_bf16 v[86:89], v[186:189], v[238:241], v[86:89]
	v_mfma_f32_16x16x32_bf16 v[126:129], v[182:185], v[218:221], v[126:129]
	v_mfma_f32_16x16x32_bf16 v[122:125], v[190:193], v[218:221], v[122:125]
	v_mfma_f32_16x16x32_bf16 v[118:121], v[182:185], v[226:229], v[118:121]
	v_mfma_f32_16x16x32_bf16 v[114:117], v[190:193], v[226:229], v[114:117]
	v_mfma_f32_16x16x32_bf16 v[110:113], v[182:185], v[234:237], v[110:113]
	v_mfma_f32_16x16x32_bf16 v[102:105], v[190:193], v[234:237], v[102:105]
	v_mfma_f32_16x16x32_bf16 v[94:97], v[182:185], v[242:245], v[94:97]
	v_mfma_f32_16x16x32_bf16 v[86:89], v[190:193], v[242:245], v[86:89]
	s_setprio 0
	s_setprio 1
	v_mfma_f32_16x16x32_bf16 v[106:109], v[194:197], v[210:213], v[106:109]
	v_mfma_f32_16x16x32_bf16 v[98:101], v[202:205], v[210:213], v[98:101]
	v_mfma_f32_16x16x32_bf16 v[90:93], v[194:197], v[222:225], v[90:93]
	v_mfma_f32_16x16x32_bf16 v[82:85], v[202:205], v[222:225], v[82:85]
	v_mfma_f32_16x16x32_bf16 v[78:81], v[194:197], v[230:233], v[78:81]
	v_mfma_f32_16x16x32_bf16 v[74:77], v[202:205], v[230:233], v[74:77]
	v_mfma_f32_16x16x32_bf16 v[70:73], v[194:197], v[238:241], v[70:73]
	v_mfma_f32_16x16x32_bf16 v[66:69], v[202:205], v[238:241], v[66:69]
	v_mfma_f32_16x16x32_bf16 v[106:109], v[198:201], v[218:221], v[106:109]
	v_mfma_f32_16x16x32_bf16 v[98:101], v[206:209], v[218:221], v[98:101]
	v_mfma_f32_16x16x32_bf16 v[90:93], v[198:201], v[226:229], v[90:93]
	v_mfma_f32_16x16x32_bf16 v[82:85], v[206:209], v[226:229], v[82:85]
	v_mfma_f32_16x16x32_bf16 v[78:81], v[198:201], v[234:237], v[78:81]
	v_mfma_f32_16x16x32_bf16 v[74:77], v[206:209], v[234:237], v[74:77]
	v_mfma_f32_16x16x32_bf16 v[70:73], v[198:201], v[242:245], v[70:73]
	v_mfma_f32_16x16x32_bf16 v[66:69], v[206:209], v[242:245], v[66:69]
	s_setprio 0
	s_barrier
; #define PG8_STAGE(bufoff, gbase, voff) do { _Pragma("unroll") for (int _i = 0; _i < 2; ++_i) \
;         __builtin_amdgcn_global_load_lds((const unsigned*)((const char*)(gbase) + (voff)[_i]), (PG8_LAS unsigned*)(lds + (bufoff) + ldsw + _i * 8192), 16, 0, 0); } while (0)
; #define PG8_LDA(dst, b, h) do { _Pragma("unroll") for (int m = 0; m < 4; ++m) _Pragma("unroll") for (int k = 0; k < 2; ++k) dst[m][k] = *(const PG8_LAS bf16x8*)(lds + PG8_SA(b, h) + aoff + m * 2048 + k * 1024); } while (0)
; #define PG8_MMA(ai, bj, At, Bt) do { __builtin_amdgcn_s_setprio(1); _Pragma("unroll") for (int m = 0; m < 4; ++m) _Pragma("unroll") for (int n = 0; n < 2; ++n) _Pragma("unroll") for (int k = 0; k < 2; ++k) \
;         acc[ai][bj][m][n] = __builtin_amdgcn_mfma_f32_16x16x32_bf16(Bt[n][k], At[m][k], acc[ai][bj][m][n], 0, 0, 0); __builtin_amdgcn_s_setprio(0); } while (0)
; #define PG8_WAIT_V(n) asm volatile("s_waitcnt vmcnt(" #n ")" ::: "memory")
; #define PG8_WAIT_L(n) asm volatile("s_waitcnt lgkmcnt(" #n ")" ::: "memory")
; #define PG8_BAR __builtin_amdgcn_s_barrier()
; #define PG8_SCHED __builtin_amdgcn_sched_barrier(0)
; template <class Epi, class Sched, bool ALIGN_EPI = false, bool SP2 = false>
; __device__ __forceinline__ void gemm_phase(PG8_LAS unsigned char* lds, const Gemm g, const Sched& S, const Epi& E) {
;     ...
;             PG8_WAIT_V(8); PG8_WAIT_L(0); PG8_BAR; PG8_MMA(0, 0, At, B0); PG8_MMA(0, 1, At, B1); PG8_BAR; PG8_SCHED;
;             PG8_LDA(At, 1, 1); PG8_STAGE(PG8_SB(1, 0), b3, voffB); PG8_STAGE(PG8_SB(1, 1), b3 + hstepB, voffB); PG8_STAGE(PG8_SA(1, 0), a3, voffA);
;             PG8_WAIT_V(8); PG8_WAIT_L(0); PG8_BAR; PG8_MMA(1, 0, At, B0); PG8_MMA(1, 1, At, B1); PG8_BAR; PG8_SCHED;
;     ...
;         }
;         if constexpr (ALIGN_EPI) { if (wr == 0) PG8_BAR; }
	s_add_i32 s24, s26, s39
	v_lshl_add_u64 v[214:215], v[214:215], 0, s[10:11]
	s_mov_b32 m0, s24
	ds_read_b128 v[210:213], v175 offset:49152
	ds_read_b128 v[218:221], v175 offset:50176
	ds_read_b128 v[222:225], v175 offset:51200
	ds_read_b128 v[226:229], v175 offset:52224
	ds_read_b128 v[230:233], v175 offset:53248
	ds_read_b128 v[234:237], v175 offset:54272
	ds_read_b128 v[238:241], v175 offset:55296
	ds_read_b128 v[242:245], v175 offset:56320
	global_load_lds_dwordx4 v[214:215], off
	s_add_i32 m0, s24, 0x2000
	s_add_u32 s22, s22, 0x100080
	v_lshl_add_u64 v[214:215], v[246:247], 0, s[10:11]
	s_addc_u32 s23, s23, 0
	s_add_i32 s24, s27, s39
	global_load_lds_dwordx4 v[214:215], off
	v_lshl_add_u64 v[214:215], s[22:23], 0, v[130:131]
	s_mov_b32 m0, s24
	s_nop 0
	global_load_lds_dwordx4 v[214:215], off
	v_lshl_add_u64 v[214:215], s[22:23], 0, v[136:137]
	s_add_i32 m0, s24, 0x2000
	s_nop 0
	global_load_lds_dwordx4 v[214:215], off
	v_lshl_add_u64 v[214:215], v[248:249], 0, s[10:11]
	s_mov_b32 m0, s43
	s_nop 0
	global_load_lds_dwordx4 v[214:215], off
	s_waitcnt vmcnt(7)
	s_waitcnt lgkmcnt(0)
	s_barrier
	s_setprio 1
	s_waitcnt lgkmcnt(0)
	v_mfma_f32_16x16x32_bf16 v[62:65], v[178:181], v[210:213], v[62:65]
	v_mfma_f32_16x16x32_bf16 v[58:61], v[186:189], v[210:213], v[58:61]
	v_mfma_f32_16x16x32_bf16 v[50:53], v[178:181], v[222:225], v[50:53]
	v_mfma_f32_16x16x32_bf16 v[42:45], v[186:189], v[222:225], v[42:45]
	v_mfma_f32_16x16x32_bf16 v[34:37], v[178:181], v[230:233], v[34:37]
	v_mfma_f32_16x16x32_bf16 v[26:29], v[186:189], v[230:233], v[26:29]
	v_mfma_f32_16x16x32_bf16 v[18:21], v[178:181], v[238:241], v[18:21]
	v_mfma_f32_16x16x32_bf16 v[10:13], v[186:189], v[238:241], v[10:13]
	v_mfma_f32_16x16x32_bf16 v[62:65], v[182:185], v[218:221], v[62:65]
	v_mfma_f32_16x16x32_bf16 v[58:61], v[190:193], v[218:221], v[58:61]
	v_mfma_f32_16x16x32_bf16 v[50:53], v[182:185], v[226:229], v[50:53]
	v_mfma_f32_16x16x32_bf16 v[42:45], v[190:193], v[226:229], v[42:45]
	v_mfma_f32_16x16x32_bf16 v[34:37], v[182:185], v[234:237], v[34:37]
	v_mfma_f32_16x16x32_bf16 v[26:29], v[190:193], v[234:237], v[26:29]
	v_mfma_f32_16x16x32_bf16 v[18:21], v[182:185], v[242:245], v[18:21]
	v_mfma_f32_16x16x32_bf16 v[10:13], v[190:193], v[242:245], v[10:13]
	s_setprio 0
	s_setprio 1
	v_mfma_f32_16x16x32_bf16 v[54:57], v[194:197], v[210:213], v[54:57]
	v_mfma_f32_16x16x32_bf16 v[46:49], v[202:205], v[210:213], v[46:49]
	v_mfma_f32_16x16x32_bf16 v[38:41], v[194:197], v[222:225], v[38:41]
	v_mfma_f32_16x16x32_bf16 v[30:33], v[202:205], v[222:225], v[30:33]
	v_mfma_f32_16x16x32_bf16 v[22:25], v[194:197], v[230:233], v[22:25]
	v_mfma_f32_16x16x32_bf16 v[14:17], v[202:205], v[230:233], v[14:17]
	v_mfma_f32_16x16x32_bf16 v[6:9], v[194:197], v[238:241], v[6:9]
	v_mfma_f32_16x16x32_bf16 v[2:5], v[202:205], v[238:241], v[2:5]
	v_mfma_f32_16x16x32_bf16 v[54:57], v[198:201], v[218:221], v[54:57]
	v_mfma_f32_16x16x32_bf16 v[46:49], v[206:209], v[218:221], v[46:49]
	v_mfma_f32_16x16x32_bf16 v[38:41], v[198:201], v[226:229], v[38:41]
	v_mfma_f32_16x16x32_bf16 v[30:33], v[206:209], v[226:229], v[30:33]
	v_mfma_f32_16x16x32_bf16 v[22:25], v[198:201], v[234:237], v[22:25]
	v_mfma_f32_16x16x32_bf16 v[14:17], v[206:209], v[234:237], v[14:17]
	v_mfma_f32_16x16x32_bf16 v[6:9], v[198:201], v[242:245], v[6:9]
	v_mfma_f32_16x16x32_bf16 v[2:5], v[206:209], v[242:245], v[2:5]
	s_setprio 0
	s_barrier
	v_lshl_add_u64 v[214:215], v[250:251], 0, s[10:11]
	s_mov_b32 m0, s44
	s_nop 0
	global_load_lds_dwordx4 v[214:215], off
	s_add_i32 s22, s54, 2
	s_cmp_gt_u32 s54, 61
	s_mov_b32 s54, s22
	s_cbranch_scc1 .LBB0_255

; #define PG8_STAGE(bufoff, gbase, voff) do { _Pragma("unroll") for (int _i = 0; _i < 2; ++_i) \
;         __builtin_amdgcn_global_load_lds((const unsigned*)((const char*)(gbase) + (voff)[_i]), (PG8_LAS unsigned*)(lds + (bufoff) + ldsw + _i * 8192), 16, 0, 0); } while (0)
; #define PG8_LDA(dst, b, h) do { _Pragma("unroll") for (int m = 0; m < 4; ++m) _Pragma("unroll") for (int k = 0; k < 2; ++k) dst[m][k] = *(const PG8_LAS bf16x8*)(lds + PG8_SA(b, h) + aoff + m * 2048 + k * 1024); } while (0)
; #define PG8_LDB(dst, b, h) do { _Pragma("unroll") for (int n = 0; n < 2; ++n) _Pragma("unroll") for (int k = 0; k < 2; ++k) dst[n][k] = *(const PG8_LAS bf16x8*)(lds + PG8_SB(b, h) + boff + n * 2048 + k * 1024); } while (0)
; #define PG8_MMA(ai, bj, At, Bt) do { __builtin_amdgcn_s_setprio(1); _Pragma("unroll") for (int m = 0; m < 4; ++m) _Pragma("unroll") for (int n = 0; n < 2; ++n) _Pragma("unroll") for (int k = 0; k < 2; ++k) \
;         acc[ai][bj][m][n] = __builtin_amdgcn_mfma_f32_16x16x32_bf16(Bt[n][k], At[m][k], acc[ai][bj][m][n], 0, 0, 0); __builtin_amdgcn_s_setprio(0); } while (0)
; #define PG8_WAIT_V(n) asm volatile("s_waitcnt vmcnt(" #n ")" ::: "memory")
; #define PG8_BAR __builtin_amdgcn_s_barrier()
; template <class Epi, class Sched, bool ALIGN_EPI = false, bool SP2 = false>
; __device__ __forceinline__ void gemm_phase(PG8_LAS unsigned char* lds, const Gemm g, const Sched& S, const Epi& E) {
;     ...
;         for (int t = 0; t < nt; t += 2) {
;             const bool last = (t == nt - 2);
;             const char* a1 = cA + (size_t)(t + 1) * kstep;
;             const char* a2 = last ? nA : cA + (size_t)(t + 2) * kstep; const char* b2 = last ? nB : cB + (size_t)(t + 2) * kstep;
;             const char* a3 = a2 + kstep; const char* b3 = b2 + kstep;
;             if (last && has_next) S.a_ready(nxt);
;             if constexpr (SP2) {
;             PG8_LDB(B0, 0, 0); PG8_LDB(B1, 0, 1); PG8_SCHED; PG8_LDA(At, 0, 0); PG8_STAGE(PG8_SA(1, 1), a1 + hstepA, voffA);
;             PG8_WAIT_V(8); PG8_WAIT_L(0); PG8_BAR; PG8_MMA(0, 0, At, B0); PG8_MMA(0, 1, At, B1); PG8_BAR; PG8_SCHED;
;             PG8_LDA(At, 0, 1); PG8_STAGE(PG8_SB(0, 0), b2, voffB); PG8_STAGE(PG8_SB(0, 1), b2 + hstepB, voffB); PG8_STAGE(PG8_SA(0, 0), a2, voffA);
;             PG8_WAIT_V(8); PG8_WAIT_L(0); PG8_BAR; PG8_MMA(1, 0, At, B0); PG8_MMA(1, 1, At, B1); PG8_BAR; PG8_SCHED;
.LBB0_443:
	ds_read_b128 v[146:149], v155
	ds_read_b128 v[158:161], v155 offset:1024
	ds_read_b128 v[162:165], v155 offset:2048
	ds_read_b128 v[166:169], v155 offset:3072
	ds_read_b128 v[174:177], v156
	ds_read_b128 v[178:181], v156 offset:1024
	ds_read_b128 v[182:185], v156 offset:2048
	ds_read_b128 v[186:189], v156 offset:3072
	s_add_u32 s28, s26, 0xfff00080
	s_addc_u32 s29, s27, -1
	s_cmp_eq_u32 s53, 60
	s_cselect_b32 s31, s17, s29
	s_cselect_b32 s30, s49, s28
	s_cselect_b32 s29, s19, s52
	s_cselect_b32 s28, s50, s51
	v_lshl_add_u64 v[170:171], s[26:27], 0, v[138:139]
	s_add_i32 m0, s25, 0xc000
	ds_read_b128 v[190:193], v157
	ds_read_b128 v[194:197], v157 offset:1024
	ds_read_b128 v[198:201], v157 offset:2048
	ds_read_b128 v[202:205], v157 offset:3072
	ds_read_b128 v[206:209], v157 offset:4096
	ds_read_b128 v[210:213], v157 offset:5120
	ds_read_b128 v[218:221], v157 offset:6144
	ds_read_b128 v[222:225], v157 offset:7168
	global_load_lds_dwordx4 v[170:171], off
	v_lshl_add_u64 v[170:171], s[26:27], 0, v[140:141]
	s_add_i32 m0, s25, 0xe000
	s_nop 0
	global_load_lds_dwordx4 v[170:171], off
	s_waitcnt vmcnt(8)
	s_waitcnt lgkmcnt(0)
	s_barrier
	s_setprio 1
	s_waitcnt lgkmcnt(0)
	v_mfma_f32_16x16x32_bf16 v[126:129], v[146:149], v[190:193], v[126:129]
	v_mfma_f32_16x16x32_bf16 v[122:125], v[162:165], v[190:193], v[122:125]
	v_mfma_f32_16x16x32_bf16 v[118:121], v[146:149], v[198:201], v[118:121]
	v_mfma_f32_16x16x32_bf16 v[114:117], v[162:165], v[198:201], v[114:117]
	v_mfma_f32_16x16x32_bf16 v[106:109], v[146:149], v[206:209], v[106:109]
	v_mfma_f32_16x16x32_bf16 v[98:101], v[162:165], v[206:209], v[98:101]
	v_mfma_f32_16x16x32_bf16 v[78:81], v[146:149], v[218:221], v[78:81]
	v_mfma_f32_16x16x32_bf16 v[74:77], v[162:165], v[218:221], v[74:77]
	v_mfma_f32_16x16x32_bf16 v[126:129], v[158:161], v[194:197], v[126:129]
	v_mfma_f32_16x16x32_bf16 v[122:125], v[166:169], v[194:197], v[122:125]
	v_mfma_f32_16x16x32_bf16 v[118:121], v[158:161], v[202:205], v[118:121]
	v_mfma_f32_16x16x32_bf16 v[114:117], v[166:169], v[202:205], v[114:117]
	v_mfma_f32_16x16x32_bf16 v[106:109], v[158:161], v[210:213], v[106:109]
	v_mfma_f32_16x16x32_bf16 v[98:101], v[166:169], v[210:213], v[98:101]
	v_mfma_f32_16x16x32_bf16 v[78:81], v[158:161], v[222:225], v[78:81]
	v_mfma_f32_16x16x32_bf16 v[74:77], v[166:169], v[222:225], v[74:77]
	s_setprio 0
	s_setprio 1
	v_mfma_f32_16x16x32_bf16 v[110:113], v[174:177], v[190:193], v[110:113]
	v_mfma_f32_16x16x32_bf16 v[102:105], v[182:185], v[190:193], v[102:105]
	v_mfma_f32_16x16x32_bf16 v[94:97], v[174:177], v[198:201], v[94:97]
	v_mfma_f32_16x16x32_bf16 v[90:93], v[182:185], v[198:201], v[90:93]
	v_mfma_f32_16x16x32_bf16 v[86:89], v[174:177], v[206:209], v[86:89]
	v_mfma_f32_16x16x32_bf16 v[82:85], v[182:185], v[206:209], v[82:85]
	v_mfma_f32_16x16x32_bf16 v[70:73], v[174:177], v[218:221], v[70:73]
	v_mfma_f32_16x16x32_bf16 v[66:69], v[182:185], v[218:221], v[66:69]
	v_mfma_f32_16x16x32_bf16 v[110:113], v[178:181], v[194:197], v[110:113]
	v_mfma_f32_16x16x32_bf16 v[102:105], v[186:189], v[194:197], v[102:105]
	v_mfma_f32_16x16x32_bf16 v[94:97], v[178:181], v[202:205], v[94:97]
	v_mfma_f32_16x16x32_bf16 v[90:93], v[186:189], v[202:205], v[90:93]
	v_mfma_f32_16x16x32_bf16 v[86:89], v[178:181], v[210:213], v[86:89]
	v_mfma_f32_16x16x32_bf16 v[82:85], v[186:189], v[210:213], v[82:85]
	v_mfma_f32_16x16x32_bf16 v[70:73], v[178:181], v[222:225], v[70:73]
	v_mfma_f32_16x16x32_bf16 v[66:69], v[186:189], v[222:225], v[66:69]
	s_setprio 0
	s_barrier
	s_add_i32 s54, s45, s37
	v_lshl_add_u64 v[170:171], s[28:29], 0, v[134:135]
	s_mov_b32 m0, s54
	ds_read_b128 v[190:193], v157 offset:16384
	ds_read_b128 v[194:197], v157 offset:17408
	ds_read_b128 v[198:201], v157 offset:18432
	ds_read_b128 v[202:205], v157 offset:19456
	ds_read_b128 v[206:209], v157 offset:20480
	ds_read_b128 v[210:213], v157 offset:21504
	ds_read_b128 v[218:221], v157 offset:22528
	ds_read_b128 v[222:225], v157 offset:23552
	global_load_lds_dwordx4 v[170:171], off
	s_add_i32 m0, s54, 0x2000
	s_add_u32 s54, s28, 0x100000
	v_lshl_add_u64 v[214:215], s[28:29], 0, v[130:131]
	s_addc_u32 s55, s29, 0
	s_add_i32 s56, s46, s37
	global_load_lds_dwordx4 v[214:215], off
	v_lshl_add_u64 v[226:227], s[54:55], 0, v[134:135]
	s_mov_b32 m0, s56
	v_lshl_add_u64 v[228:229], s[30:31], 0, v[132:133]
	global_load_lds_dwordx4 v[226:227], off
	v_lshl_add_u64 v[226:227], s[54:55], 0, v[130:131]
	s_add_i32 m0, s56, 0x2000
	s_nop 0
	global_load_lds_dwordx4 v[226:227], off
	v_lshl_add_u64 v[226:227], s[30:31], 0, v[136:137]
	s_mov_b32 m0, s25
	s_nop 0
	global_load_lds_dwordx4 v[226:227], off
	s_waitcnt vmcnt(7)
	s_waitcnt lgkmcnt(0)
	s_barrier
; #define PG8_STAGE(bufoff, gbase, voff) do { _Pragma("unroll") for (int _i = 0; _i < 2; ++_i) \
;         __builtin_amdgcn_global_load_lds((const unsigned*)((const char*)(gbase) + (voff)[_i]), (PG8_LAS unsigned*)(lds + (bufoff) + ldsw + _i * 8192), 16, 0, 0); } while (0)
; #define PG8_LDA(dst, b, h) do { _Pragma("unroll") for (int m = 0; m < 4; ++m) _Pragma("unroll") for (int k = 0; k < 2; ++k) dst[m][k] = *(const PG8_LAS bf16x8*)(lds + PG8_SA(b, h) + aoff + m * 2048 + k * 1024); } while (0)
; #define PG8_LDB(dst, b, h) do { _Pragma("unroll") for (int n = 0; n < 2; ++n) _Pragma("unroll") for (int k = 0; k < 2; ++k) dst[n][k] = *(const PG8_LAS bf16x8*)(lds + PG8_SB(b, h) + boff + n * 2048 + k * 1024); } while (0)
; #define PG8_MMA(ai, bj, At, Bt) do { __builtin_amdgcn_s_setprio(1); _Pragma("unroll") for (int m = 0; m < 4; ++m) _Pragma("unroll") for (int n = 0; n < 2; ++n) _Pragma("unroll") for (int k = 0; k < 2; ++k) \
;         acc[ai][bj][m][n] = __builtin_amdgcn_mfma_f32_16x16x32_bf16(Bt[n][k], At[m][k], acc[ai][bj][m][n], 0, 0, 0); __builtin_amdgcn_s_setprio(0); } while (0)
; #define PG8_WAIT_V(n) asm volatile("s_waitcnt vmcnt(" #n ")" ::: "memory")
; #define PG8_WAIT_L(n) asm volatile("s_waitcnt lgkmcnt(" #n ")" ::: "memory")
; #define PG8_BAR __builtin_amdgcn_s_barrier()
; #define PG8_SCHED __builtin_amdgcn_sched_barrier(0)
; template <class Epi, class Sched, bool ALIGN_EPI = false, bool SP2 = false>
; __device__ __forceinline__ void gemm_phase(PG8_LAS unsigned char* lds, const Gemm g, const Sched& S, const Epi& E) {
;     ...
;             PG8_WAIT_V(8); PG8_WAIT_L(0); PG8_BAR; PG8_MMA(0, 0, At, B0); PG8_MMA(0, 1, At, B1); PG8_BAR; PG8_SCHED;
;             PG8_LDA(At, 0, 1); PG8_STAGE(PG8_SB(0, 0), b2, voffB); PG8_STAGE(PG8_SB(0, 1), b2 + hstepB, voffB); PG8_STAGE(PG8_SA(0, 0), a2, voffA);
;             PG8_WAIT_V(8); PG8_WAIT_L(0); PG8_BAR; PG8_MMA(1, 0, At, B0); PG8_MMA(1, 1, At, B1); PG8_BAR; PG8_SCHED;
;             PG8_LDB(B0, 1, 0); PG8_LDB(B1, 1, 1); PG8_SCHED; PG8_LDA(At, 1, 0); PG8_STAGE(PG8_SA(0, 1), a2 + hstepA, voffA);
;             PG8_WAIT_V(8); PG8_WAIT_L(0); PG8_BAR; PG8_MMA(0, 0, At, B0); PG8_MMA(0, 1, At, B1); PG8_BAR; PG8_SCHED;
	s_setprio 1
	s_waitcnt lgkmcnt(0)
	v_mfma_f32_16x16x32_bf16 v[62:65], v[146:149], v[190:193], v[62:65]
	v_mfma_f32_16x16x32_bf16 v[58:61], v[162:165], v[190:193], v[58:61]
	v_mfma_f32_16x16x32_bf16 v[50:53], v[146:149], v[198:201], v[50:53]
	v_mfma_f32_16x16x32_bf16 v[42:45], v[162:165], v[198:201], v[42:45]
	v_mfma_f32_16x16x32_bf16 v[34:37], v[146:149], v[206:209], v[34:37]
	v_mfma_f32_16x16x32_bf16 v[26:29], v[162:165], v[206:209], v[26:29]
	v_mfma_f32_16x16x32_bf16 v[18:21], v[146:149], v[218:221], v[18:21]
	v_mfma_f32_16x16x32_bf16 v[10:13], v[162:165], v[218:221], v[10:13]
	v_mfma_f32_16x16x32_bf16 v[62:65], v[158:161], v[194:197], v[62:65]
	v_mfma_f32_16x16x32_bf16 v[58:61], v[166:169], v[194:197], v[58:61]
	v_mfma_f32_16x16x32_bf16 v[50:53], v[158:161], v[202:205], v[50:53]
	v_mfma_f32_16x16x32_bf16 v[42:45], v[166:169], v[202:205], v[42:45]
	v_mfma_f32_16x16x32_bf16 v[34:37], v[158:161], v[210:213], v[34:37]
	v_mfma_f32_16x16x32_bf16 v[26:29], v[166:169], v[210:213], v[26:29]
	v_mfma_f32_16x16x32_bf16 v[18:21], v[158:161], v[222:225], v[18:21]
	v_mfma_f32_16x16x32_bf16 v[10:13], v[166:169], v[222:225], v[10:13]
	s_setprio 0
	s_setprio 1
	v_mfma_f32_16x16x32_bf16 v[54:57], v[174:177], v[190:193], v[54:57]
	v_mfma_f32_16x16x32_bf16 v[46:49], v[182:185], v[190:193], v[46:49]
	v_mfma_f32_16x16x32_bf16 v[38:41], v[174:177], v[198:201], v[38:41]
	v_mfma_f32_16x16x32_bf16 v[30:33], v[182:185], v[198:201], v[30:33]
	v_mfma_f32_16x16x32_bf16 v[22:25], v[174:177], v[206:209], v[22:25]
	v_mfma_f32_16x16x32_bf16 v[14:17], v[182:185], v[206:209], v[14:17]
	v_mfma_f32_16x16x32_bf16 v[6:9], v[174:177], v[218:221], v[6:9]
	v_mfma_f32_16x16x32_bf16 v[2:5], v[182:185], v[218:221], v[2:5]
	v_mfma_f32_16x16x32_bf16 v[54:57], v[178:181], v[194:197], v[54:57]
	v_mfma_f32_16x16x32_bf16 v[46:49], v[186:189], v[194:197], v[46:49]
	v_mfma_f32_16x16x32_bf16 v[38:41], v[178:181], v[202:205], v[38:41]
	v_mfma_f32_16x16x32_bf16 v[30:33], v[186:189], v[202:205], v[30:33]
	v_mfma_f32_16x16x32_bf16 v[22:25], v[178:181], v[210:213], v[22:25]
	v_mfma_f32_16x16x32_bf16 v[14:17], v[186:189], v[210:213], v[14:17]
	v_mfma_f32_16x16x32_bf16 v[6:9], v[178:181], v[222:225], v[6:9]
	v_mfma_f32_16x16x32_bf16 v[2:5], v[186:189], v[222:225], v[2:5]
	s_setprio 0
	s_barrier
	s_mov_b32 m0, s40
	s_nop 0
	global_load_lds_dwordx4 v[228:229], off
	s_add_i32 s54, 0, 0x18000
	v_add_u32_e32 v150, s54, v151
	s_add_i32 s55, 0, 0x1c000
	ds_read_b128 v[146:149], v150
	ds_read_b128 v[158:161], v150 offset:1024
	ds_read_b128 v[162:165], v150 offset:2048
	ds_read_b128 v[166:169], v150 offset:3072
	v_add_u32_e32 v150, s55, v151
	ds_read_b128 v[174:177], v150
	ds_read_b128 v[178:181], v150 offset:1024
	ds_read_b128 v[182:185], v150 offset:2048
	ds_read_b128 v[186:189], v150 offset:3072
	s_add_u32 s30, s30, 0x100000
	s_addc_u32 s31, s31, 0
	s_mov_b32 m0, s41
	v_lshl_add_u64 v[230:231], s[30:31], 0, v[136:137]
	ds_read_b128 v[190:193], v157 offset:32768
	ds_read_b128 v[194:197], v157 offset:33792
	ds_read_b128 v[198:201], v157 offset:34816
	ds_read_b128 v[202:205], v157 offset:35840
	ds_read_b128 v[206:209], v157 offset:36864
	ds_read_b128 v[210:213], v157 offset:37888
	ds_read_b128 v[218:221], v157 offset:38912
	ds_read_b128 v[222:225], v157 offset:39936
	global_load_lds_dwordx4 v[230:231], off
	v_lshl_add_u64 v[230:231], s[30:31], 0, v[132:133]
	s_mov_b32 m0, s42
	s_nop 0
	global_load_lds_dwordx4 v[230:231], off
	s_waitcnt vmcnt(8)
	s_waitcnt lgkmcnt(0)
	s_barrier
	s_setprio 1
	s_waitcnt lgkmcnt(0)
	v_mfma_f32_16x16x32_bf16 v[126:129], v[146:149], v[190:193], v[126:129]
	v_mfma_f32_16x16x32_bf16 v[122:125], v[162:165], v[190:193], v[122:125]
	v_mfma_f32_16x16x32_bf16 v[118:121], v[146:149], v[198:201], v[118:121]
	v_mfma_f32_16x16x32_bf16 v[114:117], v[162:165], v[198:201], v[114:117]
	v_mfma_f32_16x16x32_bf16 v[106:109], v[146:149], v[206:209], v[106:109]
	v_mfma_f32_16x16x32_bf16 v[98:101], v[162:165], v[206:209], v[98:101]
	v_mfma_f32_16x16x32_bf16 v[78:81], v[146:149], v[218:221], v[78:81]
	v_mfma_f32_16x16x32_bf16 v[74:77], v[162:165], v[218:221], v[74:77]
	v_mfma_f32_16x16x32_bf16 v[126:129], v[158:161], v[194:197], v[126:129]
	v_mfma_f32_16x16x32_bf16 v[122:125], v[166:169], v[194:197], v[122:125]
	v_mfma_f32_16x16x32_bf16 v[118:121], v[158:161], v[202:205], v[118:121]
	v_mfma_f32_16x16x32_bf16 v[114:117], v[166:169], v[202:205], v[114:117]
	v_mfma_f32_16x16x32_bf16 v[106:109], v[158:161], v[210:213], v[106:109]
	v_mfma_f32_16x16x32_bf16 v[98:101], v[166:169], v[210:213], v[98:101]
	v_mfma_f32_16x16x32_bf16 v[78:81], v[158:161], v[222:225], v[78:81]
	v_mfma_f32_16x16x32_bf16 v[74:77], v[166:169], v[222:225], v[74:77]
	s_setprio 0
	s_setprio 1
	v_mfma_f32_16x16x32_bf16 v[110:113], v[174:177], v[190:193], v[110:113]
	v_mfma_f32_16x16x32_bf16 v[102:105], v[182:185], v[190:193], v[102:105]
	v_mfma_f32_16x16x32_bf16 v[94:97], v[174:177], v[198:201], v[94:97]
	v_mfma_f32_16x16x32_bf16 v[90:93], v[182:185], v[198:201], v[90:93]
	v_mfma_f32_16x16x32_bf16 v[86:89], v[174:177], v[206:209], v[86:89]
	v_mfma_f32_16x16x32_bf16 v[82:85], v[182:185], v[206:209], v[82:85]
	v_mfma_f32_16x16x32_bf16 v[70:73], v[174:177], v[218:221], v[70:73]
	v_mfma_f32_16x16x32_bf16 v[66:69], v[182:185], v[218:221], v[66:69]
	v_mfma_f32_16x16x32_bf16 v[110:113], v[178:181], v[194:197], v[110:113]
	v_mfma_f32_16x16x32_bf16 v[102:105], v[186:189], v[194:197], v[102:105]
	v_mfma_f32_16x16x32_bf16 v[94:97], v[178:181], v[202:205], v[94:97]
	v_mfma_f32_16x16x32_bf16 v[90:93], v[186:189], v[202:205], v[90:93]
	v_mfma_f32_16x16x32_bf16 v[86:89], v[178:181], v[210:213], v[86:89]
	v_mfma_f32_16x16x32_bf16 v[82:85], v[186:189], v[210:213], v[82:85]
	v_mfma_f32_16x16x32_bf16 v[70:73], v[178:181], v[222:225], v[70:73]
	v_mfma_f32_16x16x32_bf16 v[66:69], v[186:189], v[222:225], v[66:69]
	s_setprio 0
	s_barrier
; #define PG8_STAGE(bufoff, gbase, voff) do { _Pragma("unroll") for (int _i = 0; _i < 2; ++_i) \
;         __builtin_amdgcn_global_load_lds((const unsigned*)((const char*)(gbase) + (voff)[_i]), (PG8_LAS unsigned*)(lds + (bufoff) + ldsw + _i * 8192), 16, 0, 0); } while (0)
; #define PG8_LDA(dst, b, h) do { _Pragma("unroll") for (int m = 0; m < 4; ++m) _Pragma("unroll") for (int k = 0; k < 2; ++k) dst[m][k] = *(const PG8_LAS bf16x8*)(lds + PG8_SA(b, h) + aoff + m * 2048 + k * 1024); } while (0)
; #define PG8_MMA(ai, bj, At, Bt) do { __builtin_amdgcn_s_setprio(1); _Pragma("unroll") for (int m = 0; m < 4; ++m) _Pragma("unroll") for (int n = 0; n < 2; ++n) _Pragma("unroll") for (int k = 0; k < 2; ++k) \
;         acc[ai][bj][m][n] = __builtin_amdgcn_mfma_f32_16x16x32_bf16(Bt[n][k], At[m][k], acc[ai][bj][m][n], 0, 0, 0); __builtin_amdgcn_s_setprio(0); } while (0)
; #define PG8_WAIT_V(n) asm volatile("s_waitcnt vmcnt(" #n ")" ::: "memory")
; #define PG8_WAIT_L(n) asm volatile("s_waitcnt lgkmcnt(" #n ")" ::: "memory")
; #define PG8_BAR __builtin_amdgcn_s_barrier()
; #define PG8_SCHED __builtin_amdgcn_sched_barrier(0)
; template <class Epi, class Sched, bool ALIGN_EPI = false, bool SP2 = false>
; __device__ __forceinline__ void gemm_phase(PG8_LAS unsigned char* lds, const Gemm g, const Sched& S, const Epi& E) {
;     ...
;             PG8_WAIT_V(8); PG8_WAIT_L(0); PG8_BAR; PG8_MMA(0, 0, At, B0); PG8_MMA(0, 1, At, B1); PG8_BAR; PG8_SCHED;
;             PG8_LDA(At, 1, 1); PG8_STAGE(PG8_SB(1, 0), b3, voffB); PG8_STAGE(PG8_SB(1, 1), b3 + hstepB, voffB); PG8_STAGE(PG8_SA(1, 0), a3, voffA);
;             PG8_WAIT_V(8); PG8_WAIT_L(0); PG8_BAR; PG8_MMA(1, 0, At, B0); PG8_MMA(1, 1, At, B1); PG8_BAR; PG8_SCHED;
;     ...
;         }
;         if constexpr (ALIGN_EPI) { if (wr == 0) PG8_BAR; }
	s_add_i32 s30, s54, s37
	v_lshl_add_u64 v[170:171], v[170:171], 0, s[12:13]
	s_mov_b32 m0, s30
	ds_read_b128 v[190:193], v157 offset:49152
	ds_read_b128 v[194:197], v157 offset:50176
	ds_read_b128 v[198:201], v157 offset:51200
	ds_read_b128 v[202:205], v157 offset:52224
	ds_read_b128 v[206:209], v157 offset:53248
	ds_read_b128 v[210:213], v157 offset:54272
	ds_read_b128 v[218:221], v157 offset:55296
	ds_read_b128 v[222:225], v157 offset:56320
	global_load_lds_dwordx4 v[170:171], off
	s_add_i32 m0, s30, 0x2000
	s_add_u32 s28, s28, 0x100080
	v_lshl_add_u64 v[170:171], v[214:215], 0, s[12:13]
	s_addc_u32 s29, s29, 0
	s_add_i32 s30, s55, s37
	global_load_lds_dwordx4 v[170:171], off
	v_lshl_add_u64 v[170:171], s[28:29], 0, v[134:135]
	s_mov_b32 m0, s30
	s_nop 0
	global_load_lds_dwordx4 v[170:171], off
	v_lshl_add_u64 v[170:171], s[28:29], 0, v[130:131]
	s_add_i32 m0, s30, 0x2000
	s_nop 0
	global_load_lds_dwordx4 v[170:171], off
	v_lshl_add_u64 v[170:171], v[226:227], 0, s[12:13]
	s_mov_b32 m0, s43
	s_nop 0
	global_load_lds_dwordx4 v[170:171], off
	s_waitcnt vmcnt(7)
	s_waitcnt lgkmcnt(0)
	s_barrier
	s_setprio 1
	s_waitcnt lgkmcnt(0)
	v_mfma_f32_16x16x32_bf16 v[62:65], v[146:149], v[190:193], v[62:65]
	v_mfma_f32_16x16x32_bf16 v[58:61], v[162:165], v[190:193], v[58:61]
	v_mfma_f32_16x16x32_bf16 v[50:53], v[146:149], v[198:201], v[50:53]
	v_mfma_f32_16x16x32_bf16 v[42:45], v[162:165], v[198:201], v[42:45]
	v_mfma_f32_16x16x32_bf16 v[34:37], v[146:149], v[206:209], v[34:37]
	v_mfma_f32_16x16x32_bf16 v[26:29], v[162:165], v[206:209], v[26:29]
	v_mfma_f32_16x16x32_bf16 v[18:21], v[146:149], v[218:221], v[18:21]
	v_mfma_f32_16x16x32_bf16 v[10:13], v[162:165], v[218:221], v[10:13]
	v_mfma_f32_16x16x32_bf16 v[62:65], v[158:161], v[194:197], v[62:65]
	v_mfma_f32_16x16x32_bf16 v[58:61], v[166:169], v[194:197], v[58:61]
	v_mfma_f32_16x16x32_bf16 v[50:53], v[158:161], v[202:205], v[50:53]
	v_mfma_f32_16x16x32_bf16 v[42:45], v[166:169], v[202:205], v[42:45]
	v_mfma_f32_16x16x32_bf16 v[34:37], v[158:161], v[210:213], v[34:37]
	v_mfma_f32_16x16x32_bf16 v[26:29], v[166:169], v[210:213], v[26:29]
	v_mfma_f32_16x16x32_bf16 v[18:21], v[158:161], v[222:225], v[18:21]
	v_mfma_f32_16x16x32_bf16 v[10:13], v[166:169], v[222:225], v[10:13]
	s_setprio 0
	s_setprio 1
	v_mfma_f32_16x16x32_bf16 v[54:57], v[174:177], v[190:193], v[54:57]
	v_mfma_f32_16x16x32_bf16 v[46:49], v[182:185], v[190:193], v[46:49]
	v_mfma_f32_16x16x32_bf16 v[38:41], v[174:177], v[198:201], v[38:41]
	v_mfma_f32_16x16x32_bf16 v[30:33], v[182:185], v[198:201], v[30:33]
	v_mfma_f32_16x16x32_bf16 v[22:25], v[174:177], v[206:209], v[22:25]
	v_mfma_f32_16x16x32_bf16 v[14:17], v[182:185], v[206:209], v[14:17]
	v_mfma_f32_16x16x32_bf16 v[6:9], v[174:177], v[218:221], v[6:9]
	v_mfma_f32_16x16x32_bf16 v[2:5], v[182:185], v[218:221], v[2:5]
	v_mfma_f32_16x16x32_bf16 v[54:57], v[178:181], v[194:197], v[54:57]
	v_mfma_f32_16x16x32_bf16 v[46:49], v[186:189], v[194:197], v[46:49]
	v_mfma_f32_16x16x32_bf16 v[38:41], v[178:181], v[202:205], v[38:41]
	v_mfma_f32_16x16x32_bf16 v[30:33], v[186:189], v[202:205], v[30:33]
	v_mfma_f32_16x16x32_bf16 v[22:25], v[178:181], v[210:213], v[22:25]
	v_mfma_f32_16x16x32_bf16 v[14:17], v[186:189], v[210:213], v[14:17]
	v_mfma_f32_16x16x32_bf16 v[6:9], v[178:181], v[222:225], v[6:9]
	v_mfma_f32_16x16x32_bf16 v[2:5], v[186:189], v[222:225], v[2:5]
	s_setprio 0
	s_barrier
	v_lshl_add_u64 v[170:171], v[228:229], 0, s[12:13]
	s_mov_b32 m0, s44
	s_nop 0
	global_load_lds_dwordx4 v[170:171], off
	s_add_i32 s53, s53, 2
	s_add_u32 s26, s26, 0x100
	s_addc_u32 s27, s27, 0
	s_add_u32 s51, s51, 0x100
	s_addc_u32 s52, s52, 0
	s_cmp_gt_u32 s53, 61
	s_cbranch_scc0 .LBB0_443
	s_and_b64 vcc, exec, s[14:15]
	s_cbranch_vccz .LBB0_446
	s_barrier

; #define PG8_STAGE(bufoff, gbase, voff) do { _Pragma("unroll") for (int _i = 0; _i < 2; ++_i) \
;         __builtin_amdgcn_global_load_lds((const unsigned*)((const char*)(gbase) + (voff)[_i]), (PG8_LAS unsigned*)(lds + (bufoff) + ldsw + _i * 8192), 16, 0, 0); } while (0)
; #define PG8_LDA(dst, b, h) do { _Pragma("unroll") for (int m = 0; m < 4; ++m) _Pragma("unroll") for (int k = 0; k < 2; ++k) dst[m][k] = *(const PG8_LAS bf16x8*)(lds + PG8_SA(b, h) + aoff + m * 2048 + k * 1024); } while (0)
; #define PG8_LDB(dst, b, h) do { _Pragma("unroll") for (int n = 0; n < 2; ++n) _Pragma("unroll") for (int k = 0; k < 2; ++k) dst[n][k] = *(const PG8_LAS bf16x8*)(lds + PG8_SB(b, h) + boff + n * 2048 + k * 1024); } while (0)
; #define PG8_MMA(ai, bj, At, Bt) do { __builtin_amdgcn_s_setprio(1); _Pragma("unroll") for (int m = 0; m < 4; ++m) _Pragma("unroll") for (int n = 0; n < 2; ++n) _Pragma("unroll") for (int k = 0; k < 2; ++k) \
;         acc[ai][bj][m][n] = __builtin_amdgcn_mfma_f32_16x16x32_bf16(Bt[n][k], At[m][k], acc[ai][bj][m][n], 0, 0, 0); __builtin_amdgcn_s_setprio(0); } while (0)
; #define PG8_WAIT_V(n) asm volatile("s_waitcnt vmcnt(" #n ")" ::: "memory")
; #define PG8_BAR __builtin_amdgcn_s_barrier()
; template <class Epi, class Sched, bool ALIGN_EPI = false, bool SP2 = false>
; __device__ __forceinline__ void gemm_phase(PG8_LAS unsigned char* lds, const Gemm g, const Sched& S, const Epi& E) {
;     ...
;         for (int t = 0; t < nt; t += 2) {
;             const bool last = (t == nt - 2);
;             const char* a1 = cA + (size_t)(t + 1) * kstep;
;             const char* a2 = last ? nA : cA + (size_t)(t + 2) * kstep; const char* b2 = last ? nB : cB + (size_t)(t + 2) * kstep;
;             const char* a3 = a2 + kstep; const char* b3 = b2 + kstep;
;             if (last && has_next) S.a_ready(nxt);
;             if constexpr (SP2) {
;             PG8_LDB(B0, 0, 0); PG8_LDB(B1, 0, 1); PG8_SCHED; PG8_LDA(At, 0, 0); PG8_STAGE(PG8_SA(1, 1), a1 + hstepA, voffA);
;             PG8_WAIT_V(8); PG8_WAIT_L(0); PG8_BAR; PG8_MMA(0, 0, At, B0); PG8_MMA(0, 1, At, B1); PG8_BAR; PG8_SCHED;
;             PG8_LDA(At, 0, 1); PG8_STAGE(PG8_SB(0, 0), b2, voffB); PG8_STAGE(PG8_SB(0, 1), b2 + hstepB, voffB); PG8_STAGE(PG8_SA(0, 0), a2, voffA);
;             PG8_WAIT_V(8); PG8_WAIT_L(0); PG8_BAR; PG8_MMA(1, 0, At, B0); PG8_MMA(1, 1, At, B1); PG8_BAR; PG8_SCHED;
.LBB0_966:
	ds_read_b128 v[154:157], v150
	ds_read_b128 v[158:161], v150 offset:1024
	ds_read_b128 v[162:165], v150 offset:2048
	ds_read_b128 v[166:169], v150 offset:3072
	ds_read_b128 v[170:173], v151
	ds_read_b128 v[174:177], v151 offset:1024
	ds_read_b128 v[178:181], v151 offset:2048
	ds_read_b128 v[182:185], v151 offset:3072
	s_add_u32 s34, s30, 0xfff00080
	s_addc_u32 s35, s31, -1
	s_cmp_eq_u32 s61, 60
	s_cselect_b32 s37, s23, s35
	s_cselect_b32 s36, s57, s34
	s_cselect_b32 s35, s21, s60
	s_cselect_b32 s34, s58, s59
	v_lshl_add_u64 v[146:147], s[30:31], 0, v[138:139]
	s_add_i32 m0, s29, 0xc000
	ds_read_b128 v[186:189], v152
	ds_read_b128 v[190:193], v152 offset:1024
	ds_read_b128 v[194:197], v152 offset:2048
	ds_read_b128 v[198:201], v152 offset:3072
	ds_read_b128 v[202:205], v152 offset:4096
	ds_read_b128 v[206:209], v152 offset:5120
	ds_read_b128 v[210:213], v152 offset:6144
	ds_read_b128 v[218:221], v152 offset:7168
	global_load_lds_dwordx4 v[146:147], off
	v_lshl_add_u64 v[146:147], s[30:31], 0, v[140:141]
	s_add_i32 m0, s29, 0xe000
	s_nop 0
	global_load_lds_dwordx4 v[146:147], off
	s_waitcnt vmcnt(8)
	s_waitcnt lgkmcnt(0)
	s_barrier
	s_setprio 1
	s_waitcnt lgkmcnt(0)
	v_mfma_f32_16x16x32_bf16 v[126:129], v[154:157], v[186:189], v[126:129]
	v_mfma_f32_16x16x32_bf16 v[122:125], v[162:165], v[186:189], v[122:125]
	v_mfma_f32_16x16x32_bf16 v[114:117], v[154:157], v[194:197], v[114:117]
	v_mfma_f32_16x16x32_bf16 v[106:109], v[162:165], v[194:197], v[106:109]
	v_mfma_f32_16x16x32_bf16 v[98:101], v[154:157], v[202:205], v[98:101]
	v_mfma_f32_16x16x32_bf16 v[90:93], v[162:165], v[202:205], v[90:93]
	v_mfma_f32_16x16x32_bf16 v[82:85], v[154:157], v[210:213], v[82:85]
	v_mfma_f32_16x16x32_bf16 v[74:77], v[162:165], v[210:213], v[74:77]
	v_mfma_f32_16x16x32_bf16 v[126:129], v[158:161], v[190:193], v[126:129]
	v_mfma_f32_16x16x32_bf16 v[122:125], v[166:169], v[190:193], v[122:125]
	v_mfma_f32_16x16x32_bf16 v[114:117], v[158:161], v[198:201], v[114:117]
	v_mfma_f32_16x16x32_bf16 v[106:109], v[166:169], v[198:201], v[106:109]
	v_mfma_f32_16x16x32_bf16 v[98:101], v[158:161], v[206:209], v[98:101]
	v_mfma_f32_16x16x32_bf16 v[90:93], v[166:169], v[206:209], v[90:93]
	v_mfma_f32_16x16x32_bf16 v[82:85], v[158:161], v[218:221], v[82:85]
	v_mfma_f32_16x16x32_bf16 v[74:77], v[166:169], v[218:221], v[74:77]
	s_setprio 0
	s_setprio 1
	v_mfma_f32_16x16x32_bf16 v[118:121], v[170:173], v[186:189], v[118:121]
	v_mfma_f32_16x16x32_bf16 v[110:113], v[178:181], v[186:189], v[110:113]
	v_mfma_f32_16x16x32_bf16 v[102:105], v[170:173], v[194:197], v[102:105]
	v_mfma_f32_16x16x32_bf16 v[94:97], v[178:181], v[194:197], v[94:97]
	v_mfma_f32_16x16x32_bf16 v[86:89], v[170:173], v[202:205], v[86:89]
	v_mfma_f32_16x16x32_bf16 v[78:81], v[178:181], v[202:205], v[78:81]
	v_mfma_f32_16x16x32_bf16 v[70:73], v[170:173], v[210:213], v[70:73]
	v_mfma_f32_16x16x32_bf16 v[66:69], v[178:181], v[210:213], v[66:69]
	v_mfma_f32_16x16x32_bf16 v[118:121], v[174:177], v[190:193], v[118:121]
	v_mfma_f32_16x16x32_bf16 v[110:113], v[182:185], v[190:193], v[110:113]
	v_mfma_f32_16x16x32_bf16 v[102:105], v[174:177], v[198:201], v[102:105]
	v_mfma_f32_16x16x32_bf16 v[94:97], v[182:185], v[198:201], v[94:97]
	v_mfma_f32_16x16x32_bf16 v[86:89], v[174:177], v[206:209], v[86:89]
	v_mfma_f32_16x16x32_bf16 v[78:81], v[182:185], v[206:209], v[78:81]
	v_mfma_f32_16x16x32_bf16 v[70:73], v[174:177], v[218:221], v[70:73]
	v_mfma_f32_16x16x32_bf16 v[66:69], v[182:185], v[218:221], v[66:69]
	s_setprio 0
	s_barrier
	s_add_i32 s62, s50, s42
	v_lshl_add_u64 v[146:147], s[34:35], 0, v[132:133]
	s_mov_b32 m0, s62
	ds_read_b128 v[186:189], v152 offset:16384
	ds_read_b128 v[190:193], v152 offset:17408
	ds_read_b128 v[194:197], v152 offset:18432
	ds_read_b128 v[198:201], v152 offset:19456
	ds_read_b128 v[202:205], v152 offset:20480
	ds_read_b128 v[206:209], v152 offset:21504
	ds_read_b128 v[210:213], v152 offset:22528
	ds_read_b128 v[218:221], v152 offset:23552
	global_load_lds_dwordx4 v[146:147], off
	s_add_i32 m0, s62, 0x2000
	s_add_u32 s62, s34, 0x100000
	v_lshl_add_u64 v[214:215], s[34:35], 0, v[136:137]
	s_addc_u32 s63, s35, 0
	s_add_i32 s64, s51, s42
	global_load_lds_dwordx4 v[214:215], off
	v_lshl_add_u64 v[222:223], s[62:63], 0, v[132:133]
	s_mov_b32 m0, s64
	v_lshl_add_u64 v[224:225], s[36:37], 0, v[134:135]
	global_load_lds_dwordx4 v[222:223], off
	v_lshl_add_u64 v[222:223], s[62:63], 0, v[136:137]
	s_add_i32 m0, s64, 0x2000
	s_nop 0
	global_load_lds_dwordx4 v[222:223], off
	v_lshl_add_u64 v[222:223], s[36:37], 0, v[130:131]
	s_mov_b32 m0, s29
	s_nop 0
	global_load_lds_dwordx4 v[222:223], off
	s_waitcnt vmcnt(7)
	s_waitcnt lgkmcnt(0)
	s_barrier
; #define PG8_STAGE(bufoff, gbase, voff) do { _Pragma("unroll") for (int _i = 0; _i < 2; ++_i) \
;         __builtin_amdgcn_global_load_lds((const unsigned*)((const char*)(gbase) + (voff)[_i]), (PG8_LAS unsigned*)(lds + (bufoff) + ldsw + _i * 8192), 16, 0, 0); } while (0)
; #define PG8_LDA(dst, b, h) do { _Pragma("unroll") for (int m = 0; m < 4; ++m) _Pragma("unroll") for (int k = 0; k < 2; ++k) dst[m][k] = *(const PG8_LAS bf16x8*)(lds + PG8_SA(b, h) + aoff + m * 2048 + k * 1024); } while (0)
; #define PG8_LDB(dst, b, h) do { _Pragma("unroll") for (int n = 0; n < 2; ++n) _Pragma("unroll") for (int k = 0; k < 2; ++k) dst[n][k] = *(const PG8_LAS bf16x8*)(lds + PG8_SB(b, h) + boff + n * 2048 + k * 1024); } while (0)
; #define PG8_MMA(ai, bj, At, Bt) do { __builtin_amdgcn_s_setprio(1); _Pragma("unroll") for (int m = 0; m < 4; ++m) _Pragma("unroll") for (int n = 0; n < 2; ++n) _Pragma("unroll") for (int k = 0; k < 2; ++k) \
;         acc[ai][bj][m][n] = __builtin_amdgcn_mfma_f32_16x16x32_bf16(Bt[n][k], At[m][k], acc[ai][bj][m][n], 0, 0, 0); __builtin_amdgcn_s_setprio(0); } while (0)
; #define PG8_WAIT_V(n) asm volatile("s_waitcnt vmcnt(" #n ")" ::: "memory")
; #define PG8_WAIT_L(n) asm volatile("s_waitcnt lgkmcnt(" #n ")" ::: "memory")
; #define PG8_BAR __builtin_amdgcn_s_barrier()
; #define PG8_SCHED __builtin_amdgcn_sched_barrier(0)
; template <class Epi, class Sched, bool ALIGN_EPI = false, bool SP2 = false>
; __device__ __forceinline__ void gemm_phase(PG8_LAS unsigned char* lds, const Gemm g, const Sched& S, const Epi& E) {
;     ...
;             PG8_WAIT_V(8); PG8_WAIT_L(0); PG8_BAR; PG8_MMA(0, 0, At, B0); PG8_MMA(0, 1, At, B1); PG8_BAR; PG8_SCHED;
;             PG8_LDA(At, 0, 1); PG8_STAGE(PG8_SB(0, 0), b2, voffB); PG8_STAGE(PG8_SB(0, 1), b2 + hstepB, voffB); PG8_STAGE(PG8_SA(0, 0), a2, voffA);
;             PG8_WAIT_V(8); PG8_WAIT_L(0); PG8_BAR; PG8_MMA(1, 0, At, B0); PG8_MMA(1, 1, At, B1); PG8_BAR; PG8_SCHED;
;             PG8_LDB(B0, 1, 0); PG8_LDB(B1, 1, 1); PG8_SCHED; PG8_LDA(At, 1, 0); PG8_STAGE(PG8_SA(0, 1), a2 + hstepA, voffA);
;             PG8_WAIT_V(8); PG8_WAIT_L(0); PG8_BAR; PG8_MMA(0, 0, At, B0); PG8_MMA(0, 1, At, B1); PG8_BAR; PG8_SCHED;
	s_setprio 1
	s_waitcnt lgkmcnt(0)
	v_mfma_f32_16x16x32_bf16 v[62:65], v[154:157], v[186:189], v[62:65]
	v_mfma_f32_16x16x32_bf16 v[58:61], v[162:165], v[186:189], v[58:61]
	v_mfma_f32_16x16x32_bf16 v[50:53], v[154:157], v[194:197], v[50:53]
	v_mfma_f32_16x16x32_bf16 v[42:45], v[162:165], v[194:197], v[42:45]
	v_mfma_f32_16x16x32_bf16 v[34:37], v[154:157], v[202:205], v[34:37]
	v_mfma_f32_16x16x32_bf16 v[26:29], v[162:165], v[202:205], v[26:29]
	v_mfma_f32_16x16x32_bf16 v[18:21], v[154:157], v[210:213], v[18:21]
	v_mfma_f32_16x16x32_bf16 v[10:13], v[162:165], v[210:213], v[10:13]
	v_mfma_f32_16x16x32_bf16 v[62:65], v[158:161], v[190:193], v[62:65]
	v_mfma_f32_16x16x32_bf16 v[58:61], v[166:169], v[190:193], v[58:61]
	v_mfma_f32_16x16x32_bf16 v[50:53], v[158:161], v[198:201], v[50:53]
	v_mfma_f32_16x16x32_bf16 v[42:45], v[166:169], v[198:201], v[42:45]
	v_mfma_f32_16x16x32_bf16 v[34:37], v[158:161], v[206:209], v[34:37]
	v_mfma_f32_16x16x32_bf16 v[26:29], v[166:169], v[206:209], v[26:29]
	v_mfma_f32_16x16x32_bf16 v[18:21], v[158:161], v[218:221], v[18:21]
	v_mfma_f32_16x16x32_bf16 v[10:13], v[166:169], v[218:221], v[10:13]
	s_setprio 0
	s_setprio 1
	v_mfma_f32_16x16x32_bf16 v[54:57], v[170:173], v[186:189], v[54:57]
	v_mfma_f32_16x16x32_bf16 v[46:49], v[178:181], v[186:189], v[46:49]
	v_mfma_f32_16x16x32_bf16 v[38:41], v[170:173], v[194:197], v[38:41]
	v_mfma_f32_16x16x32_bf16 v[30:33], v[178:181], v[194:197], v[30:33]
	v_mfma_f32_16x16x32_bf16 v[22:25], v[170:173], v[202:205], v[22:25]
	v_mfma_f32_16x16x32_bf16 v[14:17], v[178:181], v[202:205], v[14:17]
	v_mfma_f32_16x16x32_bf16 v[6:9], v[170:173], v[210:213], v[6:9]
	v_mfma_f32_16x16x32_bf16 v[2:5], v[178:181], v[210:213], v[2:5]
	v_mfma_f32_16x16x32_bf16 v[54:57], v[174:177], v[190:193], v[54:57]
	v_mfma_f32_16x16x32_bf16 v[46:49], v[182:185], v[190:193], v[46:49]
	v_mfma_f32_16x16x32_bf16 v[38:41], v[174:177], v[198:201], v[38:41]
	v_mfma_f32_16x16x32_bf16 v[30:33], v[182:185], v[198:201], v[30:33]
	v_mfma_f32_16x16x32_bf16 v[22:25], v[174:177], v[206:209], v[22:25]
	v_mfma_f32_16x16x32_bf16 v[14:17], v[182:185], v[206:209], v[14:17]
	v_mfma_f32_16x16x32_bf16 v[6:9], v[174:177], v[218:221], v[6:9]
	v_mfma_f32_16x16x32_bf16 v[2:5], v[182:185], v[218:221], v[2:5]
	s_setprio 0
	s_barrier
	s_mov_b32 m0, s43
	s_nop 0
	global_load_lds_dwordx4 v[224:225], off
	s_add_i32 s62, 0, 0x18000
	v_add_u32_e32 v153, s62, v148
	s_add_i32 s63, 0, 0x1c000
	ds_read_b128 v[154:157], v153
	ds_read_b128 v[158:161], v153 offset:1024
	ds_read_b128 v[162:165], v153 offset:2048
	ds_read_b128 v[166:169], v153 offset:3072
	v_add_u32_e32 v153, s63, v148
	ds_read_b128 v[170:173], v153
	ds_read_b128 v[174:177], v153 offset:1024
	ds_read_b128 v[178:181], v153 offset:2048
	ds_read_b128 v[182:185], v153 offset:3072
	s_add_u32 s36, s36, 0x100000
	s_addc_u32 s37, s37, 0
	s_mov_b32 m0, s44
	v_lshl_add_u64 v[226:227], s[36:37], 0, v[130:131]
	ds_read_b128 v[186:189], v152 offset:32768
	ds_read_b128 v[190:193], v152 offset:33792
	ds_read_b128 v[194:197], v152 offset:34816
	ds_read_b128 v[198:201], v152 offset:35840
	ds_read_b128 v[202:205], v152 offset:36864
	ds_read_b128 v[206:209], v152 offset:37888
	ds_read_b128 v[210:213], v152 offset:38912
	ds_read_b128 v[218:221], v152 offset:39936
	global_load_lds_dwordx4 v[226:227], off
	v_lshl_add_u64 v[226:227], s[36:37], 0, v[134:135]
	s_mov_b32 m0, s45
	s_nop 0
	global_load_lds_dwordx4 v[226:227], off
	s_waitcnt vmcnt(8)
	s_waitcnt lgkmcnt(0)
	s_barrier
	s_setprio 1
	s_waitcnt lgkmcnt(0)
	v_mfma_f32_16x16x32_bf16 v[126:129], v[154:157], v[186:189], v[126:129]
	v_mfma_f32_16x16x32_bf16 v[122:125], v[162:165], v[186:189], v[122:125]
	v_mfma_f32_16x16x32_bf16 v[114:117], v[154:157], v[194:197], v[114:117]
	v_mfma_f32_16x16x32_bf16 v[106:109], v[162:165], v[194:197], v[106:109]
	v_mfma_f32_16x16x32_bf16 v[98:101], v[154:157], v[202:205], v[98:101]
	v_mfma_f32_16x16x32_bf16 v[90:93], v[162:165], v[202:205], v[90:93]
	v_mfma_f32_16x16x32_bf16 v[82:85], v[154:157], v[210:213], v[82:85]
	v_mfma_f32_16x16x32_bf16 v[74:77], v[162:165], v[210:213], v[74:77]
	v_mfma_f32_16x16x32_bf16 v[126:129], v[158:161], v[190:193], v[126:129]
	v_mfma_f32_16x16x32_bf16 v[122:125], v[166:169], v[190:193], v[122:125]
	v_mfma_f32_16x16x32_bf16 v[114:117], v[158:161], v[198:201], v[114:117]
	v_mfma_f32_16x16x32_bf16 v[106:109], v[166:169], v[198:201], v[106:109]
	v_mfma_f32_16x16x32_bf16 v[98:101], v[158:161], v[206:209], v[98:101]
	v_mfma_f32_16x16x32_bf16 v[90:93], v[166:169], v[206:209], v[90:93]
	v_mfma_f32_16x16x32_bf16 v[82:85], v[158:161], v[218:221], v[82:85]
	v_mfma_f32_16x16x32_bf16 v[74:77], v[166:169], v[218:221], v[74:77]
	s_setprio 0
	s_setprio 1
	v_mfma_f32_16x16x32_bf16 v[118:121], v[170:173], v[186:189], v[118:121]
	v_mfma_f32_16x16x32_bf16 v[110:113], v[178:181], v[186:189], v[110:113]
	v_mfma_f32_16x16x32_bf16 v[102:105], v[170:173], v[194:197], v[102:105]
	v_mfma_f32_16x16x32_bf16 v[94:97], v[178:181], v[194:197], v[94:97]
	v_mfma_f32_16x16x32_bf16 v[86:89], v[170:173], v[202:205], v[86:89]
	v_mfma_f32_16x16x32_bf16 v[78:81], v[178:181], v[202:205], v[78:81]
	v_mfma_f32_16x16x32_bf16 v[70:73], v[170:173], v[210:213], v[70:73]
	v_mfma_f32_16x16x32_bf16 v[66:69], v[178:181], v[210:213], v[66:69]
	v_mfma_f32_16x16x32_bf16 v[118:121], v[174:177], v[190:193], v[118:121]
	v_mfma_f32_16x16x32_bf16 v[110:113], v[182:185], v[190:193], v[110:113]
	v_mfma_f32_16x16x32_bf16 v[102:105], v[174:177], v[198:201], v[102:105]
	v_mfma_f32_16x16x32_bf16 v[94:97], v[182:185], v[198:201], v[94:97]
	v_mfma_f32_16x16x32_bf16 v[86:89], v[174:177], v[206:209], v[86:89]
	v_mfma_f32_16x16x32_bf16 v[78:81], v[182:185], v[206:209], v[78:81]
	v_mfma_f32_16x16x32_bf16 v[70:73], v[174:177], v[218:221], v[70:73]
	v_mfma_f32_16x16x32_bf16 v[66:69], v[182:185], v[218:221], v[66:69]
	s_setprio 0
	s_barrier
; #define PG8_STAGE(bufoff, gbase, voff) do { _Pragma("unroll") for (int _i = 0; _i < 2; ++_i) \
;         __builtin_amdgcn_global_load_lds((const unsigned*)((const char*)(gbase) + (voff)[_i]), (PG8_LAS unsigned*)(lds + (bufoff) + ldsw + _i * 8192), 16, 0, 0); } while (0)
; #define PG8_LDA(dst, b, h) do { _Pragma("unroll") for (int m = 0; m < 4; ++m) _Pragma("unroll") for (int k = 0; k < 2; ++k) dst[m][k] = *(const PG8_LAS bf16x8*)(lds + PG8_SA(b, h) + aoff + m * 2048 + k * 1024); } while (0)
; #define PG8_MMA(ai, bj, At, Bt) do { __builtin_amdgcn_s_setprio(1); _Pragma("unroll") for (int m = 0; m < 4; ++m) _Pragma("unroll") for (int n = 0; n < 2; ++n) _Pragma("unroll") for (int k = 0; k < 2; ++k) \
;         acc[ai][bj][m][n] = __builtin_amdgcn_mfma_f32_16x16x32_bf16(Bt[n][k], At[m][k], acc[ai][bj][m][n], 0, 0, 0); __builtin_amdgcn_s_setprio(0); } while (0)
; #define PG8_WAIT_V(n) asm volatile("s_waitcnt vmcnt(" #n ")" ::: "memory")
; #define PG8_WAIT_L(n) asm volatile("s_waitcnt lgkmcnt(" #n ")" ::: "memory")
; #define PG8_BAR __builtin_amdgcn_s_barrier()
; #define PG8_SCHED __builtin_amdgcn_sched_barrier(0)
; template <class Epi, class Sched, bool ALIGN_EPI = false, bool SP2 = false>
; __device__ __forceinline__ void gemm_phase(PG8_LAS unsigned char* lds, const Gemm g, const Sched& S, const Epi& E) {
;     ...
;             PG8_WAIT_V(8); PG8_WAIT_L(0); PG8_BAR; PG8_MMA(0, 0, At, B0); PG8_MMA(0, 1, At, B1); PG8_BAR; PG8_SCHED;
;             PG8_LDA(At, 1, 1); PG8_STAGE(PG8_SB(1, 0), b3, voffB); PG8_STAGE(PG8_SB(1, 1), b3 + hstepB, voffB); PG8_STAGE(PG8_SA(1, 0), a3, voffA);
;             PG8_WAIT_V(8); PG8_WAIT_L(0); PG8_BAR; PG8_MMA(1, 0, At, B0); PG8_MMA(1, 1, At, B1); PG8_BAR; PG8_SCHED;
;     ...
;         }
;         if constexpr (ALIGN_EPI) { if (wr == 0) PG8_BAR; }
	s_add_i32 s36, s62, s42
	v_lshl_add_u64 v[146:147], v[146:147], 0, s[10:11]
	s_mov_b32 m0, s36
	ds_read_b128 v[186:189], v152 offset:49152
	ds_read_b128 v[190:193], v152 offset:50176
	ds_read_b128 v[194:197], v152 offset:51200
	ds_read_b128 v[198:201], v152 offset:52224
	ds_read_b128 v[202:205], v152 offset:53248
	ds_read_b128 v[206:209], v152 offset:54272
	ds_read_b128 v[210:213], v152 offset:55296
	ds_read_b128 v[218:221], v152 offset:56320
	global_load_lds_dwordx4 v[146:147], off
	s_add_i32 m0, s36, 0x2000
	s_add_u32 s34, s34, 0x100080
	v_lshl_add_u64 v[146:147], v[214:215], 0, s[10:11]
	s_addc_u32 s35, s35, 0
	s_add_i32 s36, s63, s42
	global_load_lds_dwordx4 v[146:147], off
	v_lshl_add_u64 v[146:147], s[34:35], 0, v[132:133]
	s_mov_b32 m0, s36
	s_nop 0
	global_load_lds_dwordx4 v[146:147], off
	v_lshl_add_u64 v[146:147], s[34:35], 0, v[136:137]
	s_add_i32 m0, s36, 0x2000
	s_nop 0
	global_load_lds_dwordx4 v[146:147], off
	v_lshl_add_u64 v[146:147], v[222:223], 0, s[10:11]
	s_mov_b32 m0, s47
	s_nop 0
	global_load_lds_dwordx4 v[146:147], off
	s_waitcnt vmcnt(7)
	s_waitcnt lgkmcnt(0)
	s_barrier
	s_setprio 1
	s_waitcnt lgkmcnt(0)
	v_mfma_f32_16x16x32_bf16 v[62:65], v[154:157], v[186:189], v[62:65]
	v_mfma_f32_16x16x32_bf16 v[58:61], v[162:165], v[186:189], v[58:61]
	v_mfma_f32_16x16x32_bf16 v[50:53], v[154:157], v[194:197], v[50:53]
	v_mfma_f32_16x16x32_bf16 v[42:45], v[162:165], v[194:197], v[42:45]
	v_mfma_f32_16x16x32_bf16 v[34:37], v[154:157], v[202:205], v[34:37]
	v_mfma_f32_16x16x32_bf16 v[26:29], v[162:165], v[202:205], v[26:29]
	v_mfma_f32_16x16x32_bf16 v[18:21], v[154:157], v[210:213], v[18:21]
	v_mfma_f32_16x16x32_bf16 v[10:13], v[162:165], v[210:213], v[10:13]
	v_mfma_f32_16x16x32_bf16 v[62:65], v[158:161], v[190:193], v[62:65]
	v_mfma_f32_16x16x32_bf16 v[58:61], v[166:169], v[190:193], v[58:61]
	v_mfma_f32_16x16x32_bf16 v[50:53], v[158:161], v[198:201], v[50:53]
	v_mfma_f32_16x16x32_bf16 v[42:45], v[166:169], v[198:201], v[42:45]
	v_mfma_f32_16x16x32_bf16 v[34:37], v[158:161], v[206:209], v[34:37]
	v_mfma_f32_16x16x32_bf16 v[26:29], v[166:169], v[206:209], v[26:29]
	v_mfma_f32_16x16x32_bf16 v[18:21], v[158:161], v[218:221], v[18:21]
	v_mfma_f32_16x16x32_bf16 v[10:13], v[166:169], v[218:221], v[10:13]
	s_setprio 0
	s_setprio 1
	v_mfma_f32_16x16x32_bf16 v[54:57], v[170:173], v[186:189], v[54:57]
	v_mfma_f32_16x16x32_bf16 v[46:49], v[178:181], v[186:189], v[46:49]
	v_mfma_f32_16x16x32_bf16 v[38:41], v[170:173], v[194:197], v[38:41]
	v_mfma_f32_16x16x32_bf16 v[30:33], v[178:181], v[194:197], v[30:33]
	v_mfma_f32_16x16x32_bf16 v[22:25], v[170:173], v[202:205], v[22:25]
	v_mfma_f32_16x16x32_bf16 v[14:17], v[178:181], v[202:205], v[14:17]
	v_mfma_f32_16x16x32_bf16 v[6:9], v[170:173], v[210:213], v[6:9]
	v_mfma_f32_16x16x32_bf16 v[2:5], v[178:181], v[210:213], v[2:5]
	v_mfma_f32_16x16x32_bf16 v[54:57], v[174:177], v[190:193], v[54:57]
	v_mfma_f32_16x16x32_bf16 v[46:49], v[182:185], v[190:193], v[46:49]
	v_mfma_f32_16x16x32_bf16 v[38:41], v[174:177], v[198:201], v[38:41]
	v_mfma_f32_16x16x32_bf16 v[30:33], v[182:185], v[198:201], v[30:33]
	v_mfma_f32_16x16x32_bf16 v[22:25], v[174:177], v[206:209], v[22:25]
	v_mfma_f32_16x16x32_bf16 v[14:17], v[182:185], v[206:209], v[14:17]
	v_mfma_f32_16x16x32_bf16 v[6:9], v[174:177], v[218:221], v[6:9]
	v_mfma_f32_16x16x32_bf16 v[2:5], v[182:185], v[218:221], v[2:5]
	s_setprio 0
	s_barrier
	v_lshl_add_u64 v[146:147], v[224:225], 0, s[10:11]
	s_mov_b32 m0, s48
	s_nop 0
	global_load_lds_dwordx4 v[146:147], off
	s_add_i32 s61, s61, 2
	s_add_u32 s30, s30, 0x100
	s_addc_u32 s31, s31, 0
	s_add_u32 s59, s59, 0x100
	s_addc_u32 s60, s60, 0
	s_cmp_gt_u32 s61, 61
	s_cbranch_scc0 .LBB0_966
	s_and_b64 vcc, exec, s[12:13]
	s_cbranch_vccz .LBB0_969
	s_barrier

; #define PG8_STAGE(bufoff, gbase, voff) do { _Pragma("unroll") for (int _i = 0; _i < 2; ++_i) \
;         __builtin_amdgcn_global_load_lds((const unsigned*)((const char*)(gbase) + (voff)[_i]), (PG8_LAS unsigned*)(lds + (bufoff) + ldsw + _i * 8192), 16, 0, 0); } while (0)
; #define PG8_LDA(dst, b, h) do { _Pragma("unroll") for (int m = 0; m < 4; ++m) _Pragma("unroll") for (int k = 0; k < 2; ++k) dst[m][k] = *(const PG8_LAS bf16x8*)(lds + PG8_SA(b, h) + aoff + m * 2048 + k * 1024); } while (0)
; #define PG8_LDB(dst, b, h) do { _Pragma("unroll") for (int n = 0; n < 2; ++n) _Pragma("unroll") for (int k = 0; k < 2; ++k) dst[n][k] = *(const PG8_LAS bf16x8*)(lds + PG8_SB(b, h) + boff + n * 2048 + k * 1024); } while (0)
; #define PG8_MMA(ai, bj, At, Bt) do { __builtin_amdgcn_s_setprio(1); _Pragma("unroll") for (int m = 0; m < 4; ++m) _Pragma("unroll") for (int n = 0; n < 2; ++n) _Pragma("unroll") for (int k = 0; k < 2; ++k) \
;         acc[ai][bj][m][n] = __builtin_amdgcn_mfma_f32_16x16x32_bf16(Bt[n][k], At[m][k], acc[ai][bj][m][n], 0, 0, 0); __builtin_amdgcn_s_setprio(0); } while (0)
; #define PG8_WAIT_V(n) asm volatile("s_waitcnt vmcnt(" #n ")" ::: "memory")
; #define PG8_BAR __builtin_amdgcn_s_barrier()
; template <class Epi, class Sched, bool ALIGN_EPI = false, bool SP2 = false>
; __device__ __forceinline__ void gemm_phase(PG8_LAS unsigned char* lds, const Gemm g, const Sched& S, const Epi& E) {
;     ...
;         for (int t = 0; t < nt; t += 2) {
;             const bool last = (t == nt - 2);
;             const char* a1 = cA + (size_t)(t + 1) * kstep;
;             const char* a2 = last ? nA : cA + (size_t)(t + 2) * kstep; const char* b2 = last ? nB : cB + (size_t)(t + 2) * kstep;
;             const char* a3 = a2 + kstep; const char* b3 = b2 + kstep;
;             if (last && has_next) S.a_ready(nxt);
;             if constexpr (SP2) {
;             PG8_LDB(B0, 0, 0); PG8_LDB(B1, 0, 1); PG8_SCHED; PG8_LDA(At, 0, 0); PG8_STAGE(PG8_SA(1, 1), a1 + hstepA, voffA);
;             PG8_WAIT_V(8); PG8_WAIT_L(0); PG8_BAR; PG8_MMA(0, 0, At, B0); PG8_MMA(0, 1, At, B1); PG8_BAR; PG8_SCHED;
;             PG8_LDA(At, 0, 1); PG8_STAGE(PG8_SB(0, 0), b2, voffB); PG8_STAGE(PG8_SB(0, 1), b2 + hstepB, voffB); PG8_STAGE(PG8_SA(0, 0), a2, voffA);
;             PG8_WAIT_V(8); PG8_WAIT_L(0); PG8_BAR; PG8_MMA(1, 0, At, B0); PG8_MMA(1, 1, At, B1); PG8_BAR; PG8_SCHED;
.LBB0_1097:
	ds_read_b128 v[156:159], v153
	ds_read_b128 v[160:163], v153 offset:1024
	ds_read_b128 v[164:167], v153 offset:2048
	ds_read_b128 v[168:171], v153 offset:3072
	ds_read_b128 v[172:175], v154
	ds_read_b128 v[176:179], v154 offset:1024
	ds_read_b128 v[180:183], v154 offset:2048
	ds_read_b128 v[184:187], v154 offset:3072
	s_add_u32 s36, s34, 0xfff00080
	s_addc_u32 s37, s35, -1
	s_cmp_eq_u32 s63, 60
	s_cselect_b32 s39, s25, s37
	s_cselect_b32 s38, s59, s36
	s_cselect_b32 s37, s23, s62
	s_cselect_b32 s36, s60, s61
	v_lshl_add_u64 v[148:149], s[34:35], 0, v[138:139]
	s_add_i32 m0, s31, 0xc000
	ds_read_b128 v[188:191], v155
	ds_read_b128 v[192:195], v155 offset:1024
	ds_read_b128 v[196:199], v155 offset:2048
	ds_read_b128 v[200:203], v155 offset:3072
	ds_read_b128 v[204:207], v155 offset:4096
	ds_read_b128 v[208:211], v155 offset:5120
	ds_read_b128 v[212:215], v155 offset:6144
	ds_read_b128 v[218:221], v155 offset:7168
	global_load_lds_dwordx4 v[148:149], off
	v_lshl_add_u64 v[148:149], s[34:35], 0, v[140:141]
	s_add_i32 m0, s31, 0xe000
	s_nop 0
	global_load_lds_dwordx4 v[148:149], off
	s_waitcnt vmcnt(8)
	s_waitcnt lgkmcnt(0)
	s_barrier
	s_setprio 1
	s_waitcnt lgkmcnt(0)
	v_mfma_f32_16x16x32_bf16 v[126:129], v[156:159], v[188:191], v[126:129]
	v_mfma_f32_16x16x32_bf16 v[122:125], v[164:167], v[188:191], v[122:125]
	v_mfma_f32_16x16x32_bf16 v[118:121], v[156:159], v[196:199], v[118:121]
	v_mfma_f32_16x16x32_bf16 v[114:117], v[164:167], v[196:199], v[114:117]
	v_mfma_f32_16x16x32_bf16 v[110:113], v[156:159], v[204:207], v[110:113]
	v_mfma_f32_16x16x32_bf16 v[102:105], v[164:167], v[204:207], v[102:105]
	v_mfma_f32_16x16x32_bf16 v[94:97], v[156:159], v[212:215], v[94:97]
	v_mfma_f32_16x16x32_bf16 v[74:77], v[164:167], v[212:215], v[74:77]
	v_mfma_f32_16x16x32_bf16 v[126:129], v[160:163], v[192:195], v[126:129]
	v_mfma_f32_16x16x32_bf16 v[122:125], v[168:171], v[192:195], v[122:125]
	v_mfma_f32_16x16x32_bf16 v[118:121], v[160:163], v[200:203], v[118:121]
	v_mfma_f32_16x16x32_bf16 v[114:117], v[168:171], v[200:203], v[114:117]
	v_mfma_f32_16x16x32_bf16 v[110:113], v[160:163], v[208:211], v[110:113]
	v_mfma_f32_16x16x32_bf16 v[102:105], v[168:171], v[208:211], v[102:105]
	v_mfma_f32_16x16x32_bf16 v[94:97], v[160:163], v[218:221], v[94:97]
	v_mfma_f32_16x16x32_bf16 v[74:77], v[168:171], v[218:221], v[74:77]
	s_setprio 0
	s_setprio 1
	v_mfma_f32_16x16x32_bf16 v[106:109], v[172:175], v[188:191], v[106:109]
	v_mfma_f32_16x16x32_bf16 v[98:101], v[180:183], v[188:191], v[98:101]
	v_mfma_f32_16x16x32_bf16 v[90:93], v[172:175], v[196:199], v[90:93]
	v_mfma_f32_16x16x32_bf16 v[86:89], v[180:183], v[196:199], v[86:89]
	v_mfma_f32_16x16x32_bf16 v[82:85], v[172:175], v[204:207], v[82:85]
	v_mfma_f32_16x16x32_bf16 v[78:81], v[180:183], v[204:207], v[78:81]
	v_mfma_f32_16x16x32_bf16 v[70:73], v[172:175], v[212:215], v[70:73]
	v_mfma_f32_16x16x32_bf16 v[66:69], v[180:183], v[212:215], v[66:69]
	v_mfma_f32_16x16x32_bf16 v[106:109], v[176:179], v[192:195], v[106:109]
	v_mfma_f32_16x16x32_bf16 v[98:101], v[184:187], v[192:195], v[98:101]
	v_mfma_f32_16x16x32_bf16 v[90:93], v[176:179], v[200:203], v[90:93]
	v_mfma_f32_16x16x32_bf16 v[86:89], v[184:187], v[200:203], v[86:89]
	v_mfma_f32_16x16x32_bf16 v[82:85], v[176:179], v[208:211], v[82:85]
	v_mfma_f32_16x16x32_bf16 v[78:81], v[184:187], v[208:211], v[78:81]
	v_mfma_f32_16x16x32_bf16 v[70:73], v[176:179], v[218:221], v[70:73]
	v_mfma_f32_16x16x32_bf16 v[66:69], v[184:187], v[218:221], v[66:69]
	s_setprio 0
	s_barrier
	s_add_i32 s64, s52, s44
	v_lshl_add_u64 v[148:149], s[36:37], 0, v[132:133]
	s_mov_b32 m0, s64
	ds_read_b128 v[188:191], v155 offset:16384
	ds_read_b128 v[192:195], v155 offset:17408
	ds_read_b128 v[196:199], v155 offset:18432
	ds_read_b128 v[200:203], v155 offset:19456
	ds_read_b128 v[204:207], v155 offset:20480
	ds_read_b128 v[208:211], v155 offset:21504
	ds_read_b128 v[212:215], v155 offset:22528
	ds_read_b128 v[218:221], v155 offset:23552
	global_load_lds_dwordx4 v[148:149], off
	s_add_i32 m0, s64, 0x2000
	s_add_u32 s64, s36, 0x100000
	v_lshl_add_u64 v[222:223], s[36:37], 0, v[136:137]
	s_addc_u32 s65, s37, 0
	s_add_i32 s66, s53, s44
	global_load_lds_dwordx4 v[222:223], off
	v_lshl_add_u64 v[224:225], s[64:65], 0, v[132:133]
	s_mov_b32 m0, s66
	v_lshl_add_u64 v[226:227], s[38:39], 0, v[134:135]
	global_load_lds_dwordx4 v[224:225], off
	v_lshl_add_u64 v[224:225], s[64:65], 0, v[136:137]
	s_add_i32 m0, s66, 0x2000
	s_nop 0
	global_load_lds_dwordx4 v[224:225], off
	v_lshl_add_u64 v[224:225], s[38:39], 0, v[130:131]
	s_mov_b32 m0, s31
	s_nop 0
	global_load_lds_dwordx4 v[224:225], off
	s_waitcnt vmcnt(7)
	s_waitcnt lgkmcnt(0)
	s_barrier
; #define PG8_STAGE(bufoff, gbase, voff) do { _Pragma("unroll") for (int _i = 0; _i < 2; ++_i) \
;         __builtin_amdgcn_global_load_lds((const unsigned*)((const char*)(gbase) + (voff)[_i]), (PG8_LAS unsigned*)(lds + (bufoff) + ldsw + _i * 8192), 16, 0, 0); } while (0)
; #define PG8_LDA(dst, b, h) do { _Pragma("unroll") for (int m = 0; m < 4; ++m) _Pragma("unroll") for (int k = 0; k < 2; ++k) dst[m][k] = *(const PG8_LAS bf16x8*)(lds + PG8_SA(b, h) + aoff + m * 2048 + k * 1024); } while (0)
; #define PG8_LDB(dst, b, h) do { _Pragma("unroll") for (int n = 0; n < 2; ++n) _Pragma("unroll") for (int k = 0; k < 2; ++k) dst[n][k] = *(const PG8_LAS bf16x8*)(lds + PG8_SB(b, h) + boff + n * 2048 + k * 1024); } while (0)
; #define PG8_MMA(ai, bj, At, Bt) do { __builtin_amdgcn_s_setprio(1); _Pragma("unroll") for (int m = 0; m < 4; ++m) _Pragma("unroll") for (int n = 0; n < 2; ++n) _Pragma("unroll") for (int k = 0; k < 2; ++k) \
;         acc[ai][bj][m][n] = __builtin_amdgcn_mfma_f32_16x16x32_bf16(Bt[n][k], At[m][k], acc[ai][bj][m][n], 0, 0, 0); __builtin_amdgcn_s_setprio(0); } while (0)
; #define PG8_WAIT_V(n) asm volatile("s_waitcnt vmcnt(" #n ")" ::: "memory")
; #define PG8_WAIT_L(n) asm volatile("s_waitcnt lgkmcnt(" #n ")" ::: "memory")
; #define PG8_BAR __builtin_amdgcn_s_barrier()
; #define PG8_SCHED __builtin_amdgcn_sched_barrier(0)
; template <class Epi, class Sched, bool ALIGN_EPI = false, bool SP2 = false>
; __device__ __forceinline__ void gemm_phase(PG8_LAS unsigned char* lds, const Gemm g, const Sched& S, const Epi& E) {
;     ...
;             PG8_WAIT_V(8); PG8_WAIT_L(0); PG8_BAR; PG8_MMA(0, 0, At, B0); PG8_MMA(0, 1, At, B1); PG8_BAR; PG8_SCHED;
;             PG8_LDA(At, 0, 1); PG8_STAGE(PG8_SB(0, 0), b2, voffB); PG8_STAGE(PG8_SB(0, 1), b2 + hstepB, voffB); PG8_STAGE(PG8_SA(0, 0), a2, voffA);
;             PG8_WAIT_V(8); PG8_WAIT_L(0); PG8_BAR; PG8_MMA(1, 0, At, B0); PG8_MMA(1, 1, At, B1); PG8_BAR; PG8_SCHED;
;             PG8_LDB(B0, 1, 0); PG8_LDB(B1, 1, 1); PG8_SCHED; PG8_LDA(At, 1, 0); PG8_STAGE(PG8_SA(0, 1), a2 + hstepA, voffA);
;             PG8_WAIT_V(8); PG8_WAIT_L(0); PG8_BAR; PG8_MMA(0, 0, At, B0); PG8_MMA(0, 1, At, B1); PG8_BAR; PG8_SCHED;
	s_setprio 1
	s_waitcnt lgkmcnt(0)
	v_mfma_f32_16x16x32_bf16 v[62:65], v[156:159], v[188:191], v[62:65]
	v_mfma_f32_16x16x32_bf16 v[58:61], v[164:167], v[188:191], v[58:61]
	v_mfma_f32_16x16x32_bf16 v[50:53], v[156:159], v[196:199], v[50:53]
	v_mfma_f32_16x16x32_bf16 v[42:45], v[164:167], v[196:199], v[42:45]
	v_mfma_f32_16x16x32_bf16 v[34:37], v[156:159], v[204:207], v[34:37]
	v_mfma_f32_16x16x32_bf16 v[26:29], v[164:167], v[204:207], v[26:29]
	v_mfma_f32_16x16x32_bf16 v[18:21], v[156:159], v[212:215], v[18:21]
	v_mfma_f32_16x16x32_bf16 v[10:13], v[164:167], v[212:215], v[10:13]
	v_mfma_f32_16x16x32_bf16 v[62:65], v[160:163], v[192:195], v[62:65]
	v_mfma_f32_16x16x32_bf16 v[58:61], v[168:171], v[192:195], v[58:61]
	v_mfma_f32_16x16x32_bf16 v[50:53], v[160:163], v[200:203], v[50:53]
	v_mfma_f32_16x16x32_bf16 v[42:45], v[168:171], v[200:203], v[42:45]
	v_mfma_f32_16x16x32_bf16 v[34:37], v[160:163], v[208:211], v[34:37]
	v_mfma_f32_16x16x32_bf16 v[26:29], v[168:171], v[208:211], v[26:29]
	v_mfma_f32_16x16x32_bf16 v[18:21], v[160:163], v[218:221], v[18:21]
	v_mfma_f32_16x16x32_bf16 v[10:13], v[168:171], v[218:221], v[10:13]
	s_setprio 0
	s_setprio 1
	v_mfma_f32_16x16x32_bf16 v[54:57], v[172:175], v[188:191], v[54:57]
	v_mfma_f32_16x16x32_bf16 v[46:49], v[180:183], v[188:191], v[46:49]
	v_mfma_f32_16x16x32_bf16 v[38:41], v[172:175], v[196:199], v[38:41]
	v_mfma_f32_16x16x32_bf16 v[30:33], v[180:183], v[196:199], v[30:33]
	v_mfma_f32_16x16x32_bf16 v[22:25], v[172:175], v[204:207], v[22:25]
	v_mfma_f32_16x16x32_bf16 v[14:17], v[180:183], v[204:207], v[14:17]
	v_mfma_f32_16x16x32_bf16 v[6:9], v[172:175], v[212:215], v[6:9]
	v_mfma_f32_16x16x32_bf16 v[2:5], v[180:183], v[212:215], v[2:5]
	v_mfma_f32_16x16x32_bf16 v[54:57], v[176:179], v[192:195], v[54:57]
	v_mfma_f32_16x16x32_bf16 v[46:49], v[184:187], v[192:195], v[46:49]
	v_mfma_f32_16x16x32_bf16 v[38:41], v[176:179], v[200:203], v[38:41]
	v_mfma_f32_16x16x32_bf16 v[30:33], v[184:187], v[200:203], v[30:33]
	v_mfma_f32_16x16x32_bf16 v[22:25], v[176:179], v[208:211], v[22:25]
	v_mfma_f32_16x16x32_bf16 v[14:17], v[184:187], v[208:211], v[14:17]
	v_mfma_f32_16x16x32_bf16 v[6:9], v[176:179], v[218:221], v[6:9]
	v_mfma_f32_16x16x32_bf16 v[2:5], v[184:187], v[218:221], v[2:5]
	s_setprio 0
	s_barrier
	s_mov_b32 m0, s45
	s_nop 0
	global_load_lds_dwordx4 v[226:227], off
	s_add_i32 s64, 0, 0x18000
	v_add_u32_e32 v146, s64, v147
	s_add_i32 s65, 0, 0x1c000
	ds_read_b128 v[156:159], v146
	ds_read_b128 v[160:163], v146 offset:1024
	ds_read_b128 v[164:167], v146 offset:2048
	ds_read_b128 v[168:171], v146 offset:3072
	v_add_u32_e32 v146, s65, v147
	ds_read_b128 v[172:175], v146
	ds_read_b128 v[176:179], v146 offset:1024
	ds_read_b128 v[180:183], v146 offset:2048
	ds_read_b128 v[184:187], v146 offset:3072
	s_add_u32 s38, s38, 0x100000
	s_addc_u32 s39, s39, 0
	s_mov_b32 m0, s46
	v_lshl_add_u64 v[228:229], s[38:39], 0, v[130:131]
	ds_read_b128 v[188:191], v155 offset:32768
	ds_read_b128 v[192:195], v155 offset:33792
	ds_read_b128 v[196:199], v155 offset:34816
	ds_read_b128 v[200:203], v155 offset:35840
	ds_read_b128 v[204:207], v155 offset:36864
	ds_read_b128 v[208:211], v155 offset:37888
	ds_read_b128 v[212:215], v155 offset:38912
	ds_read_b128 v[218:221], v155 offset:39936
	global_load_lds_dwordx4 v[228:229], off
	v_lshl_add_u64 v[228:229], s[38:39], 0, v[134:135]
	s_mov_b32 m0, s47
	s_nop 0
	global_load_lds_dwordx4 v[228:229], off
	s_waitcnt vmcnt(8)
	s_waitcnt lgkmcnt(0)
	s_barrier
	s_setprio 1
	s_waitcnt lgkmcnt(0)
	v_mfma_f32_16x16x32_bf16 v[126:129], v[156:159], v[188:191], v[126:129]
	v_mfma_f32_16x16x32_bf16 v[122:125], v[164:167], v[188:191], v[122:125]
	v_mfma_f32_16x16x32_bf16 v[118:121], v[156:159], v[196:199], v[118:121]
	v_mfma_f32_16x16x32_bf16 v[114:117], v[164:167], v[196:199], v[114:117]
	v_mfma_f32_16x16x32_bf16 v[110:113], v[156:159], v[204:207], v[110:113]
	v_mfma_f32_16x16x32_bf16 v[102:105], v[164:167], v[204:207], v[102:105]
	v_mfma_f32_16x16x32_bf16 v[94:97], v[156:159], v[212:215], v[94:97]
	v_mfma_f32_16x16x32_bf16 v[74:77], v[164:167], v[212:215], v[74:77]
	v_mfma_f32_16x16x32_bf16 v[126:129], v[160:163], v[192:195], v[126:129]
	v_mfma_f32_16x16x32_bf16 v[122:125], v[168:171], v[192:195], v[122:125]
	v_mfma_f32_16x16x32_bf16 v[118:121], v[160:163], v[200:203], v[118:121]
	v_mfma_f32_16x16x32_bf16 v[114:117], v[168:171], v[200:203], v[114:117]
	v_mfma_f32_16x16x32_bf16 v[110:113], v[160:163], v[208:211], v[110:113]
	v_mfma_f32_16x16x32_bf16 v[102:105], v[168:171], v[208:211], v[102:105]
	v_mfma_f32_16x16x32_bf16 v[94:97], v[160:163], v[218:221], v[94:97]
	v_mfma_f32_16x16x32_bf16 v[74:77], v[168:171], v[218:221], v[74:77]
	s_setprio 0
	s_setprio 1
	v_mfma_f32_16x16x32_bf16 v[106:109], v[172:175], v[188:191], v[106:109]
	v_mfma_f32_16x16x32_bf16 v[98:101], v[180:183], v[188:191], v[98:101]
	v_mfma_f32_16x16x32_bf16 v[90:93], v[172:175], v[196:199], v[90:93]
	v_mfma_f32_16x16x32_bf16 v[86:89], v[180:183], v[196:199], v[86:89]
	v_mfma_f32_16x16x32_bf16 v[82:85], v[172:175], v[204:207], v[82:85]
	v_mfma_f32_16x16x32_bf16 v[78:81], v[180:183], v[204:207], v[78:81]
	v_mfma_f32_16x16x32_bf16 v[70:73], v[172:175], v[212:215], v[70:73]
	v_mfma_f32_16x16x32_bf16 v[66:69], v[180:183], v[212:215], v[66:69]
	v_mfma_f32_16x16x32_bf16 v[106:109], v[176:179], v[192:195], v[106:109]
	v_mfma_f32_16x16x32_bf16 v[98:101], v[184:187], v[192:195], v[98:101]
	v_mfma_f32_16x16x32_bf16 v[90:93], v[176:179], v[200:203], v[90:93]
	v_mfma_f32_16x16x32_bf16 v[86:89], v[184:187], v[200:203], v[86:89]
	v_mfma_f32_16x16x32_bf16 v[82:85], v[176:179], v[208:211], v[82:85]
	v_mfma_f32_16x16x32_bf16 v[78:81], v[184:187], v[208:211], v[78:81]
	v_mfma_f32_16x16x32_bf16 v[70:73], v[176:179], v[218:221], v[70:73]
	v_mfma_f32_16x16x32_bf16 v[66:69], v[184:187], v[218:221], v[66:69]
	s_setprio 0
	s_barrier
; #define PG8_STAGE(bufoff, gbase, voff) do { _Pragma("unroll") for (int _i = 0; _i < 2; ++_i) \
;         __builtin_amdgcn_global_load_lds((const unsigned*)((const char*)(gbase) + (voff)[_i]), (PG8_LAS unsigned*)(lds + (bufoff) + ldsw + _i * 8192), 16, 0, 0); } while (0)
; #define PG8_LDA(dst, b, h) do { _Pragma("unroll") for (int m = 0; m < 4; ++m) _Pragma("unroll") for (int k = 0; k < 2; ++k) dst[m][k] = *(const PG8_LAS bf16x8*)(lds + PG8_SA(b, h) + aoff + m * 2048 + k * 1024); } while (0)
; #define PG8_MMA(ai, bj, At, Bt) do { __builtin_amdgcn_s_setprio(1); _Pragma("unroll") for (int m = 0; m < 4; ++m) _Pragma("unroll") for (int n = 0; n < 2; ++n) _Pragma("unroll") for (int k = 0; k < 2; ++k) \
;         acc[ai][bj][m][n] = __builtin_amdgcn_mfma_f32_16x16x32_bf16(Bt[n][k], At[m][k], acc[ai][bj][m][n], 0, 0, 0); __builtin_amdgcn_s_setprio(0); } while (0)
; #define PG8_WAIT_V(n) asm volatile("s_waitcnt vmcnt(" #n ")" ::: "memory")
; #define PG8_WAIT_L(n) asm volatile("s_waitcnt lgkmcnt(" #n ")" ::: "memory")
; #define PG8_BAR __builtin_amdgcn_s_barrier()
; #define PG8_SCHED __builtin_amdgcn_sched_barrier(0)
; template <class Epi, class Sched, bool ALIGN_EPI = false, bool SP2 = false>
; __device__ __forceinline__ void gemm_phase(PG8_LAS unsigned char* lds, const Gemm g, const Sched& S, const Epi& E) {
;     ...
;             PG8_WAIT_V(8); PG8_WAIT_L(0); PG8_BAR; PG8_MMA(0, 0, At, B0); PG8_MMA(0, 1, At, B1); PG8_BAR; PG8_SCHED;
;             PG8_LDA(At, 1, 1); PG8_STAGE(PG8_SB(1, 0), b3, voffB); PG8_STAGE(PG8_SB(1, 1), b3 + hstepB, voffB); PG8_STAGE(PG8_SA(1, 0), a3, voffA);
;             PG8_WAIT_V(8); PG8_WAIT_L(0); PG8_BAR; PG8_MMA(1, 0, At, B0); PG8_MMA(1, 1, At, B1); PG8_BAR; PG8_SCHED;
;     ...
;         }
;         if constexpr (ALIGN_EPI) { if (wr == 0) PG8_BAR; }
	s_add_i32 s38, s64, s44
	v_lshl_add_u64 v[148:149], v[148:149], 0, s[10:11]
	s_mov_b32 m0, s38
	ds_read_b128 v[188:191], v155 offset:49152
	ds_read_b128 v[192:195], v155 offset:50176
	ds_read_b128 v[196:199], v155 offset:51200
	ds_read_b128 v[200:203], v155 offset:52224
	ds_read_b128 v[204:207], v155 offset:53248
	ds_read_b128 v[208:211], v155 offset:54272
	ds_read_b128 v[212:215], v155 offset:55296
	ds_read_b128 v[218:221], v155 offset:56320
	global_load_lds_dwordx4 v[148:149], off
	s_add_i32 m0, s38, 0x2000
	s_add_u32 s36, s36, 0x100080
	v_lshl_add_u64 v[148:149], v[222:223], 0, s[10:11]
	s_addc_u32 s37, s37, 0
	s_add_i32 s38, s65, s44
	global_load_lds_dwordx4 v[148:149], off
	v_lshl_add_u64 v[148:149], s[36:37], 0, v[132:133]
	s_mov_b32 m0, s38
	s_nop 0
	global_load_lds_dwordx4 v[148:149], off
	v_lshl_add_u64 v[148:149], s[36:37], 0, v[136:137]
	s_add_i32 m0, s38, 0x2000
	s_nop 0
	global_load_lds_dwordx4 v[148:149], off
	v_lshl_add_u64 v[148:149], v[224:225], 0, s[10:11]
	s_mov_b32 m0, s49
	s_nop 0
	global_load_lds_dwordx4 v[148:149], off
	s_waitcnt vmcnt(7)
	s_waitcnt lgkmcnt(0)
	s_barrier
	s_setprio 1
	s_waitcnt lgkmcnt(0)
	v_mfma_f32_16x16x32_bf16 v[62:65], v[156:159], v[188:191], v[62:65]
	v_mfma_f32_16x16x32_bf16 v[58:61], v[164:167], v[188:191], v[58:61]
	v_mfma_f32_16x16x32_bf16 v[50:53], v[156:159], v[196:199], v[50:53]
	v_mfma_f32_16x16x32_bf16 v[42:45], v[164:167], v[196:199], v[42:45]
	v_mfma_f32_16x16x32_bf16 v[34:37], v[156:159], v[204:207], v[34:37]
	v_mfma_f32_16x16x32_bf16 v[26:29], v[164:167], v[204:207], v[26:29]
	v_mfma_f32_16x16x32_bf16 v[18:21], v[156:159], v[212:215], v[18:21]
	v_mfma_f32_16x16x32_bf16 v[10:13], v[164:167], v[212:215], v[10:13]
	v_mfma_f32_16x16x32_bf16 v[62:65], v[160:163], v[192:195], v[62:65]
	v_mfma_f32_16x16x32_bf16 v[58:61], v[168:171], v[192:195], v[58:61]
	v_mfma_f32_16x16x32_bf16 v[50:53], v[160:163], v[200:203], v[50:53]
	v_mfma_f32_16x16x32_bf16 v[42:45], v[168:171], v[200:203], v[42:45]
	v_mfma_f32_16x16x32_bf16 v[34:37], v[160:163], v[208:211], v[34:37]
	v_mfma_f32_16x16x32_bf16 v[26:29], v[168:171], v[208:211], v[26:29]
	v_mfma_f32_16x16x32_bf16 v[18:21], v[160:163], v[218:221], v[18:21]
	v_mfma_f32_16x16x32_bf16 v[10:13], v[168:171], v[218:221], v[10:13]
	s_setprio 0
	s_setprio 1
	v_mfma_f32_16x16x32_bf16 v[54:57], v[172:175], v[188:191], v[54:57]
	v_mfma_f32_16x16x32_bf16 v[46:49], v[180:183], v[188:191], v[46:49]
	v_mfma_f32_16x16x32_bf16 v[38:41], v[172:175], v[196:199], v[38:41]
	v_mfma_f32_16x16x32_bf16 v[30:33], v[180:183], v[196:199], v[30:33]
	v_mfma_f32_16x16x32_bf16 v[22:25], v[172:175], v[204:207], v[22:25]
	v_mfma_f32_16x16x32_bf16 v[14:17], v[180:183], v[204:207], v[14:17]
	v_mfma_f32_16x16x32_bf16 v[6:9], v[172:175], v[212:215], v[6:9]
	v_mfma_f32_16x16x32_bf16 v[2:5], v[180:183], v[212:215], v[2:5]
	v_mfma_f32_16x16x32_bf16 v[54:57], v[176:179], v[192:195], v[54:57]
	v_mfma_f32_16x16x32_bf16 v[46:49], v[184:187], v[192:195], v[46:49]
	v_mfma_f32_16x16x32_bf16 v[38:41], v[176:179], v[200:203], v[38:41]
	v_mfma_f32_16x16x32_bf16 v[30:33], v[184:187], v[200:203], v[30:33]
	v_mfma_f32_16x16x32_bf16 v[22:25], v[176:179], v[208:211], v[22:25]
	v_mfma_f32_16x16x32_bf16 v[14:17], v[184:187], v[208:211], v[14:17]
	v_mfma_f32_16x16x32_bf16 v[6:9], v[176:179], v[218:221], v[6:9]
	v_mfma_f32_16x16x32_bf16 v[2:5], v[184:187], v[218:221], v[2:5]
	s_setprio 0
	s_barrier
	v_lshl_add_u64 v[148:149], v[226:227], 0, s[10:11]
	s_mov_b32 m0, s50
	s_nop 0
	global_load_lds_dwordx4 v[148:149], off
	s_add_i32 s63, s63, 2
	s_add_u32 s34, s34, 0x100
	s_addc_u32 s35, s35, 0
	s_add_u32 s61, s61, 0x100
	s_addc_u32 s62, s62, 0
	s_cmp_gt_u32 s63, 61
	s_cbranch_scc0 .LBB0_1097
	s_and_b64 vcc, exec, s[12:13]
	s_cbranch_vccz .LBB0_1100
	s_barrier

; #define PG8_STAGE(bufoff, gbase, voff) do { _Pragma("unroll") for (int _i = 0; _i < 2; ++_i) \
;         __builtin_amdgcn_global_load_lds((const unsigned*)((const char*)(gbase) + (voff)[_i]), (PG8_LAS unsigned*)(lds + (bufoff) + ldsw + _i * 8192), 16, 0, 0); } while (0)
; #define PG8_LDA(dst, b, h) do { _Pragma("unroll") for (int m = 0; m < 4; ++m) _Pragma("unroll") for (int k = 0; k < 2; ++k) dst[m][k] = *(const PG8_LAS bf16x8*)(lds + PG8_SA(b, h) + aoff + m * 2048 + k * 1024); } while (0)
; #define PG8_LDB(dst, b, h) do { _Pragma("unroll") for (int n = 0; n < 2; ++n) _Pragma("unroll") for (int k = 0; k < 2; ++k) dst[n][k] = *(const PG8_LAS bf16x8*)(lds + PG8_SB(b, h) + boff + n * 2048 + k * 1024); } while (0)
; #define PG8_MMA(ai, bj, At, Bt) do { __builtin_amdgcn_s_setprio(1); _Pragma("unroll") for (int m = 0; m < 4; ++m) _Pragma("unroll") for (int n = 0; n < 2; ++n) _Pragma("unroll") for (int k = 0; k < 2; ++k) \
;         acc[ai][bj][m][n] = __builtin_amdgcn_mfma_f32_16x16x32_bf16(Bt[n][k], At[m][k], acc[ai][bj][m][n], 0, 0, 0); __builtin_amdgcn_s_setprio(0); } while (0)
; #define PG8_WAIT_V(n) asm volatile("s_waitcnt vmcnt(" #n ")" ::: "memory")
; #define PG8_BAR __builtin_amdgcn_s_barrier()
; template <class Epi, class Sched, bool ALIGN_EPI = false, bool SP2 = false>
; __device__ __forceinline__ void gemm_phase(PG8_LAS unsigned char* lds, const Gemm g, const Sched& S, const Epi& E) {
;     ...
;         for (int t = 0; t < nt; t += 2) {
;             const bool last = (t == nt - 2);
;             const char* a1 = cA + (size_t)(t + 1) * kstep;
;             const char* a2 = last ? nA : cA + (size_t)(t + 2) * kstep; const char* b2 = last ? nB : cB + (size_t)(t + 2) * kstep;
;             const char* a3 = a2 + kstep; const char* b3 = b2 + kstep;
;             if (last && has_next) S.a_ready(nxt);
;             if constexpr (SP2) {
;             PG8_LDB(B0, 0, 0); PG8_LDB(B1, 0, 1); PG8_SCHED; PG8_LDA(At, 0, 0); PG8_STAGE(PG8_SA(1, 1), a1 + hstepA, voffA);
;             PG8_WAIT_V(8); PG8_WAIT_L(0); PG8_BAR; PG8_MMA(0, 0, At, B0); PG8_MMA(0, 1, At, B1); PG8_BAR; PG8_SCHED;
;             PG8_LDA(At, 0, 1); PG8_STAGE(PG8_SB(0, 0), b2, voffB); PG8_STAGE(PG8_SB(0, 1), b2 + hstepB, voffB); PG8_STAGE(PG8_SA(0, 0), a2, voffA);
;             PG8_WAIT_V(8); PG8_WAIT_L(0); PG8_BAR; PG8_MMA(1, 0, At, B0); PG8_MMA(1, 1, At, B1); PG8_BAR; PG8_SCHED;
.LBB0_1743:
	s_lshl_b32 s36, s62, 7
	s_add_u32 s37, s24, s36
	s_addc_u32 s38, s25, 0
	v_add_u32_e32 v140, s53, v143
	s_add_u32 s39, s37, 0x100
	ds_read_b128 v[146:149], v140
	ds_read_b128 v[150:153], v140 offset:1024
	ds_read_b128 v[154:157], v140 offset:2048
	ds_read_b128 v[158:161], v140 offset:3072
	v_add_u32_e32 v140, s54, v143
	s_addc_u32 s63, s38, 0
	ds_read_b128 v[162:165], v140
	ds_read_b128 v[166:169], v140 offset:1024
	ds_read_b128 v[170:173], v140 offset:2048
	ds_read_b128 v[174:177], v140 offset:3072
	s_and_b64 s[34:35], s[30:31], exec
	s_cselect_b32 s35, s23, s63
	s_cselect_b32 s34, s59, s39
	s_add_u32 s36, s26, s36
	s_addc_u32 s39, s27, 0
	s_add_u32 s36, s36, 0x100
	s_addc_u32 s39, s39, 0
	s_and_b64 s[30:31], s[30:31], exec
	s_cselect_b32 s31, s60, s39
	s_cselect_b32 s30, s61, s36
	s_add_u32 s36, s37, 0x100080
	s_addc_u32 s37, s38, 0
	v_lshl_add_u64 v[140:141], s[36:37], 0, v[130:131]
	s_add_i32 m0, s45, 0xc000
	ds_read_b128 v[178:181], v144
	ds_read_b128 v[182:185], v144 offset:1024
	ds_read_b128 v[186:189], v144 offset:2048
	ds_read_b128 v[190:193], v144 offset:3072
	ds_read_b128 v[194:197], v144 offset:4096
	ds_read_b128 v[198:201], v144 offset:5120
	ds_read_b128 v[202:205], v144 offset:6144
	ds_read_b128 v[206:209], v144 offset:7168
	global_load_lds_dwordx4 v[140:141], off
	v_lshl_add_u64 v[140:141], s[36:37], 0, v[134:135]
	s_add_i32 m0, s45, 0xe000
	s_nop 0
	global_load_lds_dwordx4 v[140:141], off
	s_waitcnt vmcnt(8)
	s_waitcnt lgkmcnt(0)
	s_barrier
	s_setprio 1
	s_waitcnt lgkmcnt(0)
	v_mfma_f32_16x16x32_bf16 v[126:129], v[146:149], v[178:181], v[126:129]
	v_mfma_f32_16x16x32_bf16 v[122:125], v[154:157], v[178:181], v[122:125]
	v_mfma_f32_16x16x32_bf16 v[114:117], v[146:149], v[186:189], v[114:117]
	v_mfma_f32_16x16x32_bf16 v[106:109], v[154:157], v[186:189], v[106:109]
	v_mfma_f32_16x16x32_bf16 v[98:101], v[146:149], v[194:197], v[98:101]
	v_mfma_f32_16x16x32_bf16 v[90:93], v[154:157], v[194:197], v[90:93]
	v_mfma_f32_16x16x32_bf16 v[82:85], v[146:149], v[202:205], v[82:85]
	v_mfma_f32_16x16x32_bf16 v[74:77], v[154:157], v[202:205], v[74:77]
	v_mfma_f32_16x16x32_bf16 v[126:129], v[150:153], v[182:185], v[126:129]
	v_mfma_f32_16x16x32_bf16 v[122:125], v[158:161], v[182:185], v[122:125]
	v_mfma_f32_16x16x32_bf16 v[114:117], v[150:153], v[190:193], v[114:117]
	v_mfma_f32_16x16x32_bf16 v[106:109], v[158:161], v[190:193], v[106:109]
	v_mfma_f32_16x16x32_bf16 v[98:101], v[150:153], v[198:201], v[98:101]
	v_mfma_f32_16x16x32_bf16 v[90:93], v[158:161], v[198:201], v[90:93]
	v_mfma_f32_16x16x32_bf16 v[82:85], v[150:153], v[206:209], v[82:85]
	v_mfma_f32_16x16x32_bf16 v[74:77], v[158:161], v[206:209], v[74:77]
	s_setprio 0
	s_setprio 1
	v_mfma_f32_16x16x32_bf16 v[118:121], v[162:165], v[178:181], v[118:121]
	v_mfma_f32_16x16x32_bf16 v[110:113], v[170:173], v[178:181], v[110:113]
	v_mfma_f32_16x16x32_bf16 v[102:105], v[162:165], v[186:189], v[102:105]
	v_mfma_f32_16x16x32_bf16 v[94:97], v[170:173], v[186:189], v[94:97]
	v_mfma_f32_16x16x32_bf16 v[86:89], v[162:165], v[194:197], v[86:89]
	v_mfma_f32_16x16x32_bf16 v[78:81], v[170:173], v[194:197], v[78:81]
	v_mfma_f32_16x16x32_bf16 v[70:73], v[162:165], v[202:205], v[70:73]
	v_mfma_f32_16x16x32_bf16 v[66:69], v[170:173], v[202:205], v[66:69]
	v_mfma_f32_16x16x32_bf16 v[118:121], v[166:169], v[182:185], v[118:121]
	v_mfma_f32_16x16x32_bf16 v[110:113], v[174:177], v[182:185], v[110:113]
	v_mfma_f32_16x16x32_bf16 v[102:105], v[166:169], v[190:193], v[102:105]
	v_mfma_f32_16x16x32_bf16 v[94:97], v[174:177], v[190:193], v[94:97]
	v_mfma_f32_16x16x32_bf16 v[86:89], v[166:169], v[198:201], v[86:89]
	v_mfma_f32_16x16x32_bf16 v[78:81], v[174:177], v[198:201], v[78:81]
	v_mfma_f32_16x16x32_bf16 v[70:73], v[166:169], v[206:209], v[70:73]
	v_mfma_f32_16x16x32_bf16 v[66:69], v[174:177], v[206:209], v[66:69]
	s_setprio 0
	s_barrier
	s_add_i32 s36, s53, s43
	v_lshl_add_u64 v[140:141], s[30:31], 0, v[132:133]
	s_mov_b32 m0, s36
	ds_read_b128 v[178:181], v144 offset:16384
	ds_read_b128 v[182:185], v144 offset:17408
	ds_read_b128 v[186:189], v144 offset:18432
	ds_read_b128 v[190:193], v144 offset:19456
	ds_read_b128 v[194:197], v144 offset:20480
	ds_read_b128 v[198:201], v144 offset:21504
	ds_read_b128 v[202:205], v144 offset:22528
	ds_read_b128 v[206:209], v144 offset:23552
	global_load_lds_dwordx4 v[140:141], off
	s_add_i32 m0, s36, 0x2000
	s_add_u32 s36, s30, 0x100000
	v_lshl_add_u64 v[210:211], s[30:31], 0, v[136:137]
	s_addc_u32 s37, s31, 0
	s_add_i32 s38, s54, s43
	global_load_lds_dwordx4 v[210:211], off
	v_lshl_add_u64 v[212:213], s[36:37], 0, v[132:133]
	s_mov_b32 m0, s38
	v_lshl_add_u64 v[214:215], s[34:35], 0, v[134:135]
	global_load_lds_dwordx4 v[212:213], off
	v_lshl_add_u64 v[212:213], s[36:37], 0, v[136:137]
	s_add_i32 m0, s38, 0x2000
	s_nop 0
	global_load_lds_dwordx4 v[212:213], off
	v_lshl_add_u64 v[212:213], s[34:35], 0, v[130:131]
	s_mov_b32 m0, s45
	s_nop 0
	global_load_lds_dwordx4 v[212:213], off
	s_waitcnt vmcnt(7)
	s_waitcnt lgkmcnt(0)
	s_barrier
; #define PG8_STAGE(bufoff, gbase, voff) do { _Pragma("unroll") for (int _i = 0; _i < 2; ++_i) \
;         __builtin_amdgcn_global_load_lds((const unsigned*)((const char*)(gbase) + (voff)[_i]), (PG8_LAS unsigned*)(lds + (bufoff) + ldsw + _i * 8192), 16, 0, 0); } while (0)
; #define PG8_LDA(dst, b, h) do { _Pragma("unroll") for (int m = 0; m < 4; ++m) _Pragma("unroll") for (int k = 0; k < 2; ++k) dst[m][k] = *(const PG8_LAS bf16x8*)(lds + PG8_SA(b, h) + aoff + m * 2048 + k * 1024); } while (0)
; #define PG8_LDB(dst, b, h) do { _Pragma("unroll") for (int n = 0; n < 2; ++n) _Pragma("unroll") for (int k = 0; k < 2; ++k) dst[n][k] = *(const PG8_LAS bf16x8*)(lds + PG8_SB(b, h) + boff + n * 2048 + k * 1024); } while (0)
; #define PG8_MMA(ai, bj, At, Bt) do { __builtin_amdgcn_s_setprio(1); _Pragma("unroll") for (int m = 0; m < 4; ++m) _Pragma("unroll") for (int n = 0; n < 2; ++n) _Pragma("unroll") for (int k = 0; k < 2; ++k) \
;         acc[ai][bj][m][n] = __builtin_amdgcn_mfma_f32_16x16x32_bf16(Bt[n][k], At[m][k], acc[ai][bj][m][n], 0, 0, 0); __builtin_amdgcn_s_setprio(0); } while (0)
; #define PG8_WAIT_V(n) asm volatile("s_waitcnt vmcnt(" #n ")" ::: "memory")
; #define PG8_WAIT_L(n) asm volatile("s_waitcnt lgkmcnt(" #n ")" ::: "memory")
; #define PG8_BAR __builtin_amdgcn_s_barrier()
; #define PG8_SCHED __builtin_amdgcn_sched_barrier(0)
; template <class Epi, class Sched, bool ALIGN_EPI = false, bool SP2 = false>
; __device__ __forceinline__ void gemm_phase(PG8_LAS unsigned char* lds, const Gemm g, const Sched& S, const Epi& E) {
;     ...
;             PG8_WAIT_V(8); PG8_WAIT_L(0); PG8_BAR; PG8_MMA(0, 0, At, B0); PG8_MMA(0, 1, At, B1); PG8_BAR; PG8_SCHED;
;             PG8_LDA(At, 0, 1); PG8_STAGE(PG8_SB(0, 0), b2, voffB); PG8_STAGE(PG8_SB(0, 1), b2 + hstepB, voffB); PG8_STAGE(PG8_SA(0, 0), a2, voffA);
;             PG8_WAIT_V(8); PG8_WAIT_L(0); PG8_BAR; PG8_MMA(1, 0, At, B0); PG8_MMA(1, 1, At, B1); PG8_BAR; PG8_SCHED;
;             PG8_LDB(B0, 1, 0); PG8_LDB(B1, 1, 1); PG8_SCHED; PG8_LDA(At, 1, 0); PG8_STAGE(PG8_SA(0, 1), a2 + hstepA, voffA);
;             PG8_WAIT_V(8); PG8_WAIT_L(0); PG8_BAR; PG8_MMA(0, 0, At, B0); PG8_MMA(0, 1, At, B1); PG8_BAR; PG8_SCHED;
	s_setprio 1
	s_waitcnt lgkmcnt(0)
	v_mfma_f32_16x16x32_bf16 v[62:65], v[146:149], v[178:181], v[62:65]
	v_mfma_f32_16x16x32_bf16 v[58:61], v[154:157], v[178:181], v[58:61]
	v_mfma_f32_16x16x32_bf16 v[50:53], v[146:149], v[186:189], v[50:53]
	v_mfma_f32_16x16x32_bf16 v[42:45], v[154:157], v[186:189], v[42:45]
	v_mfma_f32_16x16x32_bf16 v[34:37], v[146:149], v[194:197], v[34:37]
	v_mfma_f32_16x16x32_bf16 v[26:29], v[154:157], v[194:197], v[26:29]
	v_mfma_f32_16x16x32_bf16 v[18:21], v[146:149], v[202:205], v[18:21]
	v_mfma_f32_16x16x32_bf16 v[10:13], v[154:157], v[202:205], v[10:13]
	v_mfma_f32_16x16x32_bf16 v[62:65], v[150:153], v[182:185], v[62:65]
	v_mfma_f32_16x16x32_bf16 v[58:61], v[158:161], v[182:185], v[58:61]
	v_mfma_f32_16x16x32_bf16 v[50:53], v[150:153], v[190:193], v[50:53]
	v_mfma_f32_16x16x32_bf16 v[42:45], v[158:161], v[190:193], v[42:45]
	v_mfma_f32_16x16x32_bf16 v[34:37], v[150:153], v[198:201], v[34:37]
	v_mfma_f32_16x16x32_bf16 v[26:29], v[158:161], v[198:201], v[26:29]
	v_mfma_f32_16x16x32_bf16 v[18:21], v[150:153], v[206:209], v[18:21]
	v_mfma_f32_16x16x32_bf16 v[10:13], v[158:161], v[206:209], v[10:13]
	s_setprio 0
	s_setprio 1
	v_mfma_f32_16x16x32_bf16 v[54:57], v[162:165], v[178:181], v[54:57]
	v_mfma_f32_16x16x32_bf16 v[46:49], v[170:173], v[178:181], v[46:49]
	v_mfma_f32_16x16x32_bf16 v[38:41], v[162:165], v[186:189], v[38:41]
	v_mfma_f32_16x16x32_bf16 v[30:33], v[170:173], v[186:189], v[30:33]
	v_mfma_f32_16x16x32_bf16 v[22:25], v[162:165], v[194:197], v[22:25]
	v_mfma_f32_16x16x32_bf16 v[14:17], v[170:173], v[194:197], v[14:17]
	v_mfma_f32_16x16x32_bf16 v[6:9], v[162:165], v[202:205], v[6:9]
	v_mfma_f32_16x16x32_bf16 v[2:5], v[170:173], v[202:205], v[2:5]
	v_mfma_f32_16x16x32_bf16 v[54:57], v[166:169], v[182:185], v[54:57]
	v_mfma_f32_16x16x32_bf16 v[46:49], v[174:177], v[182:185], v[46:49]
	v_mfma_f32_16x16x32_bf16 v[38:41], v[166:169], v[190:193], v[38:41]
	v_mfma_f32_16x16x32_bf16 v[30:33], v[174:177], v[190:193], v[30:33]
	v_mfma_f32_16x16x32_bf16 v[22:25], v[166:169], v[198:201], v[22:25]
	v_mfma_f32_16x16x32_bf16 v[14:17], v[174:177], v[198:201], v[14:17]
	v_mfma_f32_16x16x32_bf16 v[6:9], v[166:169], v[206:209], v[6:9]
	v_mfma_f32_16x16x32_bf16 v[2:5], v[174:177], v[206:209], v[2:5]
	s_setprio 0
	s_barrier
	s_mov_b32 m0, s46
	s_nop 0
	global_load_lds_dwordx4 v[214:215], off
	s_add_i32 s36, 0, 0x18000
	v_add_u32_e32 v145, s36, v143
	s_add_i32 s37, 0, 0x1c000
	ds_read_b128 v[146:149], v145
	ds_read_b128 v[150:153], v145 offset:1024
	ds_read_b128 v[154:157], v145 offset:2048
	ds_read_b128 v[158:161], v145 offset:3072
	v_add_u32_e32 v145, s37, v143
	ds_read_b128 v[162:165], v145
	ds_read_b128 v[166:169], v145 offset:1024
	ds_read_b128 v[170:173], v145 offset:2048
	ds_read_b128 v[174:177], v145 offset:3072
	s_add_u32 s34, s34, 0x100000
	s_addc_u32 s35, s35, 0
	s_mov_b32 m0, s47
	v_lshl_add_u64 v[218:219], s[34:35], 0, v[130:131]
	ds_read_b128 v[178:181], v144 offset:32768
	ds_read_b128 v[182:185], v144 offset:33792
	ds_read_b128 v[186:189], v144 offset:34816
	ds_read_b128 v[190:193], v144 offset:35840
	ds_read_b128 v[194:197], v144 offset:36864
	ds_read_b128 v[198:201], v144 offset:37888
	ds_read_b128 v[202:205], v144 offset:38912
	ds_read_b128 v[206:209], v144 offset:39936
	global_load_lds_dwordx4 v[218:219], off
	v_lshl_add_u64 v[218:219], s[34:35], 0, v[134:135]
	s_mov_b32 m0, s48
	s_nop 0
	global_load_lds_dwordx4 v[218:219], off
	s_waitcnt vmcnt(8)
	s_waitcnt lgkmcnt(0)
	s_barrier
	s_setprio 1
	s_waitcnt lgkmcnt(0)
	v_mfma_f32_16x16x32_bf16 v[126:129], v[146:149], v[178:181], v[126:129]
	v_mfma_f32_16x16x32_bf16 v[122:125], v[154:157], v[178:181], v[122:125]
	v_mfma_f32_16x16x32_bf16 v[114:117], v[146:149], v[186:189], v[114:117]
	v_mfma_f32_16x16x32_bf16 v[106:109], v[154:157], v[186:189], v[106:109]
	v_mfma_f32_16x16x32_bf16 v[98:101], v[146:149], v[194:197], v[98:101]
	v_mfma_f32_16x16x32_bf16 v[90:93], v[154:157], v[194:197], v[90:93]
	v_mfma_f32_16x16x32_bf16 v[82:85], v[146:149], v[202:205], v[82:85]
	v_mfma_f32_16x16x32_bf16 v[74:77], v[154:157], v[202:205], v[74:77]
	v_mfma_f32_16x16x32_bf16 v[126:129], v[150:153], v[182:185], v[126:129]
	v_mfma_f32_16x16x32_bf16 v[122:125], v[158:161], v[182:185], v[122:125]
	v_mfma_f32_16x16x32_bf16 v[114:117], v[150:153], v[190:193], v[114:117]
	v_mfma_f32_16x16x32_bf16 v[106:109], v[158:161], v[190:193], v[106:109]
	v_mfma_f32_16x16x32_bf16 v[98:101], v[150:153], v[198:201], v[98:101]
	v_mfma_f32_16x16x32_bf16 v[90:93], v[158:161], v[198:201], v[90:93]
	v_mfma_f32_16x16x32_bf16 v[82:85], v[150:153], v[206:209], v[82:85]
	v_mfma_f32_16x16x32_bf16 v[74:77], v[158:161], v[206:209], v[74:77]
	s_setprio 0
	s_setprio 1
	v_mfma_f32_16x16x32_bf16 v[118:121], v[162:165], v[178:181], v[118:121]
	v_mfma_f32_16x16x32_bf16 v[110:113], v[170:173], v[178:181], v[110:113]
	v_mfma_f32_16x16x32_bf16 v[102:105], v[162:165], v[186:189], v[102:105]
	v_mfma_f32_16x16x32_bf16 v[94:97], v[170:173], v[186:189], v[94:97]
	v_mfma_f32_16x16x32_bf16 v[86:89], v[162:165], v[194:197], v[86:89]
	v_mfma_f32_16x16x32_bf16 v[78:81], v[170:173], v[194:197], v[78:81]
	v_mfma_f32_16x16x32_bf16 v[70:73], v[162:165], v[202:205], v[70:73]
	v_mfma_f32_16x16x32_bf16 v[66:69], v[170:173], v[202:205], v[66:69]
	v_mfma_f32_16x16x32_bf16 v[118:121], v[166:169], v[182:185], v[118:121]
	v_mfma_f32_16x16x32_bf16 v[110:113], v[174:177], v[182:185], v[110:113]
	v_mfma_f32_16x16x32_bf16 v[102:105], v[166:169], v[190:193], v[102:105]
	v_mfma_f32_16x16x32_bf16 v[94:97], v[174:177], v[190:193], v[94:97]
	v_mfma_f32_16x16x32_bf16 v[86:89], v[166:169], v[198:201], v[86:89]
	v_mfma_f32_16x16x32_bf16 v[78:81], v[174:177], v[198:201], v[78:81]
	v_mfma_f32_16x16x32_bf16 v[70:73], v[166:169], v[206:209], v[70:73]
	v_mfma_f32_16x16x32_bf16 v[66:69], v[174:177], v[206:209], v[66:69]
	s_setprio 0
	s_barrier
; #define PG8_STAGE(bufoff, gbase, voff) do { _Pragma("unroll") for (int _i = 0; _i < 2; ++_i) \
;         __builtin_amdgcn_global_load_lds((const unsigned*)((const char*)(gbase) + (voff)[_i]), (PG8_LAS unsigned*)(lds + (bufoff) + ldsw + _i * 8192), 16, 0, 0); } while (0)
; #define PG8_LDA(dst, b, h) do { _Pragma("unroll") for (int m = 0; m < 4; ++m) _Pragma("unroll") for (int k = 0; k < 2; ++k) dst[m][k] = *(const PG8_LAS bf16x8*)(lds + PG8_SA(b, h) + aoff + m * 2048 + k * 1024); } while (0)
; #define PG8_MMA(ai, bj, At, Bt) do { __builtin_amdgcn_s_setprio(1); _Pragma("unroll") for (int m = 0; m < 4; ++m) _Pragma("unroll") for (int n = 0; n < 2; ++n) _Pragma("unroll") for (int k = 0; k < 2; ++k) \
;         acc[ai][bj][m][n] = __builtin_amdgcn_mfma_f32_16x16x32_bf16(Bt[n][k], At[m][k], acc[ai][bj][m][n], 0, 0, 0); __builtin_amdgcn_s_setprio(0); } while (0)
; #define PG8_WAIT_V(n) asm volatile("s_waitcnt vmcnt(" #n ")" ::: "memory")
; #define PG8_WAIT_L(n) asm volatile("s_waitcnt lgkmcnt(" #n ")" ::: "memory")
; #define PG8_BAR __builtin_amdgcn_s_barrier()
; #define PG8_SCHED __builtin_amdgcn_sched_barrier(0)
; template <class Epi, class Sched, bool ALIGN_EPI = false, bool SP2 = false>
; __device__ __forceinline__ void gemm_phase(PG8_LAS unsigned char* lds, const Gemm g, const Sched& S, const Epi& E) {
;     ...
;             PG8_WAIT_V(8); PG8_WAIT_L(0); PG8_BAR; PG8_MMA(0, 0, At, B0); PG8_MMA(0, 1, At, B1); PG8_BAR; PG8_SCHED;
;             PG8_LDA(At, 1, 1); PG8_STAGE(PG8_SB(1, 0), b3, voffB); PG8_STAGE(PG8_SB(1, 1), b3 + hstepB, voffB); PG8_STAGE(PG8_SA(1, 0), a3, voffA);
;             PG8_WAIT_V(8); PG8_WAIT_L(0); PG8_BAR; PG8_MMA(1, 0, At, B0); PG8_MMA(1, 1, At, B1); PG8_BAR; PG8_SCHED;
;     ...
;         }
;         if constexpr (ALIGN_EPI) { if (wr == 0) PG8_BAR; }
	s_add_i32 s34, s36, s43
	v_lshl_add_u64 v[140:141], v[140:141], 0, s[10:11]
	s_mov_b32 m0, s34
	ds_read_b128 v[178:181], v144 offset:49152
	ds_read_b128 v[182:185], v144 offset:50176
	ds_read_b128 v[186:189], v144 offset:51200
	ds_read_b128 v[190:193], v144 offset:52224
	ds_read_b128 v[194:197], v144 offset:53248
	ds_read_b128 v[198:201], v144 offset:54272
	ds_read_b128 v[202:205], v144 offset:55296
	ds_read_b128 v[206:209], v144 offset:56320
	global_load_lds_dwordx4 v[140:141], off
	s_add_i32 m0, s34, 0x2000
	s_add_u32 s30, s30, 0x100080
	v_lshl_add_u64 v[140:141], v[210:211], 0, s[10:11]
	s_addc_u32 s31, s31, 0
	s_add_i32 s34, s37, s43
	global_load_lds_dwordx4 v[140:141], off
	v_lshl_add_u64 v[140:141], s[30:31], 0, v[132:133]
	s_mov_b32 m0, s34
	s_nop 0
	global_load_lds_dwordx4 v[140:141], off
	v_lshl_add_u64 v[140:141], s[30:31], 0, v[136:137]
	s_add_i32 m0, s34, 0x2000
	s_nop 0
	global_load_lds_dwordx4 v[140:141], off
	v_lshl_add_u64 v[140:141], v[212:213], 0, s[10:11]
	s_mov_b32 m0, s49
	s_nop 0
	global_load_lds_dwordx4 v[140:141], off
	s_waitcnt vmcnt(7)
	s_waitcnt lgkmcnt(0)
	s_barrier
	s_setprio 1
	s_waitcnt lgkmcnt(0)
	v_mfma_f32_16x16x32_bf16 v[62:65], v[146:149], v[178:181], v[62:65]
	v_mfma_f32_16x16x32_bf16 v[58:61], v[154:157], v[178:181], v[58:61]
	v_mfma_f32_16x16x32_bf16 v[50:53], v[146:149], v[186:189], v[50:53]
	v_mfma_f32_16x16x32_bf16 v[42:45], v[154:157], v[186:189], v[42:45]
	v_mfma_f32_16x16x32_bf16 v[34:37], v[146:149], v[194:197], v[34:37]
	v_mfma_f32_16x16x32_bf16 v[26:29], v[154:157], v[194:197], v[26:29]
	v_mfma_f32_16x16x32_bf16 v[18:21], v[146:149], v[202:205], v[18:21]
	v_mfma_f32_16x16x32_bf16 v[10:13], v[154:157], v[202:205], v[10:13]
	v_mfma_f32_16x16x32_bf16 v[62:65], v[150:153], v[182:185], v[62:65]
	v_mfma_f32_16x16x32_bf16 v[58:61], v[158:161], v[182:185], v[58:61]
	v_mfma_f32_16x16x32_bf16 v[50:53], v[150:153], v[190:193], v[50:53]
	v_mfma_f32_16x16x32_bf16 v[42:45], v[158:161], v[190:193], v[42:45]
	v_mfma_f32_16x16x32_bf16 v[34:37], v[150:153], v[198:201], v[34:37]
	v_mfma_f32_16x16x32_bf16 v[26:29], v[158:161], v[198:201], v[26:29]
	v_mfma_f32_16x16x32_bf16 v[18:21], v[150:153], v[206:209], v[18:21]
	v_mfma_f32_16x16x32_bf16 v[10:13], v[158:161], v[206:209], v[10:13]
	s_setprio 0
	s_setprio 1
	v_mfma_f32_16x16x32_bf16 v[54:57], v[162:165], v[178:181], v[54:57]
	v_mfma_f32_16x16x32_bf16 v[46:49], v[170:173], v[178:181], v[46:49]
	v_mfma_f32_16x16x32_bf16 v[38:41], v[162:165], v[186:189], v[38:41]
	v_mfma_f32_16x16x32_bf16 v[30:33], v[170:173], v[186:189], v[30:33]
	v_mfma_f32_16x16x32_bf16 v[22:25], v[162:165], v[194:197], v[22:25]
	v_mfma_f32_16x16x32_bf16 v[14:17], v[170:173], v[194:197], v[14:17]
	v_mfma_f32_16x16x32_bf16 v[6:9], v[162:165], v[202:205], v[6:9]
	v_mfma_f32_16x16x32_bf16 v[2:5], v[170:173], v[202:205], v[2:5]
	v_mfma_f32_16x16x32_bf16 v[54:57], v[166:169], v[182:185], v[54:57]
	v_mfma_f32_16x16x32_bf16 v[46:49], v[174:177], v[182:185], v[46:49]
	v_mfma_f32_16x16x32_bf16 v[38:41], v[166:169], v[190:193], v[38:41]
	v_mfma_f32_16x16x32_bf16 v[30:33], v[174:177], v[190:193], v[30:33]
	v_mfma_f32_16x16x32_bf16 v[22:25], v[166:169], v[198:201], v[22:25]
	v_mfma_f32_16x16x32_bf16 v[14:17], v[174:177], v[198:201], v[14:17]
	v_mfma_f32_16x16x32_bf16 v[6:9], v[166:169], v[206:209], v[6:9]
	v_mfma_f32_16x16x32_bf16 v[2:5], v[174:177], v[206:209], v[2:5]
	s_setprio 0
	s_barrier
	v_lshl_add_u64 v[140:141], v[214:215], 0, s[10:11]
	s_mov_b32 m0, s50
	s_nop 0
	global_load_lds_dwordx4 v[140:141], off
	s_add_i32 s30, s62, 2
	s_cmp_gt_u32 s62, 61
	s_mov_b32 s62, s30
	s_cbranch_scc1 .LBB0_1770

; #define PG8_STAGE(bufoff, gbase, voff) do { _Pragma("unroll") for (int _i = 0; _i < 2; ++_i) \
;         __builtin_amdgcn_global_load_lds((const unsigned*)((const char*)(gbase) + (voff)[_i]), (PG8_LAS unsigned*)(lds + (bufoff) + ldsw + _i * 8192), 16, 0, 0); } while (0)
; #define PG8_LDA(dst, b, h) do { _Pragma("unroll") for (int m = 0; m < 4; ++m) _Pragma("unroll") for (int k = 0; k < 2; ++k) dst[m][k] = *(const PG8_LAS bf16x8*)(lds + PG8_SA(b, h) + aoff + m * 2048 + k * 1024); } while (0)
; #define PG8_LDB(dst, b, h) do { _Pragma("unroll") for (int n = 0; n < 2; ++n) _Pragma("unroll") for (int k = 0; k < 2; ++k) dst[n][k] = *(const PG8_LAS bf16x8*)(lds + PG8_SB(b, h) + boff + n * 2048 + k * 1024); } while (0)
; #define PG8_MMA(ai, bj, At, Bt) do { __builtin_amdgcn_s_setprio(1); _Pragma("unroll") for (int m = 0; m < 4; ++m) _Pragma("unroll") for (int n = 0; n < 2; ++n) _Pragma("unroll") for (int k = 0; k < 2; ++k) \
;         acc[ai][bj][m][n] = __builtin_amdgcn_mfma_f32_16x16x32_bf16(Bt[n][k], At[m][k], acc[ai][bj][m][n], 0, 0, 0); __builtin_amdgcn_s_setprio(0); } while (0)
; #define PG8_WAIT_V(n) asm volatile("s_waitcnt vmcnt(" #n ")" ::: "memory")
; #define PG8_BAR __builtin_amdgcn_s_barrier()
; template <class Epi, class Sched, bool ALIGN_EPI = false, bool SP2 = false>
; __device__ __forceinline__ void gemm_phase(PG8_LAS unsigned char* lds, const Gemm g, const Sched& S, const Epi& E) {
;     ...
;         for (int t = 0; t < nt; t += 2) {
;             const bool last = (t == nt - 2);
;             const char* a1 = cA + (size_t)(t + 1) * kstep;
;             const char* a2 = last ? nA : cA + (size_t)(t + 2) * kstep; const char* b2 = last ? nB : cB + (size_t)(t + 2) * kstep;
;             const char* a3 = a2 + kstep; const char* b3 = b2 + kstep;
;             if (last && has_next) S.a_ready(nxt);
;             if constexpr (SP2) {
;             PG8_LDB(B0, 0, 0); PG8_LDB(B1, 0, 1); PG8_SCHED; PG8_LDA(At, 0, 0); PG8_STAGE(PG8_SA(1, 1), a1 + hstepA, voffA);
;             PG8_WAIT_V(8); PG8_WAIT_L(0); PG8_BAR; PG8_MMA(0, 0, At, B0); PG8_MMA(0, 1, At, B1); PG8_BAR; PG8_SCHED;
;             PG8_LDA(At, 0, 1); PG8_STAGE(PG8_SB(0, 0), b2, voffB); PG8_STAGE(PG8_SB(0, 1), b2 + hstepB, voffB); PG8_STAGE(PG8_SA(0, 0), a2, voffA);
;             PG8_WAIT_V(8); PG8_WAIT_L(0); PG8_BAR; PG8_MMA(1, 0, At, B0); PG8_MMA(1, 1, At, B1); PG8_BAR; PG8_SCHED;
.LBB0_1868:
	ds_read_b128 v[160:163], v156
	ds_read_b128 v[164:167], v156 offset:1024
	ds_read_b128 v[168:171], v156 offset:2048
	ds_read_b128 v[172:175], v156 offset:3072
	ds_read_b128 v[176:179], v157
	ds_read_b128 v[180:183], v157 offset:1024
	ds_read_b128 v[184:187], v157 offset:2048
	ds_read_b128 v[188:191], v157 offset:3072
	s_add_u32 s34, s30, 0xfff00080
	s_addc_u32 s35, s31, -1
	s_cmp_eq_u32 s61, 60
	s_cselect_b32 s37, s23, s35
	s_cselect_b32 s36, s57, s34
	s_cselect_b32 s35, s21, s60
	s_cselect_b32 s34, s58, s59
	v_lshl_add_u64 v[146:147], s[30:31], 0, v[138:139]
	s_add_i32 m0, s29, 0xc000
	ds_read_b128 v[192:195], v158
	ds_read_b128 v[196:199], v158 offset:1024
	ds_read_b128 v[200:203], v158 offset:2048
	ds_read_b128 v[204:207], v158 offset:3072
	ds_read_b128 v[208:211], v158 offset:4096
	ds_read_b128 v[212:215], v158 offset:5120
	ds_read_b128 v[218:221], v158 offset:6144
	ds_read_b128 v[222:225], v158 offset:7168
	global_load_lds_dwordx4 v[146:147], off
	v_lshl_add_u64 v[146:147], s[30:31], 0, v[140:141]
	s_add_i32 m0, s29, 0xe000
	s_nop 0
	global_load_lds_dwordx4 v[146:147], off
	s_waitcnt vmcnt(8)
	s_waitcnt lgkmcnt(0)
	s_barrier
	s_setprio 1
	s_waitcnt lgkmcnt(0)
	v_mfma_f32_16x16x32_bf16 v[126:129], v[160:163], v[192:195], v[126:129]
	v_mfma_f32_16x16x32_bf16 v[122:125], v[168:171], v[192:195], v[122:125]
	v_mfma_f32_16x16x32_bf16 v[114:117], v[160:163], v[200:203], v[114:117]
	v_mfma_f32_16x16x32_bf16 v[106:109], v[168:171], v[200:203], v[106:109]
	v_mfma_f32_16x16x32_bf16 v[98:101], v[160:163], v[208:211], v[98:101]
	v_mfma_f32_16x16x32_bf16 v[90:93], v[168:171], v[208:211], v[90:93]
	v_mfma_f32_16x16x32_bf16 v[82:85], v[160:163], v[218:221], v[82:85]
	v_mfma_f32_16x16x32_bf16 v[74:77], v[168:171], v[218:221], v[74:77]
	v_mfma_f32_16x16x32_bf16 v[126:129], v[164:167], v[196:199], v[126:129]
	v_mfma_f32_16x16x32_bf16 v[122:125], v[172:175], v[196:199], v[122:125]
	v_mfma_f32_16x16x32_bf16 v[114:117], v[164:167], v[204:207], v[114:117]
	v_mfma_f32_16x16x32_bf16 v[106:109], v[172:175], v[204:207], v[106:109]
	v_mfma_f32_16x16x32_bf16 v[98:101], v[164:167], v[212:215], v[98:101]
	v_mfma_f32_16x16x32_bf16 v[90:93], v[172:175], v[212:215], v[90:93]
	v_mfma_f32_16x16x32_bf16 v[82:85], v[164:167], v[222:225], v[82:85]
	v_mfma_f32_16x16x32_bf16 v[74:77], v[172:175], v[222:225], v[74:77]
	s_setprio 0
	s_setprio 1
	v_mfma_f32_16x16x32_bf16 v[118:121], v[176:179], v[192:195], v[118:121]
	v_mfma_f32_16x16x32_bf16 v[110:113], v[184:187], v[192:195], v[110:113]
	v_mfma_f32_16x16x32_bf16 v[102:105], v[176:179], v[200:203], v[102:105]
	v_mfma_f32_16x16x32_bf16 v[94:97], v[184:187], v[200:203], v[94:97]
	v_mfma_f32_16x16x32_bf16 v[86:89], v[176:179], v[208:211], v[86:89]
	v_mfma_f32_16x16x32_bf16 v[78:81], v[184:187], v[208:211], v[78:81]
	v_mfma_f32_16x16x32_bf16 v[70:73], v[176:179], v[218:221], v[70:73]
	v_mfma_f32_16x16x32_bf16 v[66:69], v[184:187], v[218:221], v[66:69]
	v_mfma_f32_16x16x32_bf16 v[118:121], v[180:183], v[196:199], v[118:121]
	v_mfma_f32_16x16x32_bf16 v[110:113], v[188:191], v[196:199], v[110:113]
	v_mfma_f32_16x16x32_bf16 v[102:105], v[180:183], v[204:207], v[102:105]
	v_mfma_f32_16x16x32_bf16 v[94:97], v[188:191], v[204:207], v[94:97]
	v_mfma_f32_16x16x32_bf16 v[86:89], v[180:183], v[212:215], v[86:89]
	v_mfma_f32_16x16x32_bf16 v[78:81], v[188:191], v[212:215], v[78:81]
	v_mfma_f32_16x16x32_bf16 v[70:73], v[180:183], v[222:225], v[70:73]
	v_mfma_f32_16x16x32_bf16 v[66:69], v[188:191], v[222:225], v[66:69]
	s_setprio 0
	s_barrier
	s_add_i32 s62, s50, s42
	v_lshl_add_u64 v[146:147], s[34:35], 0, v[132:133]
	s_mov_b32 m0, s62
	ds_read_b128 v[192:195], v158 offset:16384
	ds_read_b128 v[196:199], v158 offset:17408
	ds_read_b128 v[200:203], v158 offset:18432
	ds_read_b128 v[204:207], v158 offset:19456
	ds_read_b128 v[208:211], v158 offset:20480
	ds_read_b128 v[212:215], v158 offset:21504
	ds_read_b128 v[218:221], v158 offset:22528
	ds_read_b128 v[222:225], v158 offset:23552
	global_load_lds_dwordx4 v[146:147], off
	s_add_i32 m0, s62, 0x2000
	s_add_u32 s62, s34, 0x100000
	v_lshl_add_u64 v[226:227], s[34:35], 0, v[136:137]
	s_addc_u32 s63, s35, 0
	s_add_i32 s64, s51, s42
	global_load_lds_dwordx4 v[226:227], off
	v_lshl_add_u64 v[228:229], s[62:63], 0, v[132:133]
	s_mov_b32 m0, s64
	v_lshl_add_u64 v[230:231], s[36:37], 0, v[134:135]
	global_load_lds_dwordx4 v[228:229], off
	v_lshl_add_u64 v[228:229], s[62:63], 0, v[136:137]
	s_add_i32 m0, s64, 0x2000
	s_nop 0
	global_load_lds_dwordx4 v[228:229], off
	v_lshl_add_u64 v[228:229], s[36:37], 0, v[130:131]
	s_mov_b32 m0, s29
	s_nop 0
	global_load_lds_dwordx4 v[228:229], off
	s_waitcnt vmcnt(7)
	s_waitcnt lgkmcnt(0)
	s_barrier
; #define PG8_STAGE(bufoff, gbase, voff) do { _Pragma("unroll") for (int _i = 0; _i < 2; ++_i) \
;         __builtin_amdgcn_global_load_lds((const unsigned*)((const char*)(gbase) + (voff)[_i]), (PG8_LAS unsigned*)(lds + (bufoff) + ldsw + _i * 8192), 16, 0, 0); } while (0)
; #define PG8_LDA(dst, b, h) do { _Pragma("unroll") for (int m = 0; m < 4; ++m) _Pragma("unroll") for (int k = 0; k < 2; ++k) dst[m][k] = *(const PG8_LAS bf16x8*)(lds + PG8_SA(b, h) + aoff + m * 2048 + k * 1024); } while (0)
; #define PG8_LDB(dst, b, h) do { _Pragma("unroll") for (int n = 0; n < 2; ++n) _Pragma("unroll") for (int k = 0; k < 2; ++k) dst[n][k] = *(const PG8_LAS bf16x8*)(lds + PG8_SB(b, h) + boff + n * 2048 + k * 1024); } while (0)
; #define PG8_MMA(ai, bj, At, Bt) do { __builtin_amdgcn_s_setprio(1); _Pragma("unroll") for (int m = 0; m < 4; ++m) _Pragma("unroll") for (int n = 0; n < 2; ++n) _Pragma("unroll") for (int k = 0; k < 2; ++k) \
;         acc[ai][bj][m][n] = __builtin_amdgcn_mfma_f32_16x16x32_bf16(Bt[n][k], At[m][k], acc[ai][bj][m][n], 0, 0, 0); __builtin_amdgcn_s_setprio(0); } while (0)
; #define PG8_WAIT_V(n) asm volatile("s_waitcnt vmcnt(" #n ")" ::: "memory")
; #define PG8_WAIT_L(n) asm volatile("s_waitcnt lgkmcnt(" #n ")" ::: "memory")
; #define PG8_BAR __builtin_amdgcn_s_barrier()
; #define PG8_SCHED __builtin_amdgcn_sched_barrier(0)
; template <class Epi, class Sched, bool ALIGN_EPI = false, bool SP2 = false>
; __device__ __forceinline__ void gemm_phase(PG8_LAS unsigned char* lds, const Gemm g, const Sched& S, const Epi& E) {
;     ...
;             PG8_WAIT_V(8); PG8_WAIT_L(0); PG8_BAR; PG8_MMA(0, 0, At, B0); PG8_MMA(0, 1, At, B1); PG8_BAR; PG8_SCHED;
;             PG8_LDA(At, 0, 1); PG8_STAGE(PG8_SB(0, 0), b2, voffB); PG8_STAGE(PG8_SB(0, 1), b2 + hstepB, voffB); PG8_STAGE(PG8_SA(0, 0), a2, voffA);
;             PG8_WAIT_V(8); PG8_WAIT_L(0); PG8_BAR; PG8_MMA(1, 0, At, B0); PG8_MMA(1, 1, At, B1); PG8_BAR; PG8_SCHED;
;             PG8_LDB(B0, 1, 0); PG8_LDB(B1, 1, 1); PG8_SCHED; PG8_LDA(At, 1, 0); PG8_STAGE(PG8_SA(0, 1), a2 + hstepA, voffA);
;             PG8_WAIT_V(8); PG8_WAIT_L(0); PG8_BAR; PG8_MMA(0, 0, At, B0); PG8_MMA(0, 1, At, B1); PG8_BAR; PG8_SCHED;
	s_setprio 1
	s_waitcnt lgkmcnt(0)
	v_mfma_f32_16x16x32_bf16 v[62:65], v[160:163], v[192:195], v[62:65]
	v_mfma_f32_16x16x32_bf16 v[58:61], v[168:171], v[192:195], v[58:61]
	v_mfma_f32_16x16x32_bf16 v[50:53], v[160:163], v[200:203], v[50:53]
	v_mfma_f32_16x16x32_bf16 v[42:45], v[168:171], v[200:203], v[42:45]
	v_mfma_f32_16x16x32_bf16 v[34:37], v[160:163], v[208:211], v[34:37]
	v_mfma_f32_16x16x32_bf16 v[26:29], v[168:171], v[208:211], v[26:29]
	v_mfma_f32_16x16x32_bf16 v[18:21], v[160:163], v[218:221], v[18:21]
	v_mfma_f32_16x16x32_bf16 v[10:13], v[168:171], v[218:221], v[10:13]
	v_mfma_f32_16x16x32_bf16 v[62:65], v[164:167], v[196:199], v[62:65]
	v_mfma_f32_16x16x32_bf16 v[58:61], v[172:175], v[196:199], v[58:61]
	v_mfma_f32_16x16x32_bf16 v[50:53], v[164:167], v[204:207], v[50:53]
	v_mfma_f32_16x16x32_bf16 v[42:45], v[172:175], v[204:207], v[42:45]
	v_mfma_f32_16x16x32_bf16 v[34:37], v[164:167], v[212:215], v[34:37]
	v_mfma_f32_16x16x32_bf16 v[26:29], v[172:175], v[212:215], v[26:29]
	v_mfma_f32_16x16x32_bf16 v[18:21], v[164:167], v[222:225], v[18:21]
	v_mfma_f32_16x16x32_bf16 v[10:13], v[172:175], v[222:225], v[10:13]
	s_setprio 0
	s_setprio 1
	v_mfma_f32_16x16x32_bf16 v[54:57], v[176:179], v[192:195], v[54:57]
	v_mfma_f32_16x16x32_bf16 v[46:49], v[184:187], v[192:195], v[46:49]
	v_mfma_f32_16x16x32_bf16 v[38:41], v[176:179], v[200:203], v[38:41]
	v_mfma_f32_16x16x32_bf16 v[30:33], v[184:187], v[200:203], v[30:33]
	v_mfma_f32_16x16x32_bf16 v[22:25], v[176:179], v[208:211], v[22:25]
	v_mfma_f32_16x16x32_bf16 v[14:17], v[184:187], v[208:211], v[14:17]
	v_mfma_f32_16x16x32_bf16 v[6:9], v[176:179], v[218:221], v[6:9]
	v_mfma_f32_16x16x32_bf16 v[2:5], v[184:187], v[218:221], v[2:5]
	v_mfma_f32_16x16x32_bf16 v[54:57], v[180:183], v[196:199], v[54:57]
	v_mfma_f32_16x16x32_bf16 v[46:49], v[188:191], v[196:199], v[46:49]
	v_mfma_f32_16x16x32_bf16 v[38:41], v[180:183], v[204:207], v[38:41]
	v_mfma_f32_16x16x32_bf16 v[30:33], v[188:191], v[204:207], v[30:33]
	v_mfma_f32_16x16x32_bf16 v[22:25], v[180:183], v[212:215], v[22:25]
	v_mfma_f32_16x16x32_bf16 v[14:17], v[188:191], v[212:215], v[14:17]
	v_mfma_f32_16x16x32_bf16 v[6:9], v[180:183], v[222:225], v[6:9]
	v_mfma_f32_16x16x32_bf16 v[2:5], v[188:191], v[222:225], v[2:5]
	s_setprio 0
	s_barrier
	s_mov_b32 m0, s43
	s_nop 0
	global_load_lds_dwordx4 v[230:231], off
	s_add_i32 s62, 0, 0x18000
	v_add_u32_e32 v159, s62, v154
	s_add_i32 s63, 0, 0x1c000
	ds_read_b128 v[160:163], v159
	ds_read_b128 v[164:167], v159 offset:1024
	ds_read_b128 v[168:171], v159 offset:2048
	ds_read_b128 v[172:175], v159 offset:3072
	v_add_u32_e32 v159, s63, v154
	ds_read_b128 v[176:179], v159
	ds_read_b128 v[180:183], v159 offset:1024
	ds_read_b128 v[184:187], v159 offset:2048
	ds_read_b128 v[188:191], v159 offset:3072
	s_add_u32 s36, s36, 0x100000
	s_addc_u32 s37, s37, 0
	s_mov_b32 m0, s44
	v_lshl_add_u64 v[232:233], s[36:37], 0, v[130:131]
	ds_read_b128 v[192:195], v158 offset:32768
	ds_read_b128 v[196:199], v158 offset:33792
	ds_read_b128 v[200:203], v158 offset:34816
	ds_read_b128 v[204:207], v158 offset:35840
	ds_read_b128 v[208:211], v158 offset:36864
	ds_read_b128 v[212:215], v158 offset:37888
	ds_read_b128 v[218:221], v158 offset:38912
	ds_read_b128 v[222:225], v158 offset:39936
	global_load_lds_dwordx4 v[232:233], off
	v_lshl_add_u64 v[232:233], s[36:37], 0, v[134:135]
	s_mov_b32 m0, s45
	s_nop 0
	global_load_lds_dwordx4 v[232:233], off
	s_waitcnt vmcnt(8)
	s_waitcnt lgkmcnt(0)
	s_barrier
	s_setprio 1
	s_waitcnt lgkmcnt(0)
	v_mfma_f32_16x16x32_bf16 v[126:129], v[160:163], v[192:195], v[126:129]
	v_mfma_f32_16x16x32_bf16 v[122:125], v[168:171], v[192:195], v[122:125]
	v_mfma_f32_16x16x32_bf16 v[114:117], v[160:163], v[200:203], v[114:117]
	v_mfma_f32_16x16x32_bf16 v[106:109], v[168:171], v[200:203], v[106:109]
	v_mfma_f32_16x16x32_bf16 v[98:101], v[160:163], v[208:211], v[98:101]
	v_mfma_f32_16x16x32_bf16 v[90:93], v[168:171], v[208:211], v[90:93]
	v_mfma_f32_16x16x32_bf16 v[82:85], v[160:163], v[218:221], v[82:85]
	v_mfma_f32_16x16x32_bf16 v[74:77], v[168:171], v[218:221], v[74:77]
	v_mfma_f32_16x16x32_bf16 v[126:129], v[164:167], v[196:199], v[126:129]
	v_mfma_f32_16x16x32_bf16 v[122:125], v[172:175], v[196:199], v[122:125]
	v_mfma_f32_16x16x32_bf16 v[114:117], v[164:167], v[204:207], v[114:117]
	v_mfma_f32_16x16x32_bf16 v[106:109], v[172:175], v[204:207], v[106:109]
	v_mfma_f32_16x16x32_bf16 v[98:101], v[164:167], v[212:215], v[98:101]
	v_mfma_f32_16x16x32_bf16 v[90:93], v[172:175], v[212:215], v[90:93]
	v_mfma_f32_16x16x32_bf16 v[82:85], v[164:167], v[222:225], v[82:85]
	v_mfma_f32_16x16x32_bf16 v[74:77], v[172:175], v[222:225], v[74:77]
	s_setprio 0
	s_setprio 1
	v_mfma_f32_16x16x32_bf16 v[118:121], v[176:179], v[192:195], v[118:121]
	v_mfma_f32_16x16x32_bf16 v[110:113], v[184:187], v[192:195], v[110:113]
	v_mfma_f32_16x16x32_bf16 v[102:105], v[176:179], v[200:203], v[102:105]
	v_mfma_f32_16x16x32_bf16 v[94:97], v[184:187], v[200:203], v[94:97]
	v_mfma_f32_16x16x32_bf16 v[86:89], v[176:179], v[208:211], v[86:89]
	v_mfma_f32_16x16x32_bf16 v[78:81], v[184:187], v[208:211], v[78:81]
	v_mfma_f32_16x16x32_bf16 v[70:73], v[176:179], v[218:221], v[70:73]
	v_mfma_f32_16x16x32_bf16 v[66:69], v[184:187], v[218:221], v[66:69]
	v_mfma_f32_16x16x32_bf16 v[118:121], v[180:183], v[196:199], v[118:121]
	v_mfma_f32_16x16x32_bf16 v[110:113], v[188:191], v[196:199], v[110:113]
	v_mfma_f32_16x16x32_bf16 v[102:105], v[180:183], v[204:207], v[102:105]
	v_mfma_f32_16x16x32_bf16 v[94:97], v[188:191], v[204:207], v[94:97]
	v_mfma_f32_16x16x32_bf16 v[86:89], v[180:183], v[212:215], v[86:89]
	v_mfma_f32_16x16x32_bf16 v[78:81], v[188:191], v[212:215], v[78:81]
	v_mfma_f32_16x16x32_bf16 v[70:73], v[180:183], v[222:225], v[70:73]
	v_mfma_f32_16x16x32_bf16 v[66:69], v[188:191], v[222:225], v[66:69]
	s_setprio 0
	s_barrier
; #define PG8_STAGE(bufoff, gbase, voff) do { _Pragma("unroll") for (int _i = 0; _i < 2; ++_i) \
;         __builtin_amdgcn_global_load_lds((const unsigned*)((const char*)(gbase) + (voff)[_i]), (PG8_LAS unsigned*)(lds + (bufoff) + ldsw + _i * 8192), 16, 0, 0); } while (0)
; #define PG8_LDA(dst, b, h) do { _Pragma("unroll") for (int m = 0; m < 4; ++m) _Pragma("unroll") for (int k = 0; k < 2; ++k) dst[m][k] = *(const PG8_LAS bf16x8*)(lds + PG8_SA(b, h) + aoff + m * 2048 + k * 1024); } while (0)
; #define PG8_MMA(ai, bj, At, Bt) do { __builtin_amdgcn_s_setprio(1); _Pragma("unroll") for (int m = 0; m < 4; ++m) _Pragma("unroll") for (int n = 0; n < 2; ++n) _Pragma("unroll") for (int k = 0; k < 2; ++k) \
;         acc[ai][bj][m][n] = __builtin_amdgcn_mfma_f32_16x16x32_bf16(Bt[n][k], At[m][k], acc[ai][bj][m][n], 0, 0, 0); __builtin_amdgcn_s_setprio(0); } while (0)
; #define PG8_WAIT_V(n) asm volatile("s_waitcnt vmcnt(" #n ")" ::: "memory")
; #define PG8_WAIT_L(n) asm volatile("s_waitcnt lgkmcnt(" #n ")" ::: "memory")
; #define PG8_BAR __builtin_amdgcn_s_barrier()
; #define PG8_SCHED __builtin_amdgcn_sched_barrier(0)
; template <class Epi, class Sched, bool ALIGN_EPI = false, bool SP2 = false>
; __device__ __forceinline__ void gemm_phase(PG8_LAS unsigned char* lds, const Gemm g, const Sched& S, const Epi& E) {
;     ...
;             PG8_WAIT_V(8); PG8_WAIT_L(0); PG8_BAR; PG8_MMA(0, 0, At, B0); PG8_MMA(0, 1, At, B1); PG8_BAR; PG8_SCHED;
;             PG8_LDA(At, 1, 1); PG8_STAGE(PG8_SB(1, 0), b3, voffB); PG8_STAGE(PG8_SB(1, 1), b3 + hstepB, voffB); PG8_STAGE(PG8_SA(1, 0), a3, voffA);
;             PG8_WAIT_V(8); PG8_WAIT_L(0); PG8_BAR; PG8_MMA(1, 0, At, B0); PG8_MMA(1, 1, At, B1); PG8_BAR; PG8_SCHED;
;     ...
;         }
;         if constexpr (ALIGN_EPI) { if (wr == 0) PG8_BAR; }
	s_add_i32 s36, s62, s42
	v_lshl_add_u64 v[146:147], v[146:147], 0, s[10:11]
	s_mov_b32 m0, s36
	ds_read_b128 v[192:195], v158 offset:49152
	ds_read_b128 v[196:199], v158 offset:50176
	ds_read_b128 v[200:203], v158 offset:51200
	ds_read_b128 v[204:207], v158 offset:52224
	ds_read_b128 v[208:211], v158 offset:53248
	ds_read_b128 v[212:215], v158 offset:54272
	ds_read_b128 v[218:221], v158 offset:55296
	ds_read_b128 v[222:225], v158 offset:56320
	global_load_lds_dwordx4 v[146:147], off
	s_add_i32 m0, s36, 0x2000
	s_add_u32 s34, s34, 0x100080
	v_lshl_add_u64 v[146:147], v[226:227], 0, s[10:11]
	s_addc_u32 s35, s35, 0
	s_add_i32 s36, s63, s42
	global_load_lds_dwordx4 v[146:147], off
	v_lshl_add_u64 v[146:147], s[34:35], 0, v[132:133]
	s_mov_b32 m0, s36
	s_nop 0
	global_load_lds_dwordx4 v[146:147], off
	v_lshl_add_u64 v[146:147], s[34:35], 0, v[136:137]
	s_add_i32 m0, s36, 0x2000
	s_nop 0
	global_load_lds_dwordx4 v[146:147], off
	v_lshl_add_u64 v[146:147], v[228:229], 0, s[10:11]
	s_mov_b32 m0, s47
	s_nop 0
	global_load_lds_dwordx4 v[146:147], off
	s_waitcnt vmcnt(7)
	s_waitcnt lgkmcnt(0)
	s_barrier
	s_setprio 1
	s_waitcnt lgkmcnt(0)
	v_mfma_f32_16x16x32_bf16 v[62:65], v[160:163], v[192:195], v[62:65]
	v_mfma_f32_16x16x32_bf16 v[58:61], v[168:171], v[192:195], v[58:61]
	v_mfma_f32_16x16x32_bf16 v[50:53], v[160:163], v[200:203], v[50:53]
	v_mfma_f32_16x16x32_bf16 v[42:45], v[168:171], v[200:203], v[42:45]
	v_mfma_f32_16x16x32_bf16 v[34:37], v[160:163], v[208:211], v[34:37]
	v_mfma_f32_16x16x32_bf16 v[26:29], v[168:171], v[208:211], v[26:29]
	v_mfma_f32_16x16x32_bf16 v[18:21], v[160:163], v[218:221], v[18:21]
	v_mfma_f32_16x16x32_bf16 v[10:13], v[168:171], v[218:221], v[10:13]
	v_mfma_f32_16x16x32_bf16 v[62:65], v[164:167], v[196:199], v[62:65]
	v_mfma_f32_16x16x32_bf16 v[58:61], v[172:175], v[196:199], v[58:61]
	v_mfma_f32_16x16x32_bf16 v[50:53], v[164:167], v[204:207], v[50:53]
	v_mfma_f32_16x16x32_bf16 v[42:45], v[172:175], v[204:207], v[42:45]
	v_mfma_f32_16x16x32_bf16 v[34:37], v[164:167], v[212:215], v[34:37]
	v_mfma_f32_16x16x32_bf16 v[26:29], v[172:175], v[212:215], v[26:29]
	v_mfma_f32_16x16x32_bf16 v[18:21], v[164:167], v[222:225], v[18:21]
	v_mfma_f32_16x16x32_bf16 v[10:13], v[172:175], v[222:225], v[10:13]
	s_setprio 0
	s_setprio 1
	v_mfma_f32_16x16x32_bf16 v[54:57], v[176:179], v[192:195], v[54:57]
	v_mfma_f32_16x16x32_bf16 v[46:49], v[184:187], v[192:195], v[46:49]
	v_mfma_f32_16x16x32_bf16 v[38:41], v[176:179], v[200:203], v[38:41]
	v_mfma_f32_16x16x32_bf16 v[30:33], v[184:187], v[200:203], v[30:33]
	v_mfma_f32_16x16x32_bf16 v[22:25], v[176:179], v[208:211], v[22:25]
	v_mfma_f32_16x16x32_bf16 v[14:17], v[184:187], v[208:211], v[14:17]
	v_mfma_f32_16x16x32_bf16 v[6:9], v[176:179], v[218:221], v[6:9]
	v_mfma_f32_16x16x32_bf16 v[2:5], v[184:187], v[218:221], v[2:5]
	v_mfma_f32_16x16x32_bf16 v[54:57], v[180:183], v[196:199], v[54:57]
	v_mfma_f32_16x16x32_bf16 v[46:49], v[188:191], v[196:199], v[46:49]
	v_mfma_f32_16x16x32_bf16 v[38:41], v[180:183], v[204:207], v[38:41]
	v_mfma_f32_16x16x32_bf16 v[30:33], v[188:191], v[204:207], v[30:33]
	v_mfma_f32_16x16x32_bf16 v[22:25], v[180:183], v[212:215], v[22:25]
	v_mfma_f32_16x16x32_bf16 v[14:17], v[188:191], v[212:215], v[14:17]
	v_mfma_f32_16x16x32_bf16 v[6:9], v[180:183], v[222:225], v[6:9]
	v_mfma_f32_16x16x32_bf16 v[2:5], v[188:191], v[222:225], v[2:5]
	s_setprio 0
	s_barrier
	v_lshl_add_u64 v[146:147], v[230:231], 0, s[10:11]
	s_mov_b32 m0, s48
	s_nop 0
	global_load_lds_dwordx4 v[146:147], off
	s_add_i32 s61, s61, 2
	s_add_u32 s30, s30, 0x100
	s_addc_u32 s31, s31, 0
	s_add_u32 s59, s59, 0x100
	s_addc_u32 s60, s60, 0
	s_cmp_gt_u32 s61, 61
	s_cbranch_scc0 .LBB0_1868
	s_and_b64 vcc, exec, s[12:13]
	s_cbranch_vccz .LBB0_1871
	s_barrier

; #define PG8_STAGE(bufoff, gbase, voff) do { _Pragma("unroll") for (int _i = 0; _i < 2; ++_i) \
;         __builtin_amdgcn_global_load_lds((const unsigned*)((const char*)(gbase) + (voff)[_i]), (PG8_LAS unsigned*)(lds + (bufoff) + ldsw + _i * 8192), 16, 0, 0); } while (0)
; #define PG8_LDA(dst, b, h) do { _Pragma("unroll") for (int m = 0; m < 4; ++m) _Pragma("unroll") for (int k = 0; k < 2; ++k) dst[m][k] = *(const PG8_LAS bf16x8*)(lds + PG8_SA(b, h) + aoff + m * 2048 + k * 1024); } while (0)
; #define PG8_LDB(dst, b, h) do { _Pragma("unroll") for (int n = 0; n < 2; ++n) _Pragma("unroll") for (int k = 0; k < 2; ++k) dst[n][k] = *(const PG8_LAS bf16x8*)(lds + PG8_SB(b, h) + boff + n * 2048 + k * 1024); } while (0)
; #define PG8_MMA(ai, bj, At, Bt) do { __builtin_amdgcn_s_setprio(1); _Pragma("unroll") for (int m = 0; m < 4; ++m) _Pragma("unroll") for (int n = 0; n < 2; ++n) _Pragma("unroll") for (int k = 0; k < 2; ++k) \
;         acc[ai][bj][m][n] = __builtin_amdgcn_mfma_f32_16x16x32_bf16(Bt[n][k], At[m][k], acc[ai][bj][m][n], 0, 0, 0); __builtin_amdgcn_s_setprio(0); } while (0)
; #define PG8_WAIT_V(n) asm volatile("s_waitcnt vmcnt(" #n ")" ::: "memory")
; #define PG8_BAR __builtin_amdgcn_s_barrier()
; template <class Epi, class Sched, bool ALIGN_EPI = false, bool SP2 = false>
; __device__ __forceinline__ void gemm_phase(PG8_LAS unsigned char* lds, const Gemm g, const Sched& S, const Epi& E) {
;     ...
;         for (int t = 0; t < nt; t += 2) {
;             const bool last = (t == nt - 2);
;             const char* a1 = cA + (size_t)(t + 1) * kstep;
;             const char* a2 = last ? nA : cA + (size_t)(t + 2) * kstep; const char* b2 = last ? nB : cB + (size_t)(t + 2) * kstep;
;             const char* a3 = a2 + kstep; const char* b3 = b2 + kstep;
;             if (last && has_next) S.a_ready(nxt);
;             if constexpr (SP2) {
;             PG8_LDB(B0, 0, 0); PG8_LDB(B1, 0, 1); PG8_SCHED; PG8_LDA(At, 0, 0); PG8_STAGE(PG8_SA(1, 1), a1 + hstepA, voffA);
;             PG8_WAIT_V(8); PG8_WAIT_L(0); PG8_BAR; PG8_MMA(0, 0, At, B0); PG8_MMA(0, 1, At, B1); PG8_BAR; PG8_SCHED;
;             PG8_LDA(At, 0, 1); PG8_STAGE(PG8_SB(0, 0), b2, voffB); PG8_STAGE(PG8_SB(0, 1), b2 + hstepB, voffB); PG8_STAGE(PG8_SA(0, 0), a2, voffA);
;             PG8_WAIT_V(8); PG8_WAIT_L(0); PG8_BAR; PG8_MMA(1, 0, At, B0); PG8_MMA(1, 1, At, B1); PG8_BAR; PG8_SCHED;
.LBB0_1880:
	ds_read_b128 v[148:151], v143
	ds_read_b128 v[152:155], v143 offset:1024
	ds_read_b128 v[156:159], v143 offset:2048
	ds_read_b128 v[160:163], v143 offset:3072
	ds_read_b128 v[164:167], v144
	ds_read_b128 v[168:171], v144 offset:1024
	ds_read_b128 v[172:175], v144 offset:2048
	ds_read_b128 v[176:179], v144 offset:3072
	s_add_u32 s16, s12, s14
	s_addc_u32 s17, s13, s15
	s_add_u32 s16, s16, 0x34000100
	s_addc_u32 s17, s17, 0
	s_add_u32 s42, s28, s14
	s_addc_u32 s43, s29, s15
	s_cmpk_eq_i32 s14, 0x1f00
	s_cselect_b32 s19, s9, s17
	s_cselect_b32 s18, s8, s16
	s_cselect_b32 s17, s7, s43
	s_cselect_b32 s16, s6, s42
	s_mov_b32 m0, s31
	v_lshl_add_u64 v[212:213], v[138:139], 0, s[14:15]
	ds_read_b128 v[180:183], v145
	ds_read_b128 v[184:187], v145 offset:1024
	ds_read_b128 v[188:191], v145 offset:2048
	ds_read_b128 v[192:195], v145 offset:3072
	ds_read_b128 v[196:199], v145 offset:4096
	ds_read_b128 v[200:203], v145 offset:5120
	ds_read_b128 v[204:207], v145 offset:6144
	ds_read_b128 v[208:211], v145 offset:7168
	global_load_lds_dwordx4 v[212:213], off
	v_lshl_add_u64 v[212:213], v[140:141], 0, s[14:15]
	s_mov_b32 m0, s33
	s_nop 0
	global_load_lds_dwordx4 v[212:213], off
	s_waitcnt vmcnt(8)
	s_waitcnt lgkmcnt(0)
	s_barrier
	s_setprio 1
	s_waitcnt lgkmcnt(0)
	v_mfma_f32_16x16x32_bf16 v[126:129], v[148:151], v[180:183], v[126:129]
	v_mfma_f32_16x16x32_bf16 v[122:125], v[156:159], v[180:183], v[122:125]
	v_mfma_f32_16x16x32_bf16 v[114:117], v[148:151], v[188:191], v[114:117]
	v_mfma_f32_16x16x32_bf16 v[106:109], v[156:159], v[188:191], v[106:109]
	v_mfma_f32_16x16x32_bf16 v[98:101], v[148:151], v[196:199], v[98:101]
	v_mfma_f32_16x16x32_bf16 v[90:93], v[156:159], v[196:199], v[90:93]
	v_mfma_f32_16x16x32_bf16 v[82:85], v[148:151], v[204:207], v[82:85]
	v_mfma_f32_16x16x32_bf16 v[74:77], v[156:159], v[204:207], v[74:77]
	v_mfma_f32_16x16x32_bf16 v[126:129], v[152:155], v[184:187], v[126:129]
	v_mfma_f32_16x16x32_bf16 v[122:125], v[160:163], v[184:187], v[122:125]
	v_mfma_f32_16x16x32_bf16 v[114:117], v[152:155], v[192:195], v[114:117]
	v_mfma_f32_16x16x32_bf16 v[106:109], v[160:163], v[192:195], v[106:109]
	v_mfma_f32_16x16x32_bf16 v[98:101], v[152:155], v[200:203], v[98:101]
	v_mfma_f32_16x16x32_bf16 v[90:93], v[160:163], v[200:203], v[90:93]
	v_mfma_f32_16x16x32_bf16 v[82:85], v[152:155], v[208:211], v[82:85]
	v_mfma_f32_16x16x32_bf16 v[74:77], v[160:163], v[208:211], v[74:77]
	s_setprio 0
	s_setprio 1
	v_mfma_f32_16x16x32_bf16 v[118:121], v[164:167], v[180:183], v[118:121]
	v_mfma_f32_16x16x32_bf16 v[110:113], v[172:175], v[180:183], v[110:113]
	v_mfma_f32_16x16x32_bf16 v[102:105], v[164:167], v[188:191], v[102:105]
	v_mfma_f32_16x16x32_bf16 v[94:97], v[172:175], v[188:191], v[94:97]
	v_mfma_f32_16x16x32_bf16 v[86:89], v[164:167], v[196:199], v[86:89]
	v_mfma_f32_16x16x32_bf16 v[78:81], v[172:175], v[196:199], v[78:81]
	v_mfma_f32_16x16x32_bf16 v[70:73], v[164:167], v[204:207], v[70:73]
	v_mfma_f32_16x16x32_bf16 v[66:69], v[172:175], v[204:207], v[66:69]
	v_mfma_f32_16x16x32_bf16 v[118:121], v[168:171], v[184:187], v[118:121]
	v_mfma_f32_16x16x32_bf16 v[110:113], v[176:179], v[184:187], v[110:113]
	v_mfma_f32_16x16x32_bf16 v[102:105], v[168:171], v[192:195], v[102:105]
	v_mfma_f32_16x16x32_bf16 v[94:97], v[176:179], v[192:195], v[94:97]
	v_mfma_f32_16x16x32_bf16 v[86:89], v[168:171], v[200:203], v[86:89]
	v_mfma_f32_16x16x32_bf16 v[78:81], v[176:179], v[200:203], v[78:81]
	v_mfma_f32_16x16x32_bf16 v[70:73], v[168:171], v[208:211], v[70:73]
	v_mfma_f32_16x16x32_bf16 v[66:69], v[176:179], v[208:211], v[66:69]
	s_setprio 0
	s_barrier
	s_mov_b32 m0, s34
	v_lshl_add_u64 v[212:213], s[16:17], 0, v[132:133]
	s_add_u32 s42, s16, 0x100000
	ds_read_b128 v[180:183], v145 offset:16384
	ds_read_b128 v[184:187], v145 offset:17408
	ds_read_b128 v[188:191], v145 offset:18432
	ds_read_b128 v[192:195], v145 offset:19456
	ds_read_b128 v[196:199], v145 offset:20480
	ds_read_b128 v[200:203], v145 offset:21504
	ds_read_b128 v[204:207], v145 offset:22528
	ds_read_b128 v[208:211], v145 offset:23552
	global_load_lds_dwordx4 v[212:213], off
	v_lshl_add_u64 v[214:215], s[16:17], 0, v[136:137]
	s_mov_b32 m0, s35
	s_addc_u32 s43, s17, 0
	global_load_lds_dwordx4 v[214:215], off
	v_lshl_add_u64 v[218:219], s[42:43], 0, v[132:133]
	s_mov_b32 m0, s36
	v_lshl_add_u64 v[220:221], s[18:19], 0, v[134:135]
	global_load_lds_dwordx4 v[218:219], off
	v_lshl_add_u64 v[218:219], s[42:43], 0, v[136:137]
	s_mov_b32 m0, s37
	s_nop 0
	global_load_lds_dwordx4 v[218:219], off
	v_lshl_add_u64 v[218:219], s[18:19], 0, v[130:131]
	s_mov_b32 m0, s3
	s_nop 0
	global_load_lds_dwordx4 v[218:219], off
	s_waitcnt vmcnt(7)
	s_waitcnt lgkmcnt(0)
	s_barrier
; #define PG8_STAGE(bufoff, gbase, voff) do { _Pragma("unroll") for (int _i = 0; _i < 2; ++_i) \
;         __builtin_amdgcn_global_load_lds((const unsigned*)((const char*)(gbase) + (voff)[_i]), (PG8_LAS unsigned*)(lds + (bufoff) + ldsw + _i * 8192), 16, 0, 0); } while (0)
; #define PG8_LDA(dst, b, h) do { _Pragma("unroll") for (int m = 0; m < 4; ++m) _Pragma("unroll") for (int k = 0; k < 2; ++k) dst[m][k] = *(const PG8_LAS bf16x8*)(lds + PG8_SA(b, h) + aoff + m * 2048 + k * 1024); } while (0)
; #define PG8_LDB(dst, b, h) do { _Pragma("unroll") for (int n = 0; n < 2; ++n) _Pragma("unroll") for (int k = 0; k < 2; ++k) dst[n][k] = *(const PG8_LAS bf16x8*)(lds + PG8_SB(b, h) + boff + n * 2048 + k * 1024); } while (0)
; #define PG8_MMA(ai, bj, At, Bt) do { __builtin_amdgcn_s_setprio(1); _Pragma("unroll") for (int m = 0; m < 4; ++m) _Pragma("unroll") for (int n = 0; n < 2; ++n) _Pragma("unroll") for (int k = 0; k < 2; ++k) \
;         acc[ai][bj][m][n] = __builtin_amdgcn_mfma_f32_16x16x32_bf16(Bt[n][k], At[m][k], acc[ai][bj][m][n], 0, 0, 0); __builtin_amdgcn_s_setprio(0); } while (0)
; #define PG8_WAIT_V(n) asm volatile("s_waitcnt vmcnt(" #n ")" ::: "memory")
; #define PG8_WAIT_L(n) asm volatile("s_waitcnt lgkmcnt(" #n ")" ::: "memory")
; #define PG8_BAR __builtin_amdgcn_s_barrier()
; #define PG8_SCHED __builtin_amdgcn_sched_barrier(0)
; template <class Epi, class Sched, bool ALIGN_EPI = false, bool SP2 = false>
; __device__ __forceinline__ void gemm_phase(PG8_LAS unsigned char* lds, const Gemm g, const Sched& S, const Epi& E) {
;     ...
;             PG8_WAIT_V(8); PG8_WAIT_L(0); PG8_BAR; PG8_MMA(0, 0, At, B0); PG8_MMA(0, 1, At, B1); PG8_BAR; PG8_SCHED;
;             PG8_LDA(At, 0, 1); PG8_STAGE(PG8_SB(0, 0), b2, voffB); PG8_STAGE(PG8_SB(0, 1), b2 + hstepB, voffB); PG8_STAGE(PG8_SA(0, 0), a2, voffA);
;             PG8_WAIT_V(8); PG8_WAIT_L(0); PG8_BAR; PG8_MMA(1, 0, At, B0); PG8_MMA(1, 1, At, B1); PG8_BAR; PG8_SCHED;
;             PG8_LDB(B0, 1, 0); PG8_LDB(B1, 1, 1); PG8_SCHED; PG8_LDA(At, 1, 0); PG8_STAGE(PG8_SA(0, 1), a2 + hstepA, voffA);
;             PG8_WAIT_V(8); PG8_WAIT_L(0); PG8_BAR; PG8_MMA(0, 0, At, B0); PG8_MMA(0, 1, At, B1); PG8_BAR; PG8_SCHED;
	s_setprio 1
	s_waitcnt lgkmcnt(0)
	v_mfma_f32_16x16x32_bf16 v[62:65], v[148:151], v[180:183], v[62:65]
	v_mfma_f32_16x16x32_bf16 v[58:61], v[156:159], v[180:183], v[58:61]
	v_mfma_f32_16x16x32_bf16 v[50:53], v[148:151], v[188:191], v[50:53]
	v_mfma_f32_16x16x32_bf16 v[42:45], v[156:159], v[188:191], v[42:45]
	v_mfma_f32_16x16x32_bf16 v[34:37], v[148:151], v[196:199], v[34:37]
	v_mfma_f32_16x16x32_bf16 v[26:29], v[156:159], v[196:199], v[26:29]
	v_mfma_f32_16x16x32_bf16 v[18:21], v[148:151], v[204:207], v[18:21]
	v_mfma_f32_16x16x32_bf16 v[10:13], v[156:159], v[204:207], v[10:13]
	v_mfma_f32_16x16x32_bf16 v[62:65], v[152:155], v[184:187], v[62:65]
	v_mfma_f32_16x16x32_bf16 v[58:61], v[160:163], v[184:187], v[58:61]
	v_mfma_f32_16x16x32_bf16 v[50:53], v[152:155], v[192:195], v[50:53]
	v_mfma_f32_16x16x32_bf16 v[42:45], v[160:163], v[192:195], v[42:45]
	v_mfma_f32_16x16x32_bf16 v[34:37], v[152:155], v[200:203], v[34:37]
	v_mfma_f32_16x16x32_bf16 v[26:29], v[160:163], v[200:203], v[26:29]
	v_mfma_f32_16x16x32_bf16 v[18:21], v[152:155], v[208:211], v[18:21]
	v_mfma_f32_16x16x32_bf16 v[10:13], v[160:163], v[208:211], v[10:13]
	s_setprio 0
	s_setprio 1
	v_mfma_f32_16x16x32_bf16 v[54:57], v[164:167], v[180:183], v[54:57]
	v_mfma_f32_16x16x32_bf16 v[46:49], v[172:175], v[180:183], v[46:49]
	v_mfma_f32_16x16x32_bf16 v[38:41], v[164:167], v[188:191], v[38:41]
	v_mfma_f32_16x16x32_bf16 v[30:33], v[172:175], v[188:191], v[30:33]
	v_mfma_f32_16x16x32_bf16 v[22:25], v[164:167], v[196:199], v[22:25]
	v_mfma_f32_16x16x32_bf16 v[14:17], v[172:175], v[196:199], v[14:17]
	v_mfma_f32_16x16x32_bf16 v[6:9], v[164:167], v[204:207], v[6:9]
	v_mfma_f32_16x16x32_bf16 v[2:5], v[172:175], v[204:207], v[2:5]
	v_mfma_f32_16x16x32_bf16 v[54:57], v[168:171], v[184:187], v[54:57]
	v_mfma_f32_16x16x32_bf16 v[46:49], v[176:179], v[184:187], v[46:49]
	v_mfma_f32_16x16x32_bf16 v[38:41], v[168:171], v[192:195], v[38:41]
	v_mfma_f32_16x16x32_bf16 v[30:33], v[176:179], v[192:195], v[30:33]
	v_mfma_f32_16x16x32_bf16 v[22:25], v[168:171], v[200:203], v[22:25]
	v_mfma_f32_16x16x32_bf16 v[14:17], v[176:179], v[200:203], v[14:17]
	v_mfma_f32_16x16x32_bf16 v[6:9], v[168:171], v[208:211], v[6:9]
	v_mfma_f32_16x16x32_bf16 v[2:5], v[176:179], v[208:211], v[2:5]
	s_setprio 0
	s_barrier
	s_mov_b32 m0, s22
	s_nop 0
	global_load_lds_dwordx4 v[220:221], off
	ds_read_b128 v[148:151], v146
	ds_read_b128 v[152:155], v146 offset:1024
	ds_read_b128 v[156:159], v146 offset:2048
	ds_read_b128 v[160:163], v146 offset:3072
	ds_read_b128 v[164:167], v147
	ds_read_b128 v[168:171], v147 offset:1024
	ds_read_b128 v[172:175], v147 offset:2048
	ds_read_b128 v[176:179], v147 offset:3072
	s_add_u32 s18, s18, 0x100000
	s_addc_u32 s19, s19, 0
	s_mov_b32 m0, s23
	v_lshl_add_u64 v[222:223], s[18:19], 0, v[130:131]
	ds_read_b128 v[180:183], v145 offset:32768
	ds_read_b128 v[184:187], v145 offset:33792
	ds_read_b128 v[188:191], v145 offset:34816
	ds_read_b128 v[192:195], v145 offset:35840
	ds_read_b128 v[196:199], v145 offset:36864
	ds_read_b128 v[200:203], v145 offset:37888
	ds_read_b128 v[204:207], v145 offset:38912
	ds_read_b128 v[208:211], v145 offset:39936
	global_load_lds_dwordx4 v[222:223], off
	v_lshl_add_u64 v[222:223], s[18:19], 0, v[134:135]
	s_mov_b32 m0, s24
	s_nop 0
	global_load_lds_dwordx4 v[222:223], off
	s_waitcnt vmcnt(8)
	s_waitcnt lgkmcnt(0)
	s_barrier
	s_setprio 1
	s_waitcnt lgkmcnt(0)
	v_mfma_f32_16x16x32_bf16 v[126:129], v[148:151], v[180:183], v[126:129]
	v_mfma_f32_16x16x32_bf16 v[122:125], v[156:159], v[180:183], v[122:125]
	v_mfma_f32_16x16x32_bf16 v[114:117], v[148:151], v[188:191], v[114:117]
	v_mfma_f32_16x16x32_bf16 v[106:109], v[156:159], v[188:191], v[106:109]
	v_mfma_f32_16x16x32_bf16 v[98:101], v[148:151], v[196:199], v[98:101]
	v_mfma_f32_16x16x32_bf16 v[90:93], v[156:159], v[196:199], v[90:93]
	v_mfma_f32_16x16x32_bf16 v[82:85], v[148:151], v[204:207], v[82:85]
	v_mfma_f32_16x16x32_bf16 v[74:77], v[156:159], v[204:207], v[74:77]
	v_mfma_f32_16x16x32_bf16 v[126:129], v[152:155], v[184:187], v[126:129]
	v_mfma_f32_16x16x32_bf16 v[122:125], v[160:163], v[184:187], v[122:125]
	v_mfma_f32_16x16x32_bf16 v[114:117], v[152:155], v[192:195], v[114:117]
	v_mfma_f32_16x16x32_bf16 v[106:109], v[160:163], v[192:195], v[106:109]
	v_mfma_f32_16x16x32_bf16 v[98:101], v[152:155], v[200:203], v[98:101]
	v_mfma_f32_16x16x32_bf16 v[90:93], v[160:163], v[200:203], v[90:93]
	v_mfma_f32_16x16x32_bf16 v[82:85], v[152:155], v[208:211], v[82:85]
	v_mfma_f32_16x16x32_bf16 v[74:77], v[160:163], v[208:211], v[74:77]
	s_setprio 0
	s_setprio 1
	v_mfma_f32_16x16x32_bf16 v[118:121], v[164:167], v[180:183], v[118:121]
	v_mfma_f32_16x16x32_bf16 v[110:113], v[172:175], v[180:183], v[110:113]
	v_mfma_f32_16x16x32_bf16 v[102:105], v[164:167], v[188:191], v[102:105]
	v_mfma_f32_16x16x32_bf16 v[94:97], v[172:175], v[188:191], v[94:97]
	v_mfma_f32_16x16x32_bf16 v[86:89], v[164:167], v[196:199], v[86:89]
	v_mfma_f32_16x16x32_bf16 v[78:81], v[172:175], v[196:199], v[78:81]
	v_mfma_f32_16x16x32_bf16 v[70:73], v[164:167], v[204:207], v[70:73]
	v_mfma_f32_16x16x32_bf16 v[66:69], v[172:175], v[204:207], v[66:69]
	v_mfma_f32_16x16x32_bf16 v[118:121], v[168:171], v[184:187], v[118:121]
	v_mfma_f32_16x16x32_bf16 v[110:113], v[176:179], v[184:187], v[110:113]
	v_mfma_f32_16x16x32_bf16 v[102:105], v[168:171], v[192:195], v[102:105]
	v_mfma_f32_16x16x32_bf16 v[94:97], v[176:179], v[192:195], v[94:97]
	v_mfma_f32_16x16x32_bf16 v[86:89], v[168:171], v[200:203], v[86:89]
	v_mfma_f32_16x16x32_bf16 v[78:81], v[176:179], v[200:203], v[78:81]
	v_mfma_f32_16x16x32_bf16 v[70:73], v[168:171], v[208:211], v[70:73]
	v_mfma_f32_16x16x32_bf16 v[66:69], v[176:179], v[208:211], v[66:69]
	s_setprio 0
	s_barrier
; #define PG8_STAGE(bufoff, gbase, voff) do { _Pragma("unroll") for (int _i = 0; _i < 2; ++_i) \
;         __builtin_amdgcn_global_load_lds((const unsigned*)((const char*)(gbase) + (voff)[_i]), (PG8_LAS unsigned*)(lds + (bufoff) + ldsw + _i * 8192), 16, 0, 0); } while (0)
; #define PG8_LDA(dst, b, h) do { _Pragma("unroll") for (int m = 0; m < 4; ++m) _Pragma("unroll") for (int k = 0; k < 2; ++k) dst[m][k] = *(const PG8_LAS bf16x8*)(lds + PG8_SA(b, h) + aoff + m * 2048 + k * 1024); } while (0)
; #define PG8_MMA(ai, bj, At, Bt) do { __builtin_amdgcn_s_setprio(1); _Pragma("unroll") for (int m = 0; m < 4; ++m) _Pragma("unroll") for (int n = 0; n < 2; ++n) _Pragma("unroll") for (int k = 0; k < 2; ++k) \
;         acc[ai][bj][m][n] = __builtin_amdgcn_mfma_f32_16x16x32_bf16(Bt[n][k], At[m][k], acc[ai][bj][m][n], 0, 0, 0); __builtin_amdgcn_s_setprio(0); } while (0)
; #define PG8_WAIT_V(n) asm volatile("s_waitcnt vmcnt(" #n ")" ::: "memory")
; #define PG8_WAIT_L(n) asm volatile("s_waitcnt lgkmcnt(" #n ")" ::: "memory")
; #define PG8_BAR __builtin_amdgcn_s_barrier()
; #define PG8_SCHED __builtin_amdgcn_sched_barrier(0)
; template <class Epi, class Sched, bool ALIGN_EPI = false, bool SP2 = false>
; __device__ __forceinline__ void gemm_phase(PG8_LAS unsigned char* lds, const Gemm g, const Sched& S, const Epi& E) {
;     ...
;             PG8_WAIT_V(8); PG8_WAIT_L(0); PG8_BAR; PG8_MMA(0, 0, At, B0); PG8_MMA(0, 1, At, B1); PG8_BAR; PG8_SCHED;
;             PG8_LDA(At, 1, 1); PG8_STAGE(PG8_SB(1, 0), b3, voffB); PG8_STAGE(PG8_SB(1, 1), b3 + hstepB, voffB); PG8_STAGE(PG8_SA(1, 0), a3, voffA);
;             PG8_WAIT_V(8); PG8_WAIT_L(0); PG8_BAR; PG8_MMA(1, 0, At, B0); PG8_MMA(1, 1, At, B1); PG8_BAR; PG8_SCHED;
;     ...
;         }
;         if constexpr (ALIGN_EPI) { if (wr == 0) PG8_BAR; }
	s_mov_b32 m0, s38
	v_lshl_add_u64 v[212:213], v[212:213], 0, s[10:11]
	s_add_u32 s16, s16, 0x100080
	ds_read_b128 v[180:183], v145 offset:49152
	ds_read_b128 v[184:187], v145 offset:50176
	ds_read_b128 v[188:191], v145 offset:51200
	ds_read_b128 v[192:195], v145 offset:52224
	ds_read_b128 v[196:199], v145 offset:53248
	ds_read_b128 v[200:203], v145 offset:54272
	ds_read_b128 v[204:207], v145 offset:55296
	ds_read_b128 v[208:211], v145 offset:56320
	global_load_lds_dwordx4 v[212:213], off
	v_lshl_add_u64 v[212:213], v[214:215], 0, s[10:11]
	s_mov_b32 m0, s39
	s_addc_u32 s17, s17, 0
	global_load_lds_dwordx4 v[212:213], off
	v_lshl_add_u64 v[212:213], s[16:17], 0, v[132:133]
	s_mov_b32 m0, s40
	s_nop 0
	global_load_lds_dwordx4 v[212:213], off
	v_lshl_add_u64 v[212:213], s[16:17], 0, v[136:137]
	s_mov_b32 m0, s41
	s_nop 0
	global_load_lds_dwordx4 v[212:213], off
	v_lshl_add_u64 v[212:213], v[218:219], 0, s[10:11]
	s_mov_b32 m0, s26
	s_nop 0
	global_load_lds_dwordx4 v[212:213], off
	s_waitcnt vmcnt(7)
	s_waitcnt lgkmcnt(0)
	s_barrier
	s_setprio 1
	s_waitcnt lgkmcnt(0)
	v_mfma_f32_16x16x32_bf16 v[62:65], v[148:151], v[180:183], v[62:65]
	v_mfma_f32_16x16x32_bf16 v[58:61], v[156:159], v[180:183], v[58:61]
	v_mfma_f32_16x16x32_bf16 v[50:53], v[148:151], v[188:191], v[50:53]
	v_mfma_f32_16x16x32_bf16 v[42:45], v[156:159], v[188:191], v[42:45]
	v_mfma_f32_16x16x32_bf16 v[34:37], v[148:151], v[196:199], v[34:37]
	v_mfma_f32_16x16x32_bf16 v[26:29], v[156:159], v[196:199], v[26:29]
	v_mfma_f32_16x16x32_bf16 v[18:21], v[148:151], v[204:207], v[18:21]
	v_mfma_f32_16x16x32_bf16 v[10:13], v[156:159], v[204:207], v[10:13]
	v_mfma_f32_16x16x32_bf16 v[62:65], v[152:155], v[184:187], v[62:65]
	v_mfma_f32_16x16x32_bf16 v[58:61], v[160:163], v[184:187], v[58:61]
	v_mfma_f32_16x16x32_bf16 v[50:53], v[152:155], v[192:195], v[50:53]
	v_mfma_f32_16x16x32_bf16 v[42:45], v[160:163], v[192:195], v[42:45]
	v_mfma_f32_16x16x32_bf16 v[34:37], v[152:155], v[200:203], v[34:37]
	v_mfma_f32_16x16x32_bf16 v[26:29], v[160:163], v[200:203], v[26:29]
	v_mfma_f32_16x16x32_bf16 v[18:21], v[152:155], v[208:211], v[18:21]
	v_mfma_f32_16x16x32_bf16 v[10:13], v[160:163], v[208:211], v[10:13]
	s_setprio 0
	s_setprio 1
	v_mfma_f32_16x16x32_bf16 v[54:57], v[164:167], v[180:183], v[54:57]
	v_mfma_f32_16x16x32_bf16 v[46:49], v[172:175], v[180:183], v[46:49]
	v_mfma_f32_16x16x32_bf16 v[38:41], v[164:167], v[188:191], v[38:41]
	v_mfma_f32_16x16x32_bf16 v[30:33], v[172:175], v[188:191], v[30:33]
	v_mfma_f32_16x16x32_bf16 v[22:25], v[164:167], v[196:199], v[22:25]
	v_mfma_f32_16x16x32_bf16 v[14:17], v[172:175], v[196:199], v[14:17]
	v_mfma_f32_16x16x32_bf16 v[6:9], v[164:167], v[204:207], v[6:9]
	v_mfma_f32_16x16x32_bf16 v[2:5], v[172:175], v[204:207], v[2:5]
	v_mfma_f32_16x16x32_bf16 v[54:57], v[168:171], v[184:187], v[54:57]
	v_mfma_f32_16x16x32_bf16 v[46:49], v[176:179], v[184:187], v[46:49]
	v_mfma_f32_16x16x32_bf16 v[38:41], v[168:171], v[192:195], v[38:41]
	v_mfma_f32_16x16x32_bf16 v[30:33], v[176:179], v[192:195], v[30:33]
	v_mfma_f32_16x16x32_bf16 v[22:25], v[168:171], v[200:203], v[22:25]
	v_mfma_f32_16x16x32_bf16 v[14:17], v[176:179], v[200:203], v[14:17]
	v_mfma_f32_16x16x32_bf16 v[6:9], v[168:171], v[208:211], v[6:9]
	v_mfma_f32_16x16x32_bf16 v[2:5], v[176:179], v[208:211], v[2:5]
	s_setprio 0
	s_barrier
	v_lshl_add_u64 v[212:213], v[220:221], 0, s[10:11]
	s_mov_b32 m0, s27
	s_nop 0
	global_load_lds_dwordx4 v[212:213], off
	s_add_i32 s30, s30, 2
	s_add_u32 s14, s14, 0x100
	s_addc_u32 s15, s15, 0
	s_cmp_gt_u32 s30, 61
	s_cbranch_scc0 .LBB0_1880
	s_cmpk_lt_u32 s20, 0x100
	s_cbranch_scc0 .LBB0_1883
	s_barrier
